# GEMM K-loops: back-to-back s_setprio 0 / s_setprio 1 flips between the two MFMA clusters of a compute segment removed (on top of v020)
# baseline (speedup 1.0000x reference)
; #define PG8_STAGE(bufoff, gbase, voff) do { _Pragma("unroll") for (int _i = 0; _i < 2; ++_i) \
;         __builtin_amdgcn_global_load_lds((const unsigned*)((const char*)(gbase) + (voff)[_i]), (PG8_LAS unsigned*)(lds + (bufoff) + ldsw + _i * 8192), 16, 0, 0); } while (0)
; #define PG8_LDA(dst, b, h) do { _Pragma("unroll") for (int m = 0; m < 4; ++m) _Pragma("unroll") for (int k = 0; k < 2; ++k) dst[m][k] = *(const PG8_LAS bf16x8*)(lds + PG8_SA(b, h) + aoff + m * 2048 + k * 1024); } while (0)
; #define PG8_LDB(dst, b, h) do { _Pragma("unroll") for (int n = 0; n < 2; ++n) _Pragma("unroll") for (int k = 0; k < 2; ++k) dst[n][k] = *(const PG8_LAS bf16x8*)(lds + PG8_SB(b, h) + boff + n * 2048 + k * 1024); } while (0)
; #define PG8_MMA(ai, bj, At, Bt) do { __builtin_amdgcn_s_setprio(1); _Pragma("unroll") for (int m = 0; m < 4; ++m) _Pragma("unroll") for (int n = 0; n < 2; ++n) _Pragma("unroll") for (int k = 0; k < 2; ++k) \
;         acc[ai][bj][m][n] = __builtin_amdgcn_mfma_f32_16x16x32_bf16(Bt[n][k], At[m][k], acc[ai][bj][m][n], 0, 0, 0); __builtin_amdgcn_s_setprio(0); } while (0)
; #define PG8_WAIT_V(n) asm volatile("s_waitcnt vmcnt(" #n ")" ::: "memory")
; #define PG8_WAIT_L(n) asm volatile("s_waitcnt lgkmcnt(" #n ")" ::: "memory")
; #define PG8_BAR __builtin_amdgcn_s_barrier()
; #define PG8_SCHED __builtin_amdgcn_sched_barrier(0)
; template <class Epi, class Sched, bool ALIGN_EPI = false, bool SP2 = false>
; __device__ __forceinline__ void gemm_phase(PG8_LAS unsigned char* lds, const Gemm g, const Sched& S, const Epi& E) {
;     ...
;             PG8_LDB(B0, 0, 0); PG8_LDB(B1, 0, 1); PG8_SCHED; PG8_LDA(At, 0, 0); PG8_STAGE(PG8_SA(1, 1), a1 + hstep, voffA);
;             PG8_WAIT_V(8); PG8_WAIT_L(0); PG8_BAR; PG8_MMA(0, 0, At, B0); PG8_MMA(0, 1, At, B1); PG8_BAR; PG8_SCHED;
;             PG8_LDA(At, 0, 1); PG8_STAGE(PG8_SB(0, 0), b2, voffB); PG8_STAGE(PG8_SB(0, 1), b2 + hstep, voffB); PG8_STAGE(PG8_SA(0, 0), a2, voffA);
.LBB0_351:
	ds_read_b128 v[146:149], v154
	ds_read_b128 v[158:161], v154 offset:1024
	ds_read_b128 v[162:165], v154 offset:2048
	ds_read_b128 v[166:169], v154 offset:3072
	ds_read_b128 v[170:173], v155
	ds_read_b128 v[174:177], v155 offset:1024
	ds_read_b128 v[178:181], v155 offset:2048
	ds_read_b128 v[182:185], v155 offset:3072
	s_add_u32 s22, s20, 0xfff80080
	s_addc_u32 s23, s21, -1
	s_cmp_eq_u32 s53, 28
	s_cselect_b32 s25, s13, s23
	s_cselect_b32 s24, s43, s22
	s_cselect_b32 s23, s11, s52
	s_cselect_b32 s22, s44, s45
	v_lshl_add_u64 v[218:219], s[20:21], 0, v[138:139]
	s_add_i32 m0, s19, 0xc000
	ds_read_b128 v[186:189], v156
	ds_read_b128 v[190:193], v156 offset:1024
	ds_read_b128 v[194:197], v156 offset:2048
	ds_read_b128 v[198:201], v156 offset:3072
	ds_read_b128 v[202:205], v156 offset:4096
	ds_read_b128 v[206:209], v156 offset:5120
	ds_read_b128 v[210:213], v156 offset:6144
	ds_read_b128 v[214:217], v156 offset:7168
	global_load_lds_dwordx4 v[218:219], off
	v_lshl_add_u64 v[218:219], s[20:21], 0, v[140:141]
	s_add_i32 m0, s19, 0xe000
	s_nop 0
	global_load_lds_dwordx4 v[218:219], off
	s_waitcnt vmcnt(8)
	s_waitcnt lgkmcnt(0)
	s_barrier
	s_setprio 1
	s_waitcnt lgkmcnt(0)
	v_mfma_f32_16x16x32_bf16 v[126:129], v[146:149], v[186:189], v[126:129]
	v_mfma_f32_16x16x32_bf16 v[122:125], v[162:165], v[186:189], v[122:125]
	v_mfma_f32_16x16x32_bf16 v[110:113], v[146:149], v[194:197], v[110:113]
	v_mfma_f32_16x16x32_bf16 v[106:109], v[162:165], v[194:197], v[106:109]
	v_mfma_f32_16x16x32_bf16 v[94:97], v[146:149], v[202:205], v[94:97]
	v_mfma_f32_16x16x32_bf16 v[90:93], v[162:165], v[202:205], v[90:93]
	v_mfma_f32_16x16x32_bf16 v[78:81], v[146:149], v[210:213], v[78:81]
	v_mfma_f32_16x16x32_bf16 v[74:77], v[162:165], v[210:213], v[74:77]
	v_mfma_f32_16x16x32_bf16 v[126:129], v[158:161], v[190:193], v[126:129]
	v_mfma_f32_16x16x32_bf16 v[122:125], v[166:169], v[190:193], v[122:125]
	v_mfma_f32_16x16x32_bf16 v[110:113], v[158:161], v[198:201], v[110:113]
	v_mfma_f32_16x16x32_bf16 v[106:109], v[166:169], v[198:201], v[106:109]
	v_mfma_f32_16x16x32_bf16 v[94:97], v[158:161], v[206:209], v[94:97]
	v_mfma_f32_16x16x32_bf16 v[90:93], v[166:169], v[206:209], v[90:93]
	v_mfma_f32_16x16x32_bf16 v[78:81], v[158:161], v[214:217], v[78:81]
	v_mfma_f32_16x16x32_bf16 v[74:77], v[166:169], v[214:217], v[74:77]
	v_mfma_f32_16x16x32_bf16 v[118:121], v[170:173], v[186:189], v[118:121]
	v_mfma_f32_16x16x32_bf16 v[114:117], v[178:181], v[186:189], v[114:117]
	v_mfma_f32_16x16x32_bf16 v[102:105], v[170:173], v[194:197], v[102:105]
	v_mfma_f32_16x16x32_bf16 v[98:101], v[178:181], v[194:197], v[98:101]
	v_mfma_f32_16x16x32_bf16 v[86:89], v[170:173], v[202:205], v[86:89]
	v_mfma_f32_16x16x32_bf16 v[82:85], v[178:181], v[202:205], v[82:85]
	v_mfma_f32_16x16x32_bf16 v[70:73], v[170:173], v[210:213], v[70:73]
	v_mfma_f32_16x16x32_bf16 v[66:69], v[178:181], v[210:213], v[66:69]
	v_mfma_f32_16x16x32_bf16 v[118:121], v[174:177], v[190:193], v[118:121]
	v_mfma_f32_16x16x32_bf16 v[114:117], v[182:185], v[190:193], v[114:117]
	v_mfma_f32_16x16x32_bf16 v[102:105], v[174:177], v[198:201], v[102:105]
	v_mfma_f32_16x16x32_bf16 v[98:101], v[182:185], v[198:201], v[98:101]
	v_mfma_f32_16x16x32_bf16 v[86:89], v[174:177], v[206:209], v[86:89]
	v_mfma_f32_16x16x32_bf16 v[82:85], v[182:185], v[206:209], v[82:85]
	v_mfma_f32_16x16x32_bf16 v[70:73], v[174:177], v[214:217], v[70:73]
	v_mfma_f32_16x16x32_bf16 v[66:69], v[182:185], v[214:217], v[66:69]
	s_setprio 0
	s_barrier
	s_add_i32 s54, s35, s2
	v_lshl_add_u64 v[218:219], s[22:23], 0, v[134:135]
	s_mov_b32 m0, s54
	ds_read_b128 v[186:189], v156 offset:16384
	ds_read_b128 v[190:193], v156 offset:17408
	ds_read_b128 v[194:197], v156 offset:18432
	ds_read_b128 v[198:201], v156 offset:19456
	ds_read_b128 v[202:205], v156 offset:20480
	ds_read_b128 v[206:209], v156 offset:21504
	ds_read_b128 v[210:213], v156 offset:22528
	ds_read_b128 v[214:217], v156 offset:23552
	global_load_lds_dwordx4 v[218:219], off
	s_add_i32 m0, s54, 0x2000
	s_add_u32 s54, s22, 0x80000
	v_lshl_add_u64 v[220:221], s[22:23], 0, v[130:131]
	s_addc_u32 s55, s23, 0
	s_add_i32 s56, s38, s2
	global_load_lds_dwordx4 v[220:221], off
	v_lshl_add_u64 v[222:223], s[54:55], 0, v[134:135]
	s_mov_b32 m0, s56
	v_lshl_add_u64 v[224:225], s[24:25], 0, v[132:133]
	global_load_lds_dwordx4 v[222:223], off
	v_lshl_add_u64 v[222:223], s[54:55], 0, v[130:131]
	s_add_i32 m0, s56, 0x2000
	s_nop 0
	global_load_lds_dwordx4 v[222:223], off
	v_lshl_add_u64 v[222:223], s[24:25], 0, v[136:137]
	s_mov_b32 m0, s19
	s_nop 0
	global_load_lds_dwordx4 v[222:223], off
	s_mov_b32 m0, s27
	s_nop 0
	global_load_lds_dwordx4 v[224:225], off
	s_waitcnt vmcnt(8)
	s_waitcnt lgkmcnt(0)
	s_barrier
; #define PG8_STAGE(bufoff, gbase, voff) do { _Pragma("unroll") for (int _i = 0; _i < 2; ++_i) \
;         __builtin_amdgcn_global_load_lds((const unsigned*)((const char*)(gbase) + (voff)[_i]), (PG8_LAS unsigned*)(lds + (bufoff) + ldsw + _i * 8192), 16, 0, 0); } while (0)
; #define PG8_LDA(dst, b, h) do { _Pragma("unroll") for (int m = 0; m < 4; ++m) _Pragma("unroll") for (int k = 0; k < 2; ++k) dst[m][k] = *(const PG8_LAS bf16x8*)(lds + PG8_SA(b, h) + aoff + m * 2048 + k * 1024); } while (0)
; #define PG8_LDB(dst, b, h) do { _Pragma("unroll") for (int n = 0; n < 2; ++n) _Pragma("unroll") for (int k = 0; k < 2; ++k) dst[n][k] = *(const PG8_LAS bf16x8*)(lds + PG8_SB(b, h) + boff + n * 2048 + k * 1024); } while (0)
; #define PG8_MMA(ai, bj, At, Bt) do { __builtin_amdgcn_s_setprio(1); _Pragma("unroll") for (int m = 0; m < 4; ++m) _Pragma("unroll") for (int n = 0; n < 2; ++n) _Pragma("unroll") for (int k = 0; k < 2; ++k) \
;         acc[ai][bj][m][n] = __builtin_amdgcn_mfma_f32_16x16x32_bf16(Bt[n][k], At[m][k], acc[ai][bj][m][n], 0, 0, 0); __builtin_amdgcn_s_setprio(0); } while (0)
; #define PG8_WAIT_V(n) asm volatile("s_waitcnt vmcnt(" #n ")" ::: "memory")
; #define PG8_WAIT_L(n) asm volatile("s_waitcnt lgkmcnt(" #n ")" ::: "memory")
; #define PG8_BAR __builtin_amdgcn_s_barrier()
; #define PG8_SCHED __builtin_amdgcn_sched_barrier(0)
; template <class Epi, class Sched, bool ALIGN_EPI = false, bool SP2 = false>
; __device__ __forceinline__ void gemm_phase(PG8_LAS unsigned char* lds, const Gemm g, const Sched& S, const Epi& E) {
;     ...
;             PG8_WAIT_V(8); PG8_WAIT_L(0); PG8_BAR; PG8_MMA(1, 0, At, B0); PG8_MMA(1, 1, At, B1); PG8_BAR; PG8_SCHED;
;             PG8_LDB(B0, 1, 0); PG8_LDB(B1, 1, 1); PG8_SCHED; PG8_LDA(At, 1, 0); PG8_STAGE(PG8_SA(0, 1), a2 + hstep, voffA);
;             PG8_WAIT_V(8); PG8_WAIT_L(0); PG8_BAR; PG8_MMA(0, 0, At, B0); PG8_MMA(0, 1, At, B1); PG8_BAR; PG8_SCHED;
	s_setprio 1
	s_waitcnt lgkmcnt(0)
	v_mfma_f32_16x16x32_bf16 v[62:65], v[146:149], v[186:189], v[62:65]
	v_mfma_f32_16x16x32_bf16 v[58:61], v[162:165], v[186:189], v[58:61]
	v_mfma_f32_16x16x32_bf16 v[46:49], v[146:149], v[194:197], v[46:49]
	v_mfma_f32_16x16x32_bf16 v[42:45], v[162:165], v[194:197], v[42:45]
	v_mfma_f32_16x16x32_bf16 v[30:33], v[146:149], v[202:205], v[30:33]
	v_mfma_f32_16x16x32_bf16 v[26:29], v[162:165], v[202:205], v[26:29]
	v_mfma_f32_16x16x32_bf16 v[14:17], v[146:149], v[210:213], v[14:17]
	v_mfma_f32_16x16x32_bf16 v[10:13], v[162:165], v[210:213], v[10:13]
	v_mfma_f32_16x16x32_bf16 v[62:65], v[158:161], v[190:193], v[62:65]
	v_mfma_f32_16x16x32_bf16 v[58:61], v[166:169], v[190:193], v[58:61]
	v_mfma_f32_16x16x32_bf16 v[46:49], v[158:161], v[198:201], v[46:49]
	v_mfma_f32_16x16x32_bf16 v[42:45], v[166:169], v[198:201], v[42:45]
	v_mfma_f32_16x16x32_bf16 v[30:33], v[158:161], v[206:209], v[30:33]
	v_mfma_f32_16x16x32_bf16 v[26:29], v[166:169], v[206:209], v[26:29]
	v_mfma_f32_16x16x32_bf16 v[14:17], v[158:161], v[214:217], v[14:17]
	v_mfma_f32_16x16x32_bf16 v[10:13], v[166:169], v[214:217], v[10:13]
	v_mfma_f32_16x16x32_bf16 v[54:57], v[170:173], v[186:189], v[54:57]
	v_mfma_f32_16x16x32_bf16 v[50:53], v[178:181], v[186:189], v[50:53]
	v_mfma_f32_16x16x32_bf16 v[38:41], v[170:173], v[194:197], v[38:41]
	v_mfma_f32_16x16x32_bf16 v[34:37], v[178:181], v[194:197], v[34:37]
	v_mfma_f32_16x16x32_bf16 v[22:25], v[170:173], v[202:205], v[22:25]
	v_mfma_f32_16x16x32_bf16 v[18:21], v[178:181], v[202:205], v[18:21]
	v_mfma_f32_16x16x32_bf16 v[6:9], v[170:173], v[210:213], v[6:9]
	v_mfma_f32_16x16x32_bf16 v[2:5], v[178:181], v[210:213], v[2:5]
	v_mfma_f32_16x16x32_bf16 v[54:57], v[174:177], v[190:193], v[54:57]
	v_mfma_f32_16x16x32_bf16 v[50:53], v[182:185], v[190:193], v[50:53]
	v_mfma_f32_16x16x32_bf16 v[38:41], v[174:177], v[198:201], v[38:41]
	v_mfma_f32_16x16x32_bf16 v[34:37], v[182:185], v[198:201], v[34:37]
	v_mfma_f32_16x16x32_bf16 v[22:25], v[174:177], v[206:209], v[22:25]
	v_mfma_f32_16x16x32_bf16 v[18:21], v[182:185], v[206:209], v[18:21]
	v_mfma_f32_16x16x32_bf16 v[6:9], v[174:177], v[214:217], v[6:9]
	v_mfma_f32_16x16x32_bf16 v[2:5], v[182:185], v[214:217], v[2:5]
	s_setprio 0
	s_barrier
	s_add_i32 s54, 0, 0x18000
	v_add_u32_e32 v157, s54, v150
	s_add_i32 s55, 0, 0x1c000
	ds_read_b128 v[146:149], v157
	ds_read_b128 v[158:161], v157 offset:1024
	ds_read_b128 v[162:165], v157 offset:2048
	ds_read_b128 v[166:169], v157 offset:3072
	v_add_u32_e32 v157, s55, v150
	ds_read_b128 v[170:173], v157
	ds_read_b128 v[174:177], v157 offset:1024
	ds_read_b128 v[178:181], v157 offset:2048
	ds_read_b128 v[182:185], v157 offset:3072
	s_add_u32 s24, s24, 0x80000
	s_addc_u32 s25, s25, 0
	s_mov_b32 m0, s28
	v_lshl_add_u64 v[226:227], s[24:25], 0, v[136:137]
	ds_read_b128 v[186:189], v156 offset:32768
	ds_read_b128 v[190:193], v156 offset:33792
	ds_read_b128 v[194:197], v156 offset:34816
	ds_read_b128 v[198:201], v156 offset:35840
	ds_read_b128 v[202:205], v156 offset:36864
	ds_read_b128 v[206:209], v156 offset:37888
	ds_read_b128 v[210:213], v156 offset:38912
	ds_read_b128 v[214:217], v156 offset:39936
	global_load_lds_dwordx4 v[226:227], off
	v_lshl_add_u64 v[226:227], s[24:25], 0, v[132:133]
	s_mov_b32 m0, s29
	s_nop 0
	global_load_lds_dwordx4 v[226:227], off
	s_waitcnt vmcnt(8)
	s_waitcnt lgkmcnt(0)
	s_barrier
	s_setprio 1
	s_waitcnt lgkmcnt(0)
	v_mfma_f32_16x16x32_bf16 v[126:129], v[146:149], v[186:189], v[126:129]
	v_mfma_f32_16x16x32_bf16 v[122:125], v[162:165], v[186:189], v[122:125]
	v_mfma_f32_16x16x32_bf16 v[110:113], v[146:149], v[194:197], v[110:113]
	v_mfma_f32_16x16x32_bf16 v[106:109], v[162:165], v[194:197], v[106:109]
	v_mfma_f32_16x16x32_bf16 v[94:97], v[146:149], v[202:205], v[94:97]
	v_mfma_f32_16x16x32_bf16 v[90:93], v[162:165], v[202:205], v[90:93]
	v_mfma_f32_16x16x32_bf16 v[78:81], v[146:149], v[210:213], v[78:81]
	v_mfma_f32_16x16x32_bf16 v[74:77], v[162:165], v[210:213], v[74:77]
	v_mfma_f32_16x16x32_bf16 v[126:129], v[158:161], v[190:193], v[126:129]
	v_mfma_f32_16x16x32_bf16 v[122:125], v[166:169], v[190:193], v[122:125]
	v_mfma_f32_16x16x32_bf16 v[110:113], v[158:161], v[198:201], v[110:113]
	v_mfma_f32_16x16x32_bf16 v[106:109], v[166:169], v[198:201], v[106:109]
	v_mfma_f32_16x16x32_bf16 v[94:97], v[158:161], v[206:209], v[94:97]
	v_mfma_f32_16x16x32_bf16 v[90:93], v[166:169], v[206:209], v[90:93]
	v_mfma_f32_16x16x32_bf16 v[78:81], v[158:161], v[214:217], v[78:81]
	v_mfma_f32_16x16x32_bf16 v[74:77], v[166:169], v[214:217], v[74:77]
	v_mfma_f32_16x16x32_bf16 v[118:121], v[170:173], v[186:189], v[118:121]
	v_mfma_f32_16x16x32_bf16 v[114:117], v[178:181], v[186:189], v[114:117]
	v_mfma_f32_16x16x32_bf16 v[102:105], v[170:173], v[194:197], v[102:105]
	v_mfma_f32_16x16x32_bf16 v[98:101], v[178:181], v[194:197], v[98:101]
	v_mfma_f32_16x16x32_bf16 v[86:89], v[170:173], v[202:205], v[86:89]
	v_mfma_f32_16x16x32_bf16 v[82:85], v[178:181], v[202:205], v[82:85]
	v_mfma_f32_16x16x32_bf16 v[70:73], v[170:173], v[210:213], v[70:73]
	v_mfma_f32_16x16x32_bf16 v[66:69], v[178:181], v[210:213], v[66:69]
	v_mfma_f32_16x16x32_bf16 v[118:121], v[174:177], v[190:193], v[118:121]
	v_mfma_f32_16x16x32_bf16 v[114:117], v[182:185], v[190:193], v[114:117]
	v_mfma_f32_16x16x32_bf16 v[102:105], v[174:177], v[198:201], v[102:105]
	v_mfma_f32_16x16x32_bf16 v[98:101], v[182:185], v[198:201], v[98:101]
	v_mfma_f32_16x16x32_bf16 v[86:89], v[174:177], v[206:209], v[86:89]
	v_mfma_f32_16x16x32_bf16 v[82:85], v[182:185], v[206:209], v[82:85]
	v_mfma_f32_16x16x32_bf16 v[70:73], v[174:177], v[214:217], v[70:73]
	v_mfma_f32_16x16x32_bf16 v[66:69], v[182:185], v[214:217], v[66:69]
	s_setprio 0
	s_barrier
; #define PG8_STAGE(bufoff, gbase, voff) do { _Pragma("unroll") for (int _i = 0; _i < 2; ++_i) \
;         __builtin_amdgcn_global_load_lds((const unsigned*)((const char*)(gbase) + (voff)[_i]), (PG8_LAS unsigned*)(lds + (bufoff) + ldsw + _i * 8192), 16, 0, 0); } while (0)
; #define PG8_LDA(dst, b, h) do { _Pragma("unroll") for (int m = 0; m < 4; ++m) _Pragma("unroll") for (int k = 0; k < 2; ++k) dst[m][k] = *(const PG8_LAS bf16x8*)(lds + PG8_SA(b, h) + aoff + m * 2048 + k * 1024); } while (0)
; #define PG8_MMA(ai, bj, At, Bt) do { __builtin_amdgcn_s_setprio(1); _Pragma("unroll") for (int m = 0; m < 4; ++m) _Pragma("unroll") for (int n = 0; n < 2; ++n) _Pragma("unroll") for (int k = 0; k < 2; ++k) \
;         acc[ai][bj][m][n] = __builtin_amdgcn_mfma_f32_16x16x32_bf16(Bt[n][k], At[m][k], acc[ai][bj][m][n], 0, 0, 0); __builtin_amdgcn_s_setprio(0); } while (0)
; #define PG8_WAIT_V(n) asm volatile("s_waitcnt vmcnt(" #n ")" ::: "memory")
; #define PG8_WAIT_L(n) asm volatile("s_waitcnt lgkmcnt(" #n ")" ::: "memory")
; #define PG8_BAR __builtin_amdgcn_s_barrier()
; #define PG8_SCHED __builtin_amdgcn_sched_barrier(0)
; template <class Epi, class Sched, bool ALIGN_EPI = false, bool SP2 = false>
; __device__ __forceinline__ void gemm_phase(PG8_LAS unsigned char* lds, const Gemm g, const Sched& S, const Epi& E) {
;     ...
;         for (int t = 0; t < nt; t += 2) {
;     ...
;             PG8_LDA(At, 1, 1); PG8_STAGE(PG8_SB(1, 0), b3, voffB); PG8_STAGE(PG8_SB(1, 1), b3 + hstep, voffB); PG8_STAGE(PG8_SA(1, 0), a3, voffA);
;             PG8_WAIT_V(8); PG8_WAIT_L(0); PG8_BAR; PG8_MMA(1, 0, At, B0); PG8_MMA(1, 1, At, B1); PG8_BAR; PG8_SCHED;
;     ...
;         if constexpr (ALIGN_EPI) { if (wr == 0) PG8_BAR; }
	s_add_i32 s24, s54, s2
	v_lshl_add_u64 v[218:219], v[218:219], 0, s[6:7]
	s_mov_b32 m0, s24
	ds_read_b128 v[186:189], v156 offset:49152
	ds_read_b128 v[190:193], v156 offset:50176
	ds_read_b128 v[194:197], v156 offset:51200
	ds_read_b128 v[198:201], v156 offset:52224
	ds_read_b128 v[202:205], v156 offset:53248
	ds_read_b128 v[206:209], v156 offset:54272
	ds_read_b128 v[210:213], v156 offset:55296
	ds_read_b128 v[214:217], v156 offset:56320
	global_load_lds_dwordx4 v[218:219], off
	s_add_i32 m0, s24, 0x2000
	s_add_u32 s22, s22, 0x80080
	v_lshl_add_u64 v[218:219], v[220:221], 0, s[6:7]
	s_addc_u32 s23, s23, 0
	s_add_i32 s24, s55, s2
	global_load_lds_dwordx4 v[218:219], off
	v_lshl_add_u64 v[218:219], s[22:23], 0, v[134:135]
	s_mov_b32 m0, s24
	s_nop 0
	global_load_lds_dwordx4 v[218:219], off
	v_lshl_add_u64 v[218:219], s[22:23], 0, v[130:131]
	s_add_i32 m0, s24, 0x2000
	s_nop 0
	global_load_lds_dwordx4 v[218:219], off
	v_lshl_add_u64 v[218:219], v[222:223], 0, s[6:7]
	s_mov_b32 m0, s31
	s_nop 0
	global_load_lds_dwordx4 v[218:219], off
	v_lshl_add_u64 v[218:219], v[224:225], 0, s[6:7]
	s_mov_b32 m0, s33
	s_nop 0
	global_load_lds_dwordx4 v[218:219], off
	s_waitcnt vmcnt(8)
	s_waitcnt lgkmcnt(0)
	s_barrier
	s_setprio 1
	s_waitcnt lgkmcnt(0)
	v_mfma_f32_16x16x32_bf16 v[62:65], v[146:149], v[186:189], v[62:65]
	v_mfma_f32_16x16x32_bf16 v[58:61], v[162:165], v[186:189], v[58:61]
	v_mfma_f32_16x16x32_bf16 v[46:49], v[146:149], v[194:197], v[46:49]
	v_mfma_f32_16x16x32_bf16 v[42:45], v[162:165], v[194:197], v[42:45]
	v_mfma_f32_16x16x32_bf16 v[30:33], v[146:149], v[202:205], v[30:33]
	v_mfma_f32_16x16x32_bf16 v[26:29], v[162:165], v[202:205], v[26:29]
	v_mfma_f32_16x16x32_bf16 v[14:17], v[146:149], v[210:213], v[14:17]
	v_mfma_f32_16x16x32_bf16 v[10:13], v[162:165], v[210:213], v[10:13]
	v_mfma_f32_16x16x32_bf16 v[62:65], v[158:161], v[190:193], v[62:65]
	v_mfma_f32_16x16x32_bf16 v[58:61], v[166:169], v[190:193], v[58:61]
	v_mfma_f32_16x16x32_bf16 v[46:49], v[158:161], v[198:201], v[46:49]
	v_mfma_f32_16x16x32_bf16 v[42:45], v[166:169], v[198:201], v[42:45]
	v_mfma_f32_16x16x32_bf16 v[30:33], v[158:161], v[206:209], v[30:33]
	v_mfma_f32_16x16x32_bf16 v[26:29], v[166:169], v[206:209], v[26:29]
	v_mfma_f32_16x16x32_bf16 v[14:17], v[158:161], v[214:217], v[14:17]
	v_mfma_f32_16x16x32_bf16 v[10:13], v[166:169], v[214:217], v[10:13]
	v_mfma_f32_16x16x32_bf16 v[54:57], v[170:173], v[186:189], v[54:57]
	v_mfma_f32_16x16x32_bf16 v[50:53], v[178:181], v[186:189], v[50:53]
	v_mfma_f32_16x16x32_bf16 v[38:41], v[170:173], v[194:197], v[38:41]
	v_mfma_f32_16x16x32_bf16 v[34:37], v[178:181], v[194:197], v[34:37]
	v_mfma_f32_16x16x32_bf16 v[22:25], v[170:173], v[202:205], v[22:25]
	v_mfma_f32_16x16x32_bf16 v[18:21], v[178:181], v[202:205], v[18:21]
	v_mfma_f32_16x16x32_bf16 v[6:9], v[170:173], v[210:213], v[6:9]
	v_mfma_f32_16x16x32_bf16 v[2:5], v[178:181], v[210:213], v[2:5]
	v_mfma_f32_16x16x32_bf16 v[54:57], v[174:177], v[190:193], v[54:57]
	v_mfma_f32_16x16x32_bf16 v[50:53], v[182:185], v[190:193], v[50:53]
	v_mfma_f32_16x16x32_bf16 v[38:41], v[174:177], v[198:201], v[38:41]
	v_mfma_f32_16x16x32_bf16 v[34:37], v[182:185], v[198:201], v[34:37]
	v_mfma_f32_16x16x32_bf16 v[22:25], v[174:177], v[206:209], v[22:25]
	v_mfma_f32_16x16x32_bf16 v[18:21], v[182:185], v[206:209], v[18:21]
	v_mfma_f32_16x16x32_bf16 v[6:9], v[174:177], v[214:217], v[6:9]
	v_mfma_f32_16x16x32_bf16 v[2:5], v[182:185], v[214:217], v[2:5]
	s_setprio 0
	s_barrier
	s_add_i32 s53, s53, 2
	s_add_u32 s20, s20, 0x100
	s_addc_u32 s21, s21, 0
	s_add_u32 s45, s45, 0x100
	s_addc_u32 s52, s52, 0
	s_cmp_gt_u32 s53, 29
	s_cbranch_scc0 .LBB0_351
	s_and_b64 vcc, exec, s[8:9]
	s_cbranch_vccz .LBB0_354
	s_barrier

; #define PG8_STAGE(bufoff, gbase, voff) do { _Pragma("unroll") for (int _i = 0; _i < 2; ++_i) \
;         __builtin_amdgcn_global_load_lds((const unsigned*)((const char*)(gbase) + (voff)[_i]), (PG8_LAS unsigned*)(lds + (bufoff) + ldsw + _i * 8192), 16, 0, 0); } while (0)
; #define PG8_LDA(dst, b, h) do { _Pragma("unroll") for (int m = 0; m < 4; ++m) _Pragma("unroll") for (int k = 0; k < 2; ++k) dst[m][k] = *(const PG8_LAS bf16x8*)(lds + PG8_SA(b, h) + aoff + m * 2048 + k * 1024); } while (0)
; #define PG8_LDB(dst, b, h) do { _Pragma("unroll") for (int n = 0; n < 2; ++n) _Pragma("unroll") for (int k = 0; k < 2; ++k) dst[n][k] = *(const PG8_LAS bf16x8*)(lds + PG8_SB(b, h) + boff + n * 2048 + k * 1024); } while (0)
; #define PG8_MMA(ai, bj, At, Bt) do { __builtin_amdgcn_s_setprio(1); _Pragma("unroll") for (int m = 0; m < 4; ++m) _Pragma("unroll") for (int n = 0; n < 2; ++n) _Pragma("unroll") for (int k = 0; k < 2; ++k) \
;         acc[ai][bj][m][n] = __builtin_amdgcn_mfma_f32_16x16x32_bf16(Bt[n][k], At[m][k], acc[ai][bj][m][n], 0, 0, 0); __builtin_amdgcn_s_setprio(0); } while (0)
; #define PG8_WAIT_V(n) asm volatile("s_waitcnt vmcnt(" #n ")" ::: "memory")
; #define PG8_WAIT_L(n) asm volatile("s_waitcnt lgkmcnt(" #n ")" ::: "memory")
; #define PG8_BAR __builtin_amdgcn_s_barrier()
; #define PG8_SCHED __builtin_amdgcn_sched_barrier(0)
; template <class Epi, class Sched, bool ALIGN_EPI = false, bool SP2 = false>
; __device__ __forceinline__ void gemm_phase(PG8_LAS unsigned char* lds, const Gemm g, const Sched& S, const Epi& E) {
;     ...
;             PG8_LDB(B0, 0, 0); PG8_LDB(B1, 0, 1); PG8_SCHED; PG8_LDA(At, 0, 0); PG8_STAGE(PG8_SA(1, 1), a1 + hstep, voffA);
;             PG8_WAIT_V(8); PG8_WAIT_L(0); PG8_BAR; PG8_MMA(0, 0, At, B0); PG8_MMA(0, 1, At, B1); PG8_BAR; PG8_SCHED;
;             PG8_LDA(At, 0, 1); PG8_STAGE(PG8_SB(0, 0), b2, voffB); PG8_STAGE(PG8_SB(0, 1), b2 + hstep, voffB); PG8_STAGE(PG8_SA(0, 0), a2, voffA);
.LBB0_448:
	ds_read_b128 v[154:157], v150
	ds_read_b128 v[158:161], v150 offset:1024
	ds_read_b128 v[162:165], v150 offset:2048
	ds_read_b128 v[166:169], v150 offset:3072
	ds_read_b128 v[170:173], v151
	ds_read_b128 v[174:177], v151 offset:1024
	ds_read_b128 v[178:181], v151 offset:2048
	ds_read_b128 v[182:185], v151 offset:3072
	s_add_u32 s16, s14, 0x100
	s_addc_u32 s17, s15, 0
	s_cmpk_eq_i32 s43, 0x54
	s_cselect_b32 s21, s5, s17
	s_cselect_b32 s20, s4, s16
	s_cselect_b32 s19, s13, s42
	s_cselect_b32 s18, s12, s39
	v_lshl_add_u64 v[218:219], s[14:15], 0, v[138:139]
	s_add_i32 m0, s22, 0xc000
	ds_read_b128 v[186:189], v152
	ds_read_b128 v[190:193], v152 offset:1024
	ds_read_b128 v[194:197], v152 offset:2048
	ds_read_b128 v[198:201], v152 offset:3072
	ds_read_b128 v[202:205], v152 offset:4096
	ds_read_b128 v[206:209], v152 offset:5120
	ds_read_b128 v[210:213], v152 offset:6144
	ds_read_b128 v[214:217], v152 offset:7168
	global_load_lds_dwordx4 v[218:219], off
	v_lshl_add_u64 v[218:219], s[14:15], 0, v[140:141]
	s_add_i32 m0, s22, 0xe000
	s_nop 0
	global_load_lds_dwordx4 v[218:219], off
	s_waitcnt vmcnt(8)
	s_waitcnt lgkmcnt(0)
	s_barrier
	s_setprio 1
	s_waitcnt lgkmcnt(0)
	v_mfma_f32_16x16x32_bf16 v[126:129], v[154:157], v[186:189], v[126:129]
	v_mfma_f32_16x16x32_bf16 v[122:125], v[162:165], v[186:189], v[122:125]
	v_mfma_f32_16x16x32_bf16 v[114:117], v[154:157], v[194:197], v[114:117]
	v_mfma_f32_16x16x32_bf16 v[106:109], v[162:165], v[194:197], v[106:109]
	v_mfma_f32_16x16x32_bf16 v[102:105], v[154:157], v[202:205], v[102:105]
	v_mfma_f32_16x16x32_bf16 v[94:97], v[162:165], v[202:205], v[94:97]
	v_mfma_f32_16x16x32_bf16 v[86:89], v[154:157], v[210:213], v[86:89]
	v_mfma_f32_16x16x32_bf16 v[78:81], v[162:165], v[210:213], v[78:81]
	v_mfma_f32_16x16x32_bf16 v[126:129], v[158:161], v[190:193], v[126:129]
	v_mfma_f32_16x16x32_bf16 v[122:125], v[166:169], v[190:193], v[122:125]
	v_mfma_f32_16x16x32_bf16 v[114:117], v[158:161], v[198:201], v[114:117]
	v_mfma_f32_16x16x32_bf16 v[106:109], v[166:169], v[198:201], v[106:109]
	v_mfma_f32_16x16x32_bf16 v[102:105], v[158:161], v[206:209], v[102:105]
	v_mfma_f32_16x16x32_bf16 v[94:97], v[166:169], v[206:209], v[94:97]
	v_mfma_f32_16x16x32_bf16 v[86:89], v[158:161], v[214:217], v[86:89]
	v_mfma_f32_16x16x32_bf16 v[78:81], v[166:169], v[214:217], v[78:81]
	v_mfma_f32_16x16x32_bf16 v[118:121], v[170:173], v[186:189], v[118:121]
	v_mfma_f32_16x16x32_bf16 v[110:113], v[178:181], v[186:189], v[110:113]
	v_mfma_f32_16x16x32_bf16 v[98:101], v[170:173], v[194:197], v[98:101]
	v_mfma_f32_16x16x32_bf16 v[90:93], v[178:181], v[194:197], v[90:93]
	v_mfma_f32_16x16x32_bf16 v[82:85], v[170:173], v[202:205], v[82:85]
	v_mfma_f32_16x16x32_bf16 v[74:77], v[178:181], v[202:205], v[74:77]
	v_mfma_f32_16x16x32_bf16 v[70:73], v[170:173], v[210:213], v[70:73]
	v_mfma_f32_16x16x32_bf16 v[66:69], v[178:181], v[210:213], v[66:69]
	v_mfma_f32_16x16x32_bf16 v[118:121], v[174:177], v[190:193], v[118:121]
	v_mfma_f32_16x16x32_bf16 v[110:113], v[182:185], v[190:193], v[110:113]
	v_mfma_f32_16x16x32_bf16 v[98:101], v[174:177], v[198:201], v[98:101]
	v_mfma_f32_16x16x32_bf16 v[90:93], v[182:185], v[198:201], v[90:93]
	v_mfma_f32_16x16x32_bf16 v[82:85], v[174:177], v[206:209], v[82:85]
	v_mfma_f32_16x16x32_bf16 v[74:77], v[182:185], v[206:209], v[74:77]
	v_mfma_f32_16x16x32_bf16 v[70:73], v[174:177], v[214:217], v[70:73]
	v_mfma_f32_16x16x32_bf16 v[66:69], v[182:185], v[214:217], v[66:69]
	s_setprio 0
	s_barrier
	s_add_i32 s14, s30, s3
	v_lshl_add_u64 v[218:219], s[18:19], 0, v[132:133]
	s_mov_b32 m0, s14
	ds_read_b128 v[186:189], v152 offset:16384
	ds_read_b128 v[190:193], v152 offset:17408
	ds_read_b128 v[194:197], v152 offset:18432
	ds_read_b128 v[198:201], v152 offset:19456
	ds_read_b128 v[202:205], v152 offset:20480
	ds_read_b128 v[206:209], v152 offset:21504
	ds_read_b128 v[210:213], v152 offset:22528
	ds_read_b128 v[214:217], v152 offset:23552
	global_load_lds_dwordx4 v[218:219], off
	s_add_i32 m0, s14, 0x2000
	s_add_u32 s14, s18, 0x160000
	v_lshl_add_u64 v[220:221], s[18:19], 0, v[136:137]
	s_addc_u32 s15, s19, 0
	s_add_i32 s44, s31, s3
	global_load_lds_dwordx4 v[220:221], off
	v_lshl_add_u64 v[222:223], s[14:15], 0, v[132:133]
	s_mov_b32 m0, s44
	v_lshl_add_u64 v[224:225], s[20:21], 0, v[134:135]
	global_load_lds_dwordx4 v[222:223], off
	v_lshl_add_u64 v[222:223], s[14:15], 0, v[136:137]
	s_add_i32 m0, s44, 0x2000
	s_nop 0
	global_load_lds_dwordx4 v[222:223], off
	v_lshl_add_u64 v[222:223], s[20:21], 0, v[130:131]
	s_mov_b32 m0, s22
	s_nop 0
	global_load_lds_dwordx4 v[222:223], off
	s_mov_b32 m0, s23
	s_nop 0
	global_load_lds_dwordx4 v[224:225], off
	s_waitcnt vmcnt(8)
	s_waitcnt lgkmcnt(0)
	s_barrier
; #define PG8_STAGE(bufoff, gbase, voff) do { _Pragma("unroll") for (int _i = 0; _i < 2; ++_i) \
;         __builtin_amdgcn_global_load_lds((const unsigned*)((const char*)(gbase) + (voff)[_i]), (PG8_LAS unsigned*)(lds + (bufoff) + ldsw + _i * 8192), 16, 0, 0); } while (0)
; #define PG8_LDA(dst, b, h) do { _Pragma("unroll") for (int m = 0; m < 4; ++m) _Pragma("unroll") for (int k = 0; k < 2; ++k) dst[m][k] = *(const PG8_LAS bf16x8*)(lds + PG8_SA(b, h) + aoff + m * 2048 + k * 1024); } while (0)
; #define PG8_LDB(dst, b, h) do { _Pragma("unroll") for (int n = 0; n < 2; ++n) _Pragma("unroll") for (int k = 0; k < 2; ++k) dst[n][k] = *(const PG8_LAS bf16x8*)(lds + PG8_SB(b, h) + boff + n * 2048 + k * 1024); } while (0)
; #define PG8_MMA(ai, bj, At, Bt) do { __builtin_amdgcn_s_setprio(1); _Pragma("unroll") for (int m = 0; m < 4; ++m) _Pragma("unroll") for (int n = 0; n < 2; ++n) _Pragma("unroll") for (int k = 0; k < 2; ++k) \
;         acc[ai][bj][m][n] = __builtin_amdgcn_mfma_f32_16x16x32_bf16(Bt[n][k], At[m][k], acc[ai][bj][m][n], 0, 0, 0); __builtin_amdgcn_s_setprio(0); } while (0)
; #define PG8_WAIT_V(n) asm volatile("s_waitcnt vmcnt(" #n ")" ::: "memory")
; #define PG8_WAIT_L(n) asm volatile("s_waitcnt lgkmcnt(" #n ")" ::: "memory")
; #define PG8_BAR __builtin_amdgcn_s_barrier()
; #define PG8_SCHED __builtin_amdgcn_sched_barrier(0)
; template <class Epi, class Sched, bool ALIGN_EPI = false, bool SP2 = false>
; __device__ __forceinline__ void gemm_phase(PG8_LAS unsigned char* lds, const Gemm g, const Sched& S, const Epi& E) {
;     ...
;             PG8_WAIT_V(8); PG8_WAIT_L(0); PG8_BAR; PG8_MMA(1, 0, At, B0); PG8_MMA(1, 1, At, B1); PG8_BAR; PG8_SCHED;
;             PG8_LDB(B0, 1, 0); PG8_LDB(B1, 1, 1); PG8_SCHED; PG8_LDA(At, 1, 0); PG8_STAGE(PG8_SA(0, 1), a2 + hstep, voffA);
;             PG8_WAIT_V(8); PG8_WAIT_L(0); PG8_BAR; PG8_MMA(0, 0, At, B0); PG8_MMA(0, 1, At, B1); PG8_BAR; PG8_SCHED;
	s_setprio 1
	s_waitcnt lgkmcnt(0)
	v_mfma_f32_16x16x32_bf16 v[62:65], v[154:157], v[186:189], v[62:65]
	v_mfma_f32_16x16x32_bf16 v[58:61], v[162:165], v[186:189], v[58:61]
	v_mfma_f32_16x16x32_bf16 v[54:57], v[154:157], v[194:197], v[54:57]
	v_mfma_f32_16x16x32_bf16 v[46:49], v[162:165], v[194:197], v[46:49]
	v_mfma_f32_16x16x32_bf16 v[38:41], v[154:157], v[202:205], v[38:41]
	v_mfma_f32_16x16x32_bf16 v[30:33], v[162:165], v[202:205], v[30:33]
	v_mfma_f32_16x16x32_bf16 v[22:25], v[154:157], v[210:213], v[22:25]
	v_mfma_f32_16x16x32_bf16 v[14:17], v[162:165], v[210:213], v[14:17]
	v_mfma_f32_16x16x32_bf16 v[62:65], v[158:161], v[190:193], v[62:65]
	v_mfma_f32_16x16x32_bf16 v[58:61], v[166:169], v[190:193], v[58:61]
	v_mfma_f32_16x16x32_bf16 v[54:57], v[158:161], v[198:201], v[54:57]
	v_mfma_f32_16x16x32_bf16 v[46:49], v[166:169], v[198:201], v[46:49]
	v_mfma_f32_16x16x32_bf16 v[38:41], v[158:161], v[206:209], v[38:41]
	v_mfma_f32_16x16x32_bf16 v[30:33], v[166:169], v[206:209], v[30:33]
	v_mfma_f32_16x16x32_bf16 v[22:25], v[158:161], v[214:217], v[22:25]
	v_mfma_f32_16x16x32_bf16 v[14:17], v[166:169], v[214:217], v[14:17]
	v_mfma_f32_16x16x32_bf16 v[50:53], v[170:173], v[186:189], v[50:53]
	v_mfma_f32_16x16x32_bf16 v[42:45], v[178:181], v[186:189], v[42:45]
	v_mfma_f32_16x16x32_bf16 v[34:37], v[170:173], v[194:197], v[34:37]
	v_mfma_f32_16x16x32_bf16 v[26:29], v[178:181], v[194:197], v[26:29]
	v_mfma_f32_16x16x32_bf16 v[18:21], v[170:173], v[202:205], v[18:21]
	v_mfma_f32_16x16x32_bf16 v[10:13], v[178:181], v[202:205], v[10:13]
	v_mfma_f32_16x16x32_bf16 v[6:9], v[170:173], v[210:213], v[6:9]
	v_mfma_f32_16x16x32_bf16 v[2:5], v[178:181], v[210:213], v[2:5]
	v_mfma_f32_16x16x32_bf16 v[50:53], v[174:177], v[190:193], v[50:53]
	v_mfma_f32_16x16x32_bf16 v[42:45], v[182:185], v[190:193], v[42:45]
	v_mfma_f32_16x16x32_bf16 v[34:37], v[174:177], v[198:201], v[34:37]
	v_mfma_f32_16x16x32_bf16 v[26:29], v[182:185], v[198:201], v[26:29]
	v_mfma_f32_16x16x32_bf16 v[18:21], v[174:177], v[206:209], v[18:21]
	v_mfma_f32_16x16x32_bf16 v[10:13], v[182:185], v[206:209], v[10:13]
	v_mfma_f32_16x16x32_bf16 v[6:9], v[174:177], v[214:217], v[6:9]
	v_mfma_f32_16x16x32_bf16 v[2:5], v[182:185], v[214:217], v[2:5]
	s_setprio 0
	s_barrier
	s_add_i32 s44, 0, 0x18000
	v_add_u32_e32 v153, s44, v146
	s_add_i32 s45, 0, 0x1c000
	ds_read_b128 v[154:157], v153
	ds_read_b128 v[158:161], v153 offset:1024
	ds_read_b128 v[162:165], v153 offset:2048
	ds_read_b128 v[166:169], v153 offset:3072
	v_add_u32_e32 v153, s45, v146
	ds_read_b128 v[170:173], v153
	ds_read_b128 v[174:177], v153 offset:1024
	ds_read_b128 v[178:181], v153 offset:2048
	ds_read_b128 v[182:185], v153 offset:3072
	s_add_u32 s14, s20, 0x160000
	s_addc_u32 s15, s21, 0
	s_mov_b32 m0, s24
	v_lshl_add_u64 v[226:227], s[14:15], 0, v[130:131]
	ds_read_b128 v[186:189], v152 offset:32768
	ds_read_b128 v[190:193], v152 offset:33792
	ds_read_b128 v[194:197], v152 offset:34816
	ds_read_b128 v[198:201], v152 offset:35840
	ds_read_b128 v[202:205], v152 offset:36864
	ds_read_b128 v[206:209], v152 offset:37888
	ds_read_b128 v[210:213], v152 offset:38912
	ds_read_b128 v[214:217], v152 offset:39936
	global_load_lds_dwordx4 v[226:227], off
	v_lshl_add_u64 v[226:227], s[14:15], 0, v[134:135]
	s_mov_b32 m0, s25
	s_nop 0
	global_load_lds_dwordx4 v[226:227], off
	s_waitcnt vmcnt(8)
	s_waitcnt lgkmcnt(0)
	s_barrier
	s_setprio 1
	s_waitcnt lgkmcnt(0)
	v_mfma_f32_16x16x32_bf16 v[126:129], v[154:157], v[186:189], v[126:129]
	v_mfma_f32_16x16x32_bf16 v[122:125], v[162:165], v[186:189], v[122:125]
	v_mfma_f32_16x16x32_bf16 v[114:117], v[154:157], v[194:197], v[114:117]
	v_mfma_f32_16x16x32_bf16 v[106:109], v[162:165], v[194:197], v[106:109]
	v_mfma_f32_16x16x32_bf16 v[102:105], v[154:157], v[202:205], v[102:105]
	v_mfma_f32_16x16x32_bf16 v[94:97], v[162:165], v[202:205], v[94:97]
	v_mfma_f32_16x16x32_bf16 v[86:89], v[154:157], v[210:213], v[86:89]
	v_mfma_f32_16x16x32_bf16 v[78:81], v[162:165], v[210:213], v[78:81]
	v_mfma_f32_16x16x32_bf16 v[126:129], v[158:161], v[190:193], v[126:129]
	v_mfma_f32_16x16x32_bf16 v[122:125], v[166:169], v[190:193], v[122:125]
	v_mfma_f32_16x16x32_bf16 v[114:117], v[158:161], v[198:201], v[114:117]
	v_mfma_f32_16x16x32_bf16 v[106:109], v[166:169], v[198:201], v[106:109]
	v_mfma_f32_16x16x32_bf16 v[102:105], v[158:161], v[206:209], v[102:105]
	v_mfma_f32_16x16x32_bf16 v[94:97], v[166:169], v[206:209], v[94:97]
	v_mfma_f32_16x16x32_bf16 v[86:89], v[158:161], v[214:217], v[86:89]
	v_mfma_f32_16x16x32_bf16 v[78:81], v[166:169], v[214:217], v[78:81]
	v_mfma_f32_16x16x32_bf16 v[118:121], v[170:173], v[186:189], v[118:121]
	v_mfma_f32_16x16x32_bf16 v[110:113], v[178:181], v[186:189], v[110:113]
	v_mfma_f32_16x16x32_bf16 v[98:101], v[170:173], v[194:197], v[98:101]
	v_mfma_f32_16x16x32_bf16 v[90:93], v[178:181], v[194:197], v[90:93]
	v_mfma_f32_16x16x32_bf16 v[82:85], v[170:173], v[202:205], v[82:85]
	v_mfma_f32_16x16x32_bf16 v[74:77], v[178:181], v[202:205], v[74:77]
	v_mfma_f32_16x16x32_bf16 v[70:73], v[170:173], v[210:213], v[70:73]
	v_mfma_f32_16x16x32_bf16 v[66:69], v[178:181], v[210:213], v[66:69]
	v_mfma_f32_16x16x32_bf16 v[118:121], v[174:177], v[190:193], v[118:121]
	v_mfma_f32_16x16x32_bf16 v[110:113], v[182:185], v[190:193], v[110:113]
	v_mfma_f32_16x16x32_bf16 v[98:101], v[174:177], v[198:201], v[98:101]
	v_mfma_f32_16x16x32_bf16 v[90:93], v[182:185], v[198:201], v[90:93]
	v_mfma_f32_16x16x32_bf16 v[82:85], v[174:177], v[206:209], v[82:85]
	v_mfma_f32_16x16x32_bf16 v[74:77], v[182:185], v[206:209], v[74:77]
	v_mfma_f32_16x16x32_bf16 v[70:73], v[174:177], v[214:217], v[70:73]
	v_mfma_f32_16x16x32_bf16 v[66:69], v[182:185], v[214:217], v[66:69]
	s_setprio 0
	s_barrier
; #define PG8_STAGE(bufoff, gbase, voff) do { _Pragma("unroll") for (int _i = 0; _i < 2; ++_i) \
;         __builtin_amdgcn_global_load_lds((const unsigned*)((const char*)(gbase) + (voff)[_i]), (PG8_LAS unsigned*)(lds + (bufoff) + ldsw + _i * 8192), 16, 0, 0); } while (0)
; #define PG8_LDA(dst, b, h) do { _Pragma("unroll") for (int m = 0; m < 4; ++m) _Pragma("unroll") for (int k = 0; k < 2; ++k) dst[m][k] = *(const PG8_LAS bf16x8*)(lds + PG8_SA(b, h) + aoff + m * 2048 + k * 1024); } while (0)
; #define PG8_MMA(ai, bj, At, Bt) do { __builtin_amdgcn_s_setprio(1); _Pragma("unroll") for (int m = 0; m < 4; ++m) _Pragma("unroll") for (int n = 0; n < 2; ++n) _Pragma("unroll") for (int k = 0; k < 2; ++k) \
;         acc[ai][bj][m][n] = __builtin_amdgcn_mfma_f32_16x16x32_bf16(Bt[n][k], At[m][k], acc[ai][bj][m][n], 0, 0, 0); __builtin_amdgcn_s_setprio(0); } while (0)
; #define PG8_WAIT_V(n) asm volatile("s_waitcnt vmcnt(" #n ")" ::: "memory")
; #define PG8_WAIT_L(n) asm volatile("s_waitcnt lgkmcnt(" #n ")" ::: "memory")
; #define PG8_BAR __builtin_amdgcn_s_barrier()
; #define PG8_SCHED __builtin_amdgcn_sched_barrier(0)
; template <class Epi, class Sched, bool ALIGN_EPI = false, bool SP2 = false>
; __device__ __forceinline__ void gemm_phase(PG8_LAS unsigned char* lds, const Gemm g, const Sched& S, const Epi& E) {
;     ...
;         for (int t = 0; t < nt; t += 2) {
;     ...
;             PG8_LDA(At, 1, 1); PG8_STAGE(PG8_SB(1, 0), b3, voffB); PG8_STAGE(PG8_SB(1, 1), b3 + hstep, voffB); PG8_STAGE(PG8_SA(1, 0), a3, voffA);
;             PG8_WAIT_V(8); PG8_WAIT_L(0); PG8_BAR; PG8_MMA(1, 0, At, B0); PG8_MMA(1, 1, At, B1); PG8_BAR; PG8_SCHED;
;     ...
;         if constexpr (ALIGN_EPI) { if (wr == 0) PG8_BAR; }
	s_add_i32 s14, s44, s3
	v_lshl_add_u64 v[218:219], v[218:219], 0, s[8:9]
	s_mov_b32 m0, s14
	ds_read_b128 v[186:189], v152 offset:49152
	ds_read_b128 v[190:193], v152 offset:50176
	ds_read_b128 v[194:197], v152 offset:51200
	ds_read_b128 v[198:201], v152 offset:52224
	ds_read_b128 v[202:205], v152 offset:53248
	ds_read_b128 v[206:209], v152 offset:54272
	ds_read_b128 v[210:213], v152 offset:55296
	ds_read_b128 v[214:217], v152 offset:56320
	global_load_lds_dwordx4 v[218:219], off
	s_add_i32 m0, s14, 0x2000
	s_add_u32 s14, s18, 0x160080
	v_lshl_add_u64 v[218:219], v[220:221], 0, s[8:9]
	s_addc_u32 s15, s19, 0
	s_add_i32 s18, s45, s3
	global_load_lds_dwordx4 v[218:219], off
	v_lshl_add_u64 v[218:219], s[14:15], 0, v[132:133]
	s_mov_b32 m0, s18
	s_nop 0
	global_load_lds_dwordx4 v[218:219], off
	v_lshl_add_u64 v[218:219], s[14:15], 0, v[136:137]
	s_add_i32 m0, s18, 0x2000
	s_nop 0
	global_load_lds_dwordx4 v[218:219], off
	v_lshl_add_u64 v[218:219], v[222:223], 0, s[8:9]
	s_mov_b32 m0, s27
	s_nop 0
	global_load_lds_dwordx4 v[218:219], off
	v_lshl_add_u64 v[218:219], v[224:225], 0, s[8:9]
	s_mov_b32 m0, s28
	s_nop 0
	global_load_lds_dwordx4 v[218:219], off
	s_waitcnt vmcnt(8)
	s_waitcnt lgkmcnt(0)
	s_barrier
	s_setprio 1
	s_waitcnt lgkmcnt(0)
	v_mfma_f32_16x16x32_bf16 v[62:65], v[154:157], v[186:189], v[62:65]
	v_mfma_f32_16x16x32_bf16 v[58:61], v[162:165], v[186:189], v[58:61]
	v_mfma_f32_16x16x32_bf16 v[54:57], v[154:157], v[194:197], v[54:57]
	v_mfma_f32_16x16x32_bf16 v[46:49], v[162:165], v[194:197], v[46:49]
	v_mfma_f32_16x16x32_bf16 v[38:41], v[154:157], v[202:205], v[38:41]
	v_mfma_f32_16x16x32_bf16 v[30:33], v[162:165], v[202:205], v[30:33]
	v_mfma_f32_16x16x32_bf16 v[22:25], v[154:157], v[210:213], v[22:25]
	v_mfma_f32_16x16x32_bf16 v[14:17], v[162:165], v[210:213], v[14:17]
	v_mfma_f32_16x16x32_bf16 v[62:65], v[158:161], v[190:193], v[62:65]
	v_mfma_f32_16x16x32_bf16 v[58:61], v[166:169], v[190:193], v[58:61]
	v_mfma_f32_16x16x32_bf16 v[54:57], v[158:161], v[198:201], v[54:57]
	v_mfma_f32_16x16x32_bf16 v[46:49], v[166:169], v[198:201], v[46:49]
	v_mfma_f32_16x16x32_bf16 v[38:41], v[158:161], v[206:209], v[38:41]
	v_mfma_f32_16x16x32_bf16 v[30:33], v[166:169], v[206:209], v[30:33]
	v_mfma_f32_16x16x32_bf16 v[22:25], v[158:161], v[214:217], v[22:25]
	v_mfma_f32_16x16x32_bf16 v[14:17], v[166:169], v[214:217], v[14:17]
	v_mfma_f32_16x16x32_bf16 v[50:53], v[170:173], v[186:189], v[50:53]
	v_mfma_f32_16x16x32_bf16 v[42:45], v[178:181], v[186:189], v[42:45]
	v_mfma_f32_16x16x32_bf16 v[34:37], v[170:173], v[194:197], v[34:37]
	v_mfma_f32_16x16x32_bf16 v[26:29], v[178:181], v[194:197], v[26:29]
	v_mfma_f32_16x16x32_bf16 v[18:21], v[170:173], v[202:205], v[18:21]
	v_mfma_f32_16x16x32_bf16 v[10:13], v[178:181], v[202:205], v[10:13]
	v_mfma_f32_16x16x32_bf16 v[6:9], v[170:173], v[210:213], v[6:9]
	v_mfma_f32_16x16x32_bf16 v[2:5], v[178:181], v[210:213], v[2:5]
	v_mfma_f32_16x16x32_bf16 v[50:53], v[174:177], v[190:193], v[50:53]
	v_mfma_f32_16x16x32_bf16 v[42:45], v[182:185], v[190:193], v[42:45]
	v_mfma_f32_16x16x32_bf16 v[34:37], v[174:177], v[198:201], v[34:37]
	v_mfma_f32_16x16x32_bf16 v[26:29], v[182:185], v[198:201], v[26:29]
	v_mfma_f32_16x16x32_bf16 v[18:21], v[174:177], v[206:209], v[18:21]
	v_mfma_f32_16x16x32_bf16 v[10:13], v[182:185], v[206:209], v[10:13]
	v_mfma_f32_16x16x32_bf16 v[6:9], v[174:177], v[214:217], v[6:9]
	v_mfma_f32_16x16x32_bf16 v[2:5], v[182:185], v[214:217], v[2:5]
	s_setprio 0
	s_barrier
	s_add_i32 s43, s43, 2
	s_add_u32 s39, s39, 0x100
	s_addc_u32 s42, s42, 0
	s_cmpk_gt_u32 s43, 0x55
	s_mov_b64 s[14:15], s[16:17]
	s_cbranch_scc0 .LBB0_448
	s_and_b64 vcc, exec, s[10:11]
	s_cbranch_vccz .LBB0_451
	s_barrier

; #define PG8_STAGE(bufoff, gbase, voff) do { _Pragma("unroll") for (int _i = 0; _i < 2; ++_i) \
;         __builtin_amdgcn_global_load_lds((const unsigned*)((const char*)(gbase) + (voff)[_i]), (PG8_LAS unsigned*)(lds + (bufoff) + ldsw + _i * 8192), 16, 0, 0); } while (0)
; #define PG8_LDA(dst, b, h) do { _Pragma("unroll") for (int m = 0; m < 4; ++m) _Pragma("unroll") for (int k = 0; k < 2; ++k) dst[m][k] = *(const PG8_LAS bf16x8*)(lds + PG8_SA(b, h) + aoff + m * 2048 + k * 1024); } while (0)
; #define PG8_LDB(dst, b, h) do { _Pragma("unroll") for (int n = 0; n < 2; ++n) _Pragma("unroll") for (int k = 0; k < 2; ++k) dst[n][k] = *(const PG8_LAS bf16x8*)(lds + PG8_SB(b, h) + boff + n * 2048 + k * 1024); } while (0)
; #define PG8_MMA(ai, bj, At, Bt) do { __builtin_amdgcn_s_setprio(1); _Pragma("unroll") for (int m = 0; m < 4; ++m) _Pragma("unroll") for (int n = 0; n < 2; ++n) _Pragma("unroll") for (int k = 0; k < 2; ++k) \
;         acc[ai][bj][m][n] = __builtin_amdgcn_mfma_f32_16x16x32_bf16(Bt[n][k], At[m][k], acc[ai][bj][m][n], 0, 0, 0); __builtin_amdgcn_s_setprio(0); } while (0)
; #define PG8_WAIT_V(n) asm volatile("s_waitcnt vmcnt(" #n ")" ::: "memory")
; #define PG8_WAIT_L(n) asm volatile("s_waitcnt lgkmcnt(" #n ")" ::: "memory")
; #define PG8_BAR __builtin_amdgcn_s_barrier()
; #define PG8_SCHED __builtin_amdgcn_sched_barrier(0)
; template <class Epi, class Sched, bool ALIGN_EPI = false, bool SP2 = false>
; __device__ __forceinline__ void gemm_phase(PG8_LAS unsigned char* lds, const Gemm g, const Sched& S, const Epi& E) {
;     ...
;             PG8_LDB(B0, 0, 0); PG8_LDB(B1, 0, 1); PG8_SCHED; PG8_LDA(At, 0, 0); PG8_STAGE(PG8_SA(1, 1), a1 + hstep, voffA);
;             PG8_WAIT_V(8); PG8_WAIT_L(0); PG8_BAR; PG8_MMA(0, 0, At, B0); PG8_MMA(0, 1, At, B1); PG8_BAR; PG8_SCHED;
;             PG8_LDA(At, 0, 1); PG8_STAGE(PG8_SB(0, 0), b2, voffB); PG8_STAGE(PG8_SB(0, 1), b2 + hstep, voffB); PG8_STAGE(PG8_SA(0, 0), a2, voffA);
.LBB0_582:
	ds_read_b128 v[158:161], v177
	ds_read_b128 v[162:165], v177 offset:1024
	ds_read_b128 v[166:169], v177 offset:2048
	ds_read_b128 v[170:173], v177 offset:3072
	ds_read_b128 v[182:185], v178
	ds_read_b128 v[186:189], v178 offset:1024
	ds_read_b128 v[190:193], v178 offset:2048
	ds_read_b128 v[194:197], v178 offset:3072
	s_add_u32 s16, s0, 0xfff80080
	s_addc_u32 s17, s1, -1
	s_cmp_eq_u32 s23, 28
	s_cselect_b32 s19, s7, s17
	s_cselect_b32 s18, s11, s16
	s_cselect_b32 s17, s15, s22
	s_cselect_b32 s16, s20, s21
	v_lshl_add_u64 v[230:231], s[0:1], 0, v[150:151]
	s_add_i32 m0, s33, 0xc000
	ds_read_b128 v[198:201], v179
	ds_read_b128 v[202:205], v179 offset:1024
	ds_read_b128 v[206:209], v179 offset:2048
	ds_read_b128 v[210:213], v179 offset:3072
	ds_read_b128 v[214:217], v179 offset:4096
	ds_read_b128 v[218:221], v179 offset:5120
	ds_read_b128 v[222:225], v179 offset:6144
	ds_read_b128 v[226:229], v179 offset:7168
	global_load_lds_dwordx4 v[230:231], off
	v_lshl_add_u64 v[230:231], s[0:1], 0, v[152:153]
	s_add_i32 m0, s33, 0xe000
	s_nop 0
	global_load_lds_dwordx4 v[230:231], off
	s_waitcnt vmcnt(8)
	s_waitcnt lgkmcnt(0)
	s_barrier
	s_setprio 1
	s_waitcnt lgkmcnt(0)
	v_mfma_f32_16x16x32_bf16 v[126:129], v[158:161], v[198:201], v[126:129]
	v_mfma_f32_16x16x32_bf16 v[122:125], v[166:169], v[198:201], v[122:125]
	v_mfma_f32_16x16x32_bf16 v[110:113], v[158:161], v[206:209], v[110:113]
	v_mfma_f32_16x16x32_bf16 v[106:109], v[166:169], v[206:209], v[106:109]
	v_mfma_f32_16x16x32_bf16 v[94:97], v[158:161], v[214:217], v[94:97]
	v_mfma_f32_16x16x32_bf16 v[90:93], v[166:169], v[214:217], v[90:93]
	v_mfma_f32_16x16x32_bf16 v[78:81], v[158:161], v[222:225], v[78:81]
	v_mfma_f32_16x16x32_bf16 v[74:77], v[166:169], v[222:225], v[74:77]
	v_mfma_f32_16x16x32_bf16 v[126:129], v[162:165], v[202:205], v[126:129]
	v_mfma_f32_16x16x32_bf16 v[122:125], v[170:173], v[202:205], v[122:125]
	v_mfma_f32_16x16x32_bf16 v[110:113], v[162:165], v[210:213], v[110:113]
	v_mfma_f32_16x16x32_bf16 v[106:109], v[170:173], v[210:213], v[106:109]
	v_mfma_f32_16x16x32_bf16 v[94:97], v[162:165], v[218:221], v[94:97]
	v_mfma_f32_16x16x32_bf16 v[90:93], v[170:173], v[218:221], v[90:93]
	v_mfma_f32_16x16x32_bf16 v[78:81], v[162:165], v[226:229], v[78:81]
	v_mfma_f32_16x16x32_bf16 v[74:77], v[170:173], v[226:229], v[74:77]
	v_mfma_f32_16x16x32_bf16 v[118:121], v[182:185], v[198:201], v[118:121]
	v_mfma_f32_16x16x32_bf16 v[114:117], v[190:193], v[198:201], v[114:117]
	v_mfma_f32_16x16x32_bf16 v[102:105], v[182:185], v[206:209], v[102:105]
	v_mfma_f32_16x16x32_bf16 v[98:101], v[190:193], v[206:209], v[98:101]
	v_mfma_f32_16x16x32_bf16 v[86:89], v[182:185], v[214:217], v[86:89]
	v_mfma_f32_16x16x32_bf16 v[82:85], v[190:193], v[214:217], v[82:85]
	v_mfma_f32_16x16x32_bf16 v[70:73], v[182:185], v[222:225], v[70:73]
	v_mfma_f32_16x16x32_bf16 v[66:69], v[190:193], v[222:225], v[66:69]
	v_mfma_f32_16x16x32_bf16 v[118:121], v[186:189], v[202:205], v[118:121]
	v_mfma_f32_16x16x32_bf16 v[114:117], v[194:197], v[202:205], v[114:117]
	v_mfma_f32_16x16x32_bf16 v[102:105], v[186:189], v[210:213], v[102:105]
	v_mfma_f32_16x16x32_bf16 v[98:101], v[194:197], v[210:213], v[98:101]
	v_mfma_f32_16x16x32_bf16 v[86:89], v[186:189], v[218:221], v[86:89]
	v_mfma_f32_16x16x32_bf16 v[82:85], v[194:197], v[218:221], v[82:85]
	v_mfma_f32_16x16x32_bf16 v[70:73], v[186:189], v[226:229], v[70:73]
	v_mfma_f32_16x16x32_bf16 v[66:69], v[194:197], v[226:229], v[66:69]
	s_setprio 0
	s_barrier
	s_add_i32 s24, s83, s2
	v_lshl_add_u64 v[230:231], s[16:17], 0, v[132:133]
	s_mov_b32 m0, s24
	ds_read_b128 v[198:201], v179 offset:16384
	ds_read_b128 v[202:205], v179 offset:17408
	ds_read_b128 v[206:209], v179 offset:18432
	ds_read_b128 v[210:213], v179 offset:19456
	ds_read_b128 v[214:217], v179 offset:20480
	ds_read_b128 v[218:221], v179 offset:21504
	ds_read_b128 v[222:225], v179 offset:22528
	ds_read_b128 v[226:229], v179 offset:23552
	global_load_lds_dwordx4 v[230:231], off
	s_add_i32 m0, s24, 0x2000
	s_add_u32 s24, s16, 0x80000
	v_lshl_add_u64 v[232:233], s[16:17], 0, v[136:137]
	s_addc_u32 s25, s17, 0
	s_add_i32 s26, s28, s2
	global_load_lds_dwordx4 v[232:233], off
	v_lshl_add_u64 v[234:235], s[24:25], 0, v[132:133]
	s_mov_b32 m0, s26
	v_lshl_add_u64 v[236:237], s[18:19], 0, v[134:135]
	global_load_lds_dwordx4 v[234:235], off
	v_lshl_add_u64 v[234:235], s[24:25], 0, v[136:137]
	s_add_i32 m0, s26, 0x2000
	s_nop 0
	global_load_lds_dwordx4 v[234:235], off
	v_lshl_add_u64 v[234:235], s[18:19], 0, v[130:131]
	s_mov_b32 m0, s33
	s_nop 0
	global_load_lds_dwordx4 v[234:235], off
	s_mov_b32 m0, s34
	s_nop 0
	global_load_lds_dwordx4 v[236:237], off
	s_waitcnt vmcnt(8)
	s_waitcnt lgkmcnt(0)
	s_barrier
; #define PG8_STAGE(bufoff, gbase, voff) do { _Pragma("unroll") for (int _i = 0; _i < 2; ++_i) \
;         __builtin_amdgcn_global_load_lds((const unsigned*)((const char*)(gbase) + (voff)[_i]), (PG8_LAS unsigned*)(lds + (bufoff) + ldsw + _i * 8192), 16, 0, 0); } while (0)
; #define PG8_LDA(dst, b, h) do { _Pragma("unroll") for (int m = 0; m < 4; ++m) _Pragma("unroll") for (int k = 0; k < 2; ++k) dst[m][k] = *(const PG8_LAS bf16x8*)(lds + PG8_SA(b, h) + aoff + m * 2048 + k * 1024); } while (0)
; #define PG8_LDB(dst, b, h) do { _Pragma("unroll") for (int n = 0; n < 2; ++n) _Pragma("unroll") for (int k = 0; k < 2; ++k) dst[n][k] = *(const PG8_LAS bf16x8*)(lds + PG8_SB(b, h) + boff + n * 2048 + k * 1024); } while (0)
; #define PG8_MMA(ai, bj, At, Bt) do { __builtin_amdgcn_s_setprio(1); _Pragma("unroll") for (int m = 0; m < 4; ++m) _Pragma("unroll") for (int n = 0; n < 2; ++n) _Pragma("unroll") for (int k = 0; k < 2; ++k) \
;         acc[ai][bj][m][n] = __builtin_amdgcn_mfma_f32_16x16x32_bf16(Bt[n][k], At[m][k], acc[ai][bj][m][n], 0, 0, 0); __builtin_amdgcn_s_setprio(0); } while (0)
; #define PG8_WAIT_V(n) asm volatile("s_waitcnt vmcnt(" #n ")" ::: "memory")
; #define PG8_WAIT_L(n) asm volatile("s_waitcnt lgkmcnt(" #n ")" ::: "memory")
; #define PG8_BAR __builtin_amdgcn_s_barrier()
; #define PG8_SCHED __builtin_amdgcn_sched_barrier(0)
; template <class Epi, class Sched, bool ALIGN_EPI = false, bool SP2 = false>
; __device__ __forceinline__ void gemm_phase(PG8_LAS unsigned char* lds, const Gemm g, const Sched& S, const Epi& E) {
;     ...
;             PG8_WAIT_V(8); PG8_WAIT_L(0); PG8_BAR; PG8_MMA(1, 0, At, B0); PG8_MMA(1, 1, At, B1); PG8_BAR; PG8_SCHED;
;             PG8_LDB(B0, 1, 0); PG8_LDB(B1, 1, 1); PG8_SCHED; PG8_LDA(At, 1, 0); PG8_STAGE(PG8_SA(0, 1), a2 + hstep, voffA);
;             PG8_WAIT_V(8); PG8_WAIT_L(0); PG8_BAR; PG8_MMA(0, 0, At, B0); PG8_MMA(0, 1, At, B1); PG8_BAR; PG8_SCHED;
	s_setprio 1
	s_waitcnt lgkmcnt(0)
	v_mfma_f32_16x16x32_bf16 v[62:65], v[158:161], v[198:201], v[62:65]
	v_mfma_f32_16x16x32_bf16 v[58:61], v[166:169], v[198:201], v[58:61]
	v_mfma_f32_16x16x32_bf16 v[46:49], v[158:161], v[206:209], v[46:49]
	v_mfma_f32_16x16x32_bf16 v[42:45], v[166:169], v[206:209], v[42:45]
	v_mfma_f32_16x16x32_bf16 v[30:33], v[158:161], v[214:217], v[30:33]
	v_mfma_f32_16x16x32_bf16 v[26:29], v[166:169], v[214:217], v[26:29]
	v_mfma_f32_16x16x32_bf16 v[14:17], v[158:161], v[222:225], v[14:17]
	v_mfma_f32_16x16x32_bf16 v[10:13], v[166:169], v[222:225], v[10:13]
	v_mfma_f32_16x16x32_bf16 v[62:65], v[162:165], v[202:205], v[62:65]
	v_mfma_f32_16x16x32_bf16 v[58:61], v[170:173], v[202:205], v[58:61]
	v_mfma_f32_16x16x32_bf16 v[46:49], v[162:165], v[210:213], v[46:49]
	v_mfma_f32_16x16x32_bf16 v[42:45], v[170:173], v[210:213], v[42:45]
	v_mfma_f32_16x16x32_bf16 v[30:33], v[162:165], v[218:221], v[30:33]
	v_mfma_f32_16x16x32_bf16 v[26:29], v[170:173], v[218:221], v[26:29]
	v_mfma_f32_16x16x32_bf16 v[14:17], v[162:165], v[226:229], v[14:17]
	v_mfma_f32_16x16x32_bf16 v[10:13], v[170:173], v[226:229], v[10:13]
	v_mfma_f32_16x16x32_bf16 v[54:57], v[182:185], v[198:201], v[54:57]
	v_mfma_f32_16x16x32_bf16 v[50:53], v[190:193], v[198:201], v[50:53]
	v_mfma_f32_16x16x32_bf16 v[38:41], v[182:185], v[206:209], v[38:41]
	v_mfma_f32_16x16x32_bf16 v[34:37], v[190:193], v[206:209], v[34:37]
	v_mfma_f32_16x16x32_bf16 v[22:25], v[182:185], v[214:217], v[22:25]
	v_mfma_f32_16x16x32_bf16 v[18:21], v[190:193], v[214:217], v[18:21]
	v_mfma_f32_16x16x32_bf16 v[6:9], v[182:185], v[222:225], v[6:9]
	v_mfma_f32_16x16x32_bf16 v[2:5], v[190:193], v[222:225], v[2:5]
	v_mfma_f32_16x16x32_bf16 v[54:57], v[186:189], v[202:205], v[54:57]
	v_mfma_f32_16x16x32_bf16 v[50:53], v[194:197], v[202:205], v[50:53]
	v_mfma_f32_16x16x32_bf16 v[38:41], v[186:189], v[210:213], v[38:41]
	v_mfma_f32_16x16x32_bf16 v[34:37], v[194:197], v[210:213], v[34:37]
	v_mfma_f32_16x16x32_bf16 v[22:25], v[186:189], v[218:221], v[22:25]
	v_mfma_f32_16x16x32_bf16 v[18:21], v[194:197], v[218:221], v[18:21]
	v_mfma_f32_16x16x32_bf16 v[6:9], v[186:189], v[226:229], v[6:9]
	v_mfma_f32_16x16x32_bf16 v[2:5], v[194:197], v[226:229], v[2:5]
	s_setprio 0
	s_barrier
	s_add_i32 s24, 0, 0x18000
	v_add_u32_e32 v138, s24, v174
	s_add_i32 s25, 0, 0x1c000
	ds_read_b128 v[158:161], v138
	ds_read_b128 v[162:165], v138 offset:1024
	ds_read_b128 v[166:169], v138 offset:2048
	ds_read_b128 v[170:173], v138 offset:3072
	v_add_u32_e32 v138, s25, v174
	ds_read_b128 v[182:185], v138
	ds_read_b128 v[186:189], v138 offset:1024
	ds_read_b128 v[190:193], v138 offset:2048
	ds_read_b128 v[194:197], v138 offset:3072
	s_add_u32 s18, s18, 0x80000
	s_addc_u32 s19, s19, 0
	s_mov_b32 m0, s35
	v_lshl_add_u64 v[238:239], s[18:19], 0, v[130:131]
	ds_read_b128 v[198:201], v179 offset:32768
	ds_read_b128 v[202:205], v179 offset:33792
	ds_read_b128 v[206:209], v179 offset:34816
	ds_read_b128 v[210:213], v179 offset:35840
	ds_read_b128 v[214:217], v179 offset:36864
	ds_read_b128 v[218:221], v179 offset:37888
	ds_read_b128 v[222:225], v179 offset:38912
	ds_read_b128 v[226:229], v179 offset:39936
	global_load_lds_dwordx4 v[238:239], off
	v_lshl_add_u64 v[238:239], s[18:19], 0, v[134:135]
	s_mov_b32 m0, s36
	s_nop 0
	global_load_lds_dwordx4 v[238:239], off
	s_waitcnt vmcnt(8)
	s_waitcnt lgkmcnt(0)
	s_barrier
	s_setprio 1
	s_waitcnt lgkmcnt(0)
	v_mfma_f32_16x16x32_bf16 v[126:129], v[158:161], v[198:201], v[126:129]
	v_mfma_f32_16x16x32_bf16 v[122:125], v[166:169], v[198:201], v[122:125]
	v_mfma_f32_16x16x32_bf16 v[110:113], v[158:161], v[206:209], v[110:113]
	v_mfma_f32_16x16x32_bf16 v[106:109], v[166:169], v[206:209], v[106:109]
	v_mfma_f32_16x16x32_bf16 v[94:97], v[158:161], v[214:217], v[94:97]
	v_mfma_f32_16x16x32_bf16 v[90:93], v[166:169], v[214:217], v[90:93]
	v_mfma_f32_16x16x32_bf16 v[78:81], v[158:161], v[222:225], v[78:81]
	v_mfma_f32_16x16x32_bf16 v[74:77], v[166:169], v[222:225], v[74:77]
	v_mfma_f32_16x16x32_bf16 v[126:129], v[162:165], v[202:205], v[126:129]
	v_mfma_f32_16x16x32_bf16 v[122:125], v[170:173], v[202:205], v[122:125]
	v_mfma_f32_16x16x32_bf16 v[110:113], v[162:165], v[210:213], v[110:113]
	v_mfma_f32_16x16x32_bf16 v[106:109], v[170:173], v[210:213], v[106:109]
	v_mfma_f32_16x16x32_bf16 v[94:97], v[162:165], v[218:221], v[94:97]
	v_mfma_f32_16x16x32_bf16 v[90:93], v[170:173], v[218:221], v[90:93]
	v_mfma_f32_16x16x32_bf16 v[78:81], v[162:165], v[226:229], v[78:81]
	v_mfma_f32_16x16x32_bf16 v[74:77], v[170:173], v[226:229], v[74:77]
	v_mfma_f32_16x16x32_bf16 v[118:121], v[182:185], v[198:201], v[118:121]
	v_mfma_f32_16x16x32_bf16 v[114:117], v[190:193], v[198:201], v[114:117]
	v_mfma_f32_16x16x32_bf16 v[102:105], v[182:185], v[206:209], v[102:105]
	v_mfma_f32_16x16x32_bf16 v[98:101], v[190:193], v[206:209], v[98:101]
	v_mfma_f32_16x16x32_bf16 v[86:89], v[182:185], v[214:217], v[86:89]
	v_mfma_f32_16x16x32_bf16 v[82:85], v[190:193], v[214:217], v[82:85]
	v_mfma_f32_16x16x32_bf16 v[70:73], v[182:185], v[222:225], v[70:73]
	v_mfma_f32_16x16x32_bf16 v[66:69], v[190:193], v[222:225], v[66:69]
	v_mfma_f32_16x16x32_bf16 v[118:121], v[186:189], v[202:205], v[118:121]
	v_mfma_f32_16x16x32_bf16 v[114:117], v[194:197], v[202:205], v[114:117]
	v_mfma_f32_16x16x32_bf16 v[102:105], v[186:189], v[210:213], v[102:105]
	v_mfma_f32_16x16x32_bf16 v[98:101], v[194:197], v[210:213], v[98:101]
	v_mfma_f32_16x16x32_bf16 v[86:89], v[186:189], v[218:221], v[86:89]
	v_mfma_f32_16x16x32_bf16 v[82:85], v[194:197], v[218:221], v[82:85]
	v_mfma_f32_16x16x32_bf16 v[70:73], v[186:189], v[226:229], v[70:73]
	v_mfma_f32_16x16x32_bf16 v[66:69], v[194:197], v[226:229], v[66:69]
	s_setprio 0
	s_barrier
; #define PG8_STAGE(bufoff, gbase, voff) do { _Pragma("unroll") for (int _i = 0; _i < 2; ++_i) \
;         __builtin_amdgcn_global_load_lds((const unsigned*)((const char*)(gbase) + (voff)[_i]), (PG8_LAS unsigned*)(lds + (bufoff) + ldsw + _i * 8192), 16, 0, 0); } while (0)
; #define PG8_LDA(dst, b, h) do { _Pragma("unroll") for (int m = 0; m < 4; ++m) _Pragma("unroll") for (int k = 0; k < 2; ++k) dst[m][k] = *(const PG8_LAS bf16x8*)(lds + PG8_SA(b, h) + aoff + m * 2048 + k * 1024); } while (0)
; #define PG8_MMA(ai, bj, At, Bt) do { __builtin_amdgcn_s_setprio(1); _Pragma("unroll") for (int m = 0; m < 4; ++m) _Pragma("unroll") for (int n = 0; n < 2; ++n) _Pragma("unroll") for (int k = 0; k < 2; ++k) \
;         acc[ai][bj][m][n] = __builtin_amdgcn_mfma_f32_16x16x32_bf16(Bt[n][k], At[m][k], acc[ai][bj][m][n], 0, 0, 0); __builtin_amdgcn_s_setprio(0); } while (0)
; #define PG8_WAIT_V(n) asm volatile("s_waitcnt vmcnt(" #n ")" ::: "memory")
; #define PG8_WAIT_L(n) asm volatile("s_waitcnt lgkmcnt(" #n ")" ::: "memory")
; #define PG8_BAR __builtin_amdgcn_s_barrier()
; #define PG8_SCHED __builtin_amdgcn_sched_barrier(0)
; template <class Epi, class Sched, bool ALIGN_EPI = false, bool SP2 = false>
; __device__ __forceinline__ void gemm_phase(PG8_LAS unsigned char* lds, const Gemm g, const Sched& S, const Epi& E) {
;     ...
;         for (int t = 0; t < nt; t += 2) {
;     ...
;             PG8_LDA(At, 1, 1); PG8_STAGE(PG8_SB(1, 0), b3, voffB); PG8_STAGE(PG8_SB(1, 1), b3 + hstep, voffB); PG8_STAGE(PG8_SA(1, 0), a3, voffA);
;             PG8_WAIT_V(8); PG8_WAIT_L(0); PG8_BAR; PG8_MMA(1, 0, At, B0); PG8_MMA(1, 1, At, B1); PG8_BAR; PG8_SCHED;
;     ...
;         if constexpr (ALIGN_EPI) { if (wr == 0) PG8_BAR; }
	s_add_i32 s18, s24, s2
	v_lshl_add_u64 v[230:231], v[230:231], 0, s[42:43]
	s_mov_b32 m0, s18
	ds_read_b128 v[198:201], v179 offset:49152
	ds_read_b128 v[202:205], v179 offset:50176
	ds_read_b128 v[206:209], v179 offset:51200
	ds_read_b128 v[210:213], v179 offset:52224
	ds_read_b128 v[214:217], v179 offset:53248
	ds_read_b128 v[218:221], v179 offset:54272
	ds_read_b128 v[222:225], v179 offset:55296
	ds_read_b128 v[226:229], v179 offset:56320
	global_load_lds_dwordx4 v[230:231], off
	s_add_i32 m0, s18, 0x2000
	s_add_u32 s16, s16, 0x80080
	v_lshl_add_u64 v[230:231], v[232:233], 0, s[42:43]
	s_addc_u32 s17, s17, 0
	s_add_i32 s18, s25, s2
	global_load_lds_dwordx4 v[230:231], off
	v_lshl_add_u64 v[230:231], s[16:17], 0, v[132:133]
	s_mov_b32 m0, s18
	s_nop 0
	global_load_lds_dwordx4 v[230:231], off
	v_lshl_add_u64 v[230:231], s[16:17], 0, v[136:137]
	s_add_i32 m0, s18, 0x2000
	s_nop 0
	global_load_lds_dwordx4 v[230:231], off
	v_lshl_add_u64 v[230:231], v[234:235], 0, s[42:43]
	s_mov_b32 m0, s3
	s_nop 0
	global_load_lds_dwordx4 v[230:231], off
	v_lshl_add_u64 v[230:231], v[236:237], 0, s[42:43]
	s_mov_b32 m0, s82
	s_nop 0
	global_load_lds_dwordx4 v[230:231], off
	s_waitcnt vmcnt(8)
	s_waitcnt lgkmcnt(0)
	s_barrier
	s_setprio 1
	s_waitcnt lgkmcnt(0)
	v_mfma_f32_16x16x32_bf16 v[62:65], v[158:161], v[198:201], v[62:65]
	v_mfma_f32_16x16x32_bf16 v[58:61], v[166:169], v[198:201], v[58:61]
	v_mfma_f32_16x16x32_bf16 v[46:49], v[158:161], v[206:209], v[46:49]
	v_mfma_f32_16x16x32_bf16 v[42:45], v[166:169], v[206:209], v[42:45]
	v_mfma_f32_16x16x32_bf16 v[30:33], v[158:161], v[214:217], v[30:33]
	v_mfma_f32_16x16x32_bf16 v[26:29], v[166:169], v[214:217], v[26:29]
	v_mfma_f32_16x16x32_bf16 v[14:17], v[158:161], v[222:225], v[14:17]
	v_mfma_f32_16x16x32_bf16 v[10:13], v[166:169], v[222:225], v[10:13]
	v_mfma_f32_16x16x32_bf16 v[62:65], v[162:165], v[202:205], v[62:65]
	v_mfma_f32_16x16x32_bf16 v[58:61], v[170:173], v[202:205], v[58:61]
	v_mfma_f32_16x16x32_bf16 v[46:49], v[162:165], v[210:213], v[46:49]
	v_mfma_f32_16x16x32_bf16 v[42:45], v[170:173], v[210:213], v[42:45]
	v_mfma_f32_16x16x32_bf16 v[30:33], v[162:165], v[218:221], v[30:33]
	v_mfma_f32_16x16x32_bf16 v[26:29], v[170:173], v[218:221], v[26:29]
	v_mfma_f32_16x16x32_bf16 v[14:17], v[162:165], v[226:229], v[14:17]
	v_mfma_f32_16x16x32_bf16 v[10:13], v[170:173], v[226:229], v[10:13]
	v_mfma_f32_16x16x32_bf16 v[54:57], v[182:185], v[198:201], v[54:57]
	v_mfma_f32_16x16x32_bf16 v[50:53], v[190:193], v[198:201], v[50:53]
	v_mfma_f32_16x16x32_bf16 v[38:41], v[182:185], v[206:209], v[38:41]
	v_mfma_f32_16x16x32_bf16 v[34:37], v[190:193], v[206:209], v[34:37]
	v_mfma_f32_16x16x32_bf16 v[22:25], v[182:185], v[214:217], v[22:25]
	v_mfma_f32_16x16x32_bf16 v[18:21], v[190:193], v[214:217], v[18:21]
	v_mfma_f32_16x16x32_bf16 v[6:9], v[182:185], v[222:225], v[6:9]
	v_mfma_f32_16x16x32_bf16 v[2:5], v[190:193], v[222:225], v[2:5]
	v_mfma_f32_16x16x32_bf16 v[54:57], v[186:189], v[202:205], v[54:57]
	v_mfma_f32_16x16x32_bf16 v[50:53], v[194:197], v[202:205], v[50:53]
	v_mfma_f32_16x16x32_bf16 v[38:41], v[186:189], v[210:213], v[38:41]
	v_mfma_f32_16x16x32_bf16 v[34:37], v[194:197], v[210:213], v[34:37]
	v_mfma_f32_16x16x32_bf16 v[22:25], v[186:189], v[218:221], v[22:25]
	v_mfma_f32_16x16x32_bf16 v[18:21], v[194:197], v[218:221], v[18:21]
	v_mfma_f32_16x16x32_bf16 v[6:9], v[186:189], v[226:229], v[6:9]
	v_mfma_f32_16x16x32_bf16 v[2:5], v[194:197], v[226:229], v[2:5]
	s_setprio 0
	s_barrier
	s_add_i32 s23, s23, 2
	s_add_u32 s0, s0, 0x100
	s_addc_u32 s1, s1, 0
	s_add_u32 s21, s21, 0x100
	s_addc_u32 s22, s22, 0
	s_cmp_gt_u32 s23, 29
	s_cbranch_scc0 .LBB0_582
	s_and_b64 vcc, exec, s[84:85]
	s_cbranch_vccz .LBB0_585
	s_barrier

; #define PG8_STAGE(bufoff, gbase, voff) do { _Pragma("unroll") for (int _i = 0; _i < 2; ++_i) \
;         __builtin_amdgcn_global_load_lds((const unsigned*)((const char*)(gbase) + (voff)[_i]), (PG8_LAS unsigned*)(lds + (bufoff) + ldsw + _i * 8192), 16, 0, 0); } while (0)
; #define PG8_LDA(dst, b, h) do { _Pragma("unroll") for (int m = 0; m < 4; ++m) _Pragma("unroll") for (int k = 0; k < 2; ++k) dst[m][k] = *(const PG8_LAS bf16x8*)(lds + PG8_SA(b, h) + aoff + m * 2048 + k * 1024); } while (0)
; #define PG8_LDB(dst, b, h) do { _Pragma("unroll") for (int n = 0; n < 2; ++n) _Pragma("unroll") for (int k = 0; k < 2; ++k) dst[n][k] = *(const PG8_LAS bf16x8*)(lds + PG8_SB(b, h) + boff + n * 2048 + k * 1024); } while (0)
; #define PG8_MMA(ai, bj, At, Bt) do { __builtin_amdgcn_s_setprio(1); _Pragma("unroll") for (int m = 0; m < 4; ++m) _Pragma("unroll") for (int n = 0; n < 2; ++n) _Pragma("unroll") for (int k = 0; k < 2; ++k) \
;         acc[ai][bj][m][n] = __builtin_amdgcn_mfma_f32_16x16x32_bf16(Bt[n][k], At[m][k], acc[ai][bj][m][n], 0, 0, 0); __builtin_amdgcn_s_setprio(0); } while (0)
; #define PG8_WAIT_V(n) asm volatile("s_waitcnt vmcnt(" #n ")" ::: "memory")
; #define PG8_WAIT_L(n) asm volatile("s_waitcnt lgkmcnt(" #n ")" ::: "memory")
; #define PG8_BAR __builtin_amdgcn_s_barrier()
; #define PG8_SCHED __builtin_amdgcn_sched_barrier(0)
; template <class Epi, class Sched, bool ALIGN_EPI = false, bool SP2 = false>
; __device__ __forceinline__ void gemm_phase(PG8_LAS unsigned char* lds, const Gemm g, const Sched& S, const Epi& E) {
;     ...
;             PG8_LDB(B0, 0, 0); PG8_LDB(B1, 0, 1); PG8_SCHED; PG8_LDA(At, 0, 0); PG8_STAGE(PG8_SA(1, 1), a1 + hstep, voffA);
;             PG8_WAIT_V(8); PG8_WAIT_L(0); PG8_BAR; PG8_MMA(0, 0, At, B0); PG8_MMA(0, 1, At, B1); PG8_BAR; PG8_SCHED;
;             PG8_LDA(At, 0, 1); PG8_STAGE(PG8_SB(0, 0), b2, voffB); PG8_STAGE(PG8_SB(0, 1), b2 + hstep, voffB); PG8_STAGE(PG8_SA(0, 0), a2, voffA);
.LBB0_1465:
	s_add_i32 s85, s84, 2
	s_add_u32 s94, s60, 0x80
	s_addc_u32 s95, s61, 0
	s_add_i32 s54, 0, 0x10000
	s_cmp_eq_u32 s52, s84
	s_cselect_b32 s95, s1, s95
	s_cselect_b32 s94, s0, s94
	s_cselect_b32 vcc_hi, s75, s63
	s_cselect_b32 vcc_lo, s74, s62
	s_add_i32 s55, 0, 0x14000
	v_add_u32_e32 v154, s54, v173
	v_add_u32_e32 v170, s55, v173
	ds_read_b128 v[130:133], v154
	ds_read_b128 v[134:137], v154 offset:1024
	ds_read_b128 v[150:153], v154 offset:2048
	ds_read_b128 v[154:157], v154 offset:3072
	ds_read_b128 v[158:161], v170
	ds_read_b128 v[162:165], v170 offset:1024
	ds_read_b128 v[166:169], v170 offset:2048
	ds_read_b128 v[188:191], v170 offset:3072
	v_lshl_add_u64 v[170:171], s[60:61], 0, v[146:147]
	s_add_i32 m0, s3, 0xc000
	ds_read_b128 v[192:195], v175
	ds_read_b128 v[196:199], v175 offset:1024
	ds_read_b128 v[200:203], v175 offset:2048
	ds_read_b128 v[204:207], v175 offset:3072
	ds_read_b128 v[208:211], v175 offset:4096
	ds_read_b128 v[212:215], v175 offset:5120
	ds_read_b128 v[216:219], v175 offset:6144
	ds_read_b128 v[220:223], v175 offset:7168
	global_load_lds_dwordx4 v[170:171], off
	v_lshl_add_u64 v[170:171], s[60:61], 0, v[148:149]
	s_add_i32 m0, s3, 0xe000
	s_nop 0
	global_load_lds_dwordx4 v[170:171], off
	s_waitcnt vmcnt(8)
	s_waitcnt lgkmcnt(0)
	s_barrier
	s_setprio 1
	s_waitcnt lgkmcnt(0)
	v_mfma_f32_16x16x32_bf16 v[126:129], v[130:133], v[192:195], v[126:129]
	v_mfma_f32_16x16x32_bf16 v[94:97], v[150:153], v[192:195], v[94:97]
	v_mfma_f32_16x16x32_bf16 v[122:125], v[130:133], v[200:203], v[122:125]
	v_mfma_f32_16x16x32_bf16 v[90:93], v[150:153], v[200:203], v[90:93]
	v_mfma_f32_16x16x32_bf16 v[118:121], v[130:133], v[208:211], v[118:121]
	v_mfma_f32_16x16x32_bf16 v[86:89], v[150:153], v[208:211], v[86:89]
	v_mfma_f32_16x16x32_bf16 v[114:117], v[130:133], v[216:219], v[114:117]
	v_mfma_f32_16x16x32_bf16 v[82:85], v[150:153], v[216:219], v[82:85]
	v_mfma_f32_16x16x32_bf16 v[126:129], v[134:137], v[196:199], v[126:129]
	v_mfma_f32_16x16x32_bf16 v[94:97], v[154:157], v[196:199], v[94:97]
	v_mfma_f32_16x16x32_bf16 v[122:125], v[134:137], v[204:207], v[122:125]
	v_mfma_f32_16x16x32_bf16 v[90:93], v[154:157], v[204:207], v[90:93]
	v_mfma_f32_16x16x32_bf16 v[118:121], v[134:137], v[212:215], v[118:121]
	v_mfma_f32_16x16x32_bf16 v[86:89], v[154:157], v[212:215], v[86:89]
	v_mfma_f32_16x16x32_bf16 v[114:117], v[134:137], v[220:223], v[114:117]
	v_mfma_f32_16x16x32_bf16 v[82:85], v[154:157], v[220:223], v[82:85]
	v_mfma_f32_16x16x32_bf16 v[62:65], v[158:161], v[192:195], v[62:65]
	v_mfma_f32_16x16x32_bf16 v[30:33], v[166:169], v[192:195], v[30:33]
	v_mfma_f32_16x16x32_bf16 v[58:61], v[158:161], v[200:203], v[58:61]
	v_mfma_f32_16x16x32_bf16 v[26:29], v[166:169], v[200:203], v[26:29]
	v_mfma_f32_16x16x32_bf16 v[54:57], v[158:161], v[208:211], v[54:57]
	v_mfma_f32_16x16x32_bf16 v[22:25], v[166:169], v[208:211], v[22:25]
	v_mfma_f32_16x16x32_bf16 v[50:53], v[158:161], v[216:219], v[50:53]
	v_mfma_f32_16x16x32_bf16 v[18:21], v[166:169], v[216:219], v[18:21]
	v_mfma_f32_16x16x32_bf16 v[62:65], v[162:165], v[196:199], v[62:65]
	v_mfma_f32_16x16x32_bf16 v[30:33], v[188:191], v[196:199], v[30:33]
	v_mfma_f32_16x16x32_bf16 v[58:61], v[162:165], v[204:207], v[58:61]
	v_mfma_f32_16x16x32_bf16 v[26:29], v[188:191], v[204:207], v[26:29]
	v_mfma_f32_16x16x32_bf16 v[54:57], v[162:165], v[212:215], v[54:57]
	v_mfma_f32_16x16x32_bf16 v[22:25], v[188:191], v[212:215], v[22:25]
	v_mfma_f32_16x16x32_bf16 v[50:53], v[162:165], v[220:223], v[50:53]
	v_mfma_f32_16x16x32_bf16 v[18:21], v[188:191], v[220:223], v[18:21]
	s_setprio 0
	s_barrier
	s_add_i32 s54, s54, s2
	v_lshl_add_u64 v[170:171], vcc, 0, v[142:143]
	s_mov_b32 m0, s54
	ds_read_b128 v[192:195], v175 offset:16384
	ds_read_b128 v[196:199], v175 offset:17408
	ds_read_b128 v[200:203], v175 offset:18432
	ds_read_b128 v[204:207], v175 offset:19456
	ds_read_b128 v[208:211], v175 offset:20480
	ds_read_b128 v[212:215], v175 offset:21504
	ds_read_b128 v[216:219], v175 offset:22528
	ds_read_b128 v[220:223], v175 offset:23552
	global_load_lds_dwordx4 v[170:171], off
	s_add_i32 m0, s54, 0x2000
	v_lshl_add_u64 v[176:177], vcc, 0, v[138:139]
	s_add_u32 vcc_lo, vcc_lo, s10
	s_addc_u32 vcc_hi, vcc_hi, s11
	s_add_i32 s54, s55, s2
	global_load_lds_dwordx4 v[176:177], off
	v_lshl_add_u64 v[224:225], vcc, 0, v[142:143]
	s_mov_b32 m0, s54
	v_lshl_add_u64 v[226:227], vcc, 0, v[138:139]
	global_load_lds_dwordx4 v[224:225], off
	s_add_i32 m0, s54, 0x2000
	v_lshl_add_u64 v[228:229], s[94:95], 0, v[144:145]
	global_load_lds_dwordx4 v[226:227], off
	s_mov_b32 m0, s3
	v_lshl_add_u64 v[230:231], s[94:95], 0, v[140:141]
	global_load_lds_dwordx4 v[228:229], off
	s_mov_b32 m0, s4
	s_nop 0
	global_load_lds_dwordx4 v[230:231], off
	s_waitcnt vmcnt(8)
	s_waitcnt lgkmcnt(0)
	s_barrier
; #define PG8_STAGE(bufoff, gbase, voff) do { _Pragma("unroll") for (int _i = 0; _i < 2; ++_i) \
;         __builtin_amdgcn_global_load_lds((const unsigned*)((const char*)(gbase) + (voff)[_i]), (PG8_LAS unsigned*)(lds + (bufoff) + ldsw + _i * 8192), 16, 0, 0); } while (0)
; #define PG8_LDA(dst, b, h) do { _Pragma("unroll") for (int m = 0; m < 4; ++m) _Pragma("unroll") for (int k = 0; k < 2; ++k) dst[m][k] = *(const PG8_LAS bf16x8*)(lds + PG8_SA(b, h) + aoff + m * 2048 + k * 1024); } while (0)
; #define PG8_LDB(dst, b, h) do { _Pragma("unroll") for (int n = 0; n < 2; ++n) _Pragma("unroll") for (int k = 0; k < 2; ++k) dst[n][k] = *(const PG8_LAS bf16x8*)(lds + PG8_SB(b, h) + boff + n * 2048 + k * 1024); } while (0)
; #define PG8_MMA(ai, bj, At, Bt) do { __builtin_amdgcn_s_setprio(1); _Pragma("unroll") for (int m = 0; m < 4; ++m) _Pragma("unroll") for (int n = 0; n < 2; ++n) _Pragma("unroll") for (int k = 0; k < 2; ++k) \
;         acc[ai][bj][m][n] = __builtin_amdgcn_mfma_f32_16x16x32_bf16(Bt[n][k], At[m][k], acc[ai][bj][m][n], 0, 0, 0); __builtin_amdgcn_s_setprio(0); } while (0)
; #define PG8_WAIT_V(n) asm volatile("s_waitcnt vmcnt(" #n ")" ::: "memory")
; #define PG8_WAIT_L(n) asm volatile("s_waitcnt lgkmcnt(" #n ")" ::: "memory")
; #define PG8_BAR __builtin_amdgcn_s_barrier()
; #define PG8_SCHED __builtin_amdgcn_sched_barrier(0)
; template <class Epi, class Sched, bool ALIGN_EPI = false, bool SP2 = false>
; __device__ __forceinline__ void gemm_phase(PG8_LAS unsigned char* lds, const Gemm g, const Sched& S, const Epi& E) {
;     ...
;             PG8_WAIT_V(8); PG8_WAIT_L(0); PG8_BAR; PG8_MMA(1, 0, At, B0); PG8_MMA(1, 1, At, B1); PG8_BAR; PG8_SCHED;
;             PG8_LDB(B0, 1, 0); PG8_LDB(B1, 1, 1); PG8_SCHED; PG8_LDA(At, 1, 0); PG8_STAGE(PG8_SA(0, 1), a2 + hstep, voffA);
;             PG8_WAIT_V(8); PG8_WAIT_L(0); PG8_BAR; PG8_MMA(0, 0, At, B0); PG8_MMA(0, 1, At, B1); PG8_BAR; PG8_SCHED;
	s_setprio 1
	s_waitcnt lgkmcnt(0)
	v_mfma_f32_16x16x32_bf16 v[110:113], v[130:133], v[192:195], v[110:113]
	v_mfma_f32_16x16x32_bf16 v[78:81], v[150:153], v[192:195], v[78:81]
	v_mfma_f32_16x16x32_bf16 v[106:109], v[130:133], v[200:203], v[106:109]
	v_mfma_f32_16x16x32_bf16 v[74:77], v[150:153], v[200:203], v[74:77]
	v_mfma_f32_16x16x32_bf16 v[102:105], v[130:133], v[208:211], v[102:105]
	v_mfma_f32_16x16x32_bf16 v[70:73], v[150:153], v[208:211], v[70:73]
	v_mfma_f32_16x16x32_bf16 v[98:101], v[130:133], v[216:219], v[98:101]
	v_mfma_f32_16x16x32_bf16 v[66:69], v[150:153], v[216:219], v[66:69]
	v_mfma_f32_16x16x32_bf16 v[110:113], v[134:137], v[196:199], v[110:113]
	v_mfma_f32_16x16x32_bf16 v[78:81], v[154:157], v[196:199], v[78:81]
	v_mfma_f32_16x16x32_bf16 v[106:109], v[134:137], v[204:207], v[106:109]
	v_mfma_f32_16x16x32_bf16 v[74:77], v[154:157], v[204:207], v[74:77]
	v_mfma_f32_16x16x32_bf16 v[102:105], v[134:137], v[212:215], v[102:105]
	v_mfma_f32_16x16x32_bf16 v[70:73], v[154:157], v[212:215], v[70:73]
	v_mfma_f32_16x16x32_bf16 v[98:101], v[134:137], v[220:223], v[98:101]
	v_mfma_f32_16x16x32_bf16 v[66:69], v[154:157], v[220:223], v[66:69]
	v_mfma_f32_16x16x32_bf16 v[46:49], v[158:161], v[192:195], v[46:49]
	v_mfma_f32_16x16x32_bf16 v[14:17], v[166:169], v[192:195], v[14:17]
	v_mfma_f32_16x16x32_bf16 v[42:45], v[158:161], v[200:203], v[42:45]
	v_mfma_f32_16x16x32_bf16 v[10:13], v[166:169], v[200:203], v[10:13]
	v_mfma_f32_16x16x32_bf16 v[38:41], v[158:161], v[208:211], v[38:41]
	v_mfma_f32_16x16x32_bf16 v[6:9], v[166:169], v[208:211], v[6:9]
	v_mfma_f32_16x16x32_bf16 v[34:37], v[158:161], v[216:219], v[34:37]
	v_mfma_f32_16x16x32_bf16 v[2:5], v[166:169], v[216:219], v[2:5]
	v_mfma_f32_16x16x32_bf16 v[46:49], v[162:165], v[196:199], v[46:49]
	v_mfma_f32_16x16x32_bf16 v[14:17], v[188:191], v[196:199], v[14:17]
	v_mfma_f32_16x16x32_bf16 v[42:45], v[162:165], v[204:207], v[42:45]
	v_mfma_f32_16x16x32_bf16 v[10:13], v[188:191], v[204:207], v[10:13]
	v_mfma_f32_16x16x32_bf16 v[38:41], v[162:165], v[212:215], v[38:41]
	v_mfma_f32_16x16x32_bf16 v[6:9], v[188:191], v[212:215], v[6:9]
	v_mfma_f32_16x16x32_bf16 v[34:37], v[162:165], v[220:223], v[34:37]
	v_mfma_f32_16x16x32_bf16 v[2:5], v[188:191], v[220:223], v[2:5]
	s_setprio 0
	s_barrier
	s_add_i32 s54, 0, 0x18000
	s_add_i32 s55, 0, 0x1c000
	v_add_u32_e32 v154, s54, v173
	v_add_u32_e32 v180, s55, v173
	ds_read_b128 v[130:133], v154
	ds_read_b128 v[134:137], v154 offset:1024
	ds_read_b128 v[150:153], v154 offset:2048
	ds_read_b128 v[154:157], v154 offset:3072
	ds_read_b128 v[158:161], v180
	ds_read_b128 v[162:165], v180 offset:1024
	ds_read_b128 v[166:169], v180 offset:2048
	ds_read_b128 v[188:191], v180 offset:3072
	s_add_u32 s94, s94, s10
	s_addc_u32 s95, s95, s11
	s_mov_b32 m0, s5
	v_lshl_add_u64 v[232:233], s[94:95], 0, v[144:145]
	ds_read_b128 v[192:195], v175 offset:32768
	ds_read_b128 v[196:199], v175 offset:33792
	ds_read_b128 v[200:203], v175 offset:34816
	ds_read_b128 v[204:207], v175 offset:35840
	ds_read_b128 v[208:211], v175 offset:36864
	ds_read_b128 v[212:215], v175 offset:37888
	ds_read_b128 v[216:219], v175 offset:38912
	ds_read_b128 v[220:223], v175 offset:39936
	global_load_lds_dwordx4 v[232:233], off
	v_lshl_add_u64 v[232:233], s[94:95], 0, v[140:141]
	s_mov_b32 m0, s19
	s_nop 0
	global_load_lds_dwordx4 v[232:233], off
	s_waitcnt vmcnt(8)
	s_waitcnt lgkmcnt(0)
	s_barrier
	s_setprio 1
	s_waitcnt lgkmcnt(0)
	v_mfma_f32_16x16x32_bf16 v[126:129], v[130:133], v[192:195], v[126:129]
	v_mfma_f32_16x16x32_bf16 v[94:97], v[150:153], v[192:195], v[94:97]
	v_mfma_f32_16x16x32_bf16 v[122:125], v[130:133], v[200:203], v[122:125]
	v_mfma_f32_16x16x32_bf16 v[90:93], v[150:153], v[200:203], v[90:93]
	v_mfma_f32_16x16x32_bf16 v[118:121], v[130:133], v[208:211], v[118:121]
	v_mfma_f32_16x16x32_bf16 v[86:89], v[150:153], v[208:211], v[86:89]
	v_mfma_f32_16x16x32_bf16 v[114:117], v[130:133], v[216:219], v[114:117]
	v_mfma_f32_16x16x32_bf16 v[82:85], v[150:153], v[216:219], v[82:85]
	v_mfma_f32_16x16x32_bf16 v[126:129], v[134:137], v[196:199], v[126:129]
	v_mfma_f32_16x16x32_bf16 v[94:97], v[154:157], v[196:199], v[94:97]
	v_mfma_f32_16x16x32_bf16 v[122:125], v[134:137], v[204:207], v[122:125]
	v_mfma_f32_16x16x32_bf16 v[90:93], v[154:157], v[204:207], v[90:93]
	v_mfma_f32_16x16x32_bf16 v[118:121], v[134:137], v[212:215], v[118:121]
	v_mfma_f32_16x16x32_bf16 v[86:89], v[154:157], v[212:215], v[86:89]
	v_mfma_f32_16x16x32_bf16 v[114:117], v[134:137], v[220:223], v[114:117]
	v_mfma_f32_16x16x32_bf16 v[82:85], v[154:157], v[220:223], v[82:85]
	v_mfma_f32_16x16x32_bf16 v[62:65], v[158:161], v[192:195], v[62:65]
	v_mfma_f32_16x16x32_bf16 v[30:33], v[166:169], v[192:195], v[30:33]
	v_mfma_f32_16x16x32_bf16 v[58:61], v[158:161], v[200:203], v[58:61]
	v_mfma_f32_16x16x32_bf16 v[26:29], v[166:169], v[200:203], v[26:29]
	v_mfma_f32_16x16x32_bf16 v[54:57], v[158:161], v[208:211], v[54:57]
	v_mfma_f32_16x16x32_bf16 v[22:25], v[166:169], v[208:211], v[22:25]
	v_mfma_f32_16x16x32_bf16 v[50:53], v[158:161], v[216:219], v[50:53]
	v_mfma_f32_16x16x32_bf16 v[18:21], v[166:169], v[216:219], v[18:21]
	v_mfma_f32_16x16x32_bf16 v[62:65], v[162:165], v[196:199], v[62:65]
	v_mfma_f32_16x16x32_bf16 v[30:33], v[188:191], v[196:199], v[30:33]
	v_mfma_f32_16x16x32_bf16 v[58:61], v[162:165], v[204:207], v[58:61]
	v_mfma_f32_16x16x32_bf16 v[26:29], v[188:191], v[204:207], v[26:29]
	v_mfma_f32_16x16x32_bf16 v[54:57], v[162:165], v[212:215], v[54:57]
	v_mfma_f32_16x16x32_bf16 v[22:25], v[188:191], v[212:215], v[22:25]
	v_mfma_f32_16x16x32_bf16 v[50:53], v[162:165], v[220:223], v[50:53]
	v_mfma_f32_16x16x32_bf16 v[18:21], v[188:191], v[220:223], v[18:21]
	s_setprio 0
	s_barrier
; #define PG8_STAGE(bufoff, gbase, voff) do { _Pragma("unroll") for (int _i = 0; _i < 2; ++_i) \
;         __builtin_amdgcn_global_load_lds((const unsigned*)((const char*)(gbase) + (voff)[_i]), (PG8_LAS unsigned*)(lds + (bufoff) + ldsw + _i * 8192), 16, 0, 0); } while (0)
; #define PG8_LDA(dst, b, h) do { _Pragma("unroll") for (int m = 0; m < 4; ++m) _Pragma("unroll") for (int k = 0; k < 2; ++k) dst[m][k] = *(const PG8_LAS bf16x8*)(lds + PG8_SA(b, h) + aoff + m * 2048 + k * 1024); } while (0)
; #define PG8_MMA(ai, bj, At, Bt) do { __builtin_amdgcn_s_setprio(1); _Pragma("unroll") for (int m = 0; m < 4; ++m) _Pragma("unroll") for (int n = 0; n < 2; ++n) _Pragma("unroll") for (int k = 0; k < 2; ++k) \
;         acc[ai][bj][m][n] = __builtin_amdgcn_mfma_f32_16x16x32_bf16(Bt[n][k], At[m][k], acc[ai][bj][m][n], 0, 0, 0); __builtin_amdgcn_s_setprio(0); } while (0)
; #define PG8_WAIT_V(n) asm volatile("s_waitcnt vmcnt(" #n ")" ::: "memory")
; #define PG8_WAIT_L(n) asm volatile("s_waitcnt lgkmcnt(" #n ")" ::: "memory")
; #define PG8_BAR __builtin_amdgcn_s_barrier()
; #define PG8_SCHED __builtin_amdgcn_sched_barrier(0)
; template <class Epi, class Sched, bool ALIGN_EPI = false, bool SP2 = false>
; __device__ __forceinline__ void gemm_phase(PG8_LAS unsigned char* lds, const Gemm g, const Sched& S, const Epi& E) {
;     ...
;         for (int t = 0; t < nt; t += 2) {
;     ...
;             PG8_LDA(At, 1, 1); PG8_STAGE(PG8_SB(1, 0), b3, voffB); PG8_STAGE(PG8_SB(1, 1), b3 + hstep, voffB); PG8_STAGE(PG8_SA(1, 0), a3, voffA);
;             PG8_WAIT_V(8); PG8_WAIT_L(0); PG8_BAR; PG8_MMA(1, 0, At, B0); PG8_MMA(1, 1, At, B1); PG8_BAR; PG8_SCHED;
	s_add_i32 s54, s54, s2
	v_lshl_add_u64 v[170:171], v[170:171], 0, s[42:43]
	s_mov_b32 m0, s54
	ds_read_b128 v[192:195], v175 offset:49152
	ds_read_b128 v[196:199], v175 offset:50176
	ds_read_b128 v[200:203], v175 offset:51200
	ds_read_b128 v[204:207], v175 offset:52224
	ds_read_b128 v[208:211], v175 offset:53248
	ds_read_b128 v[212:215], v175 offset:54272
	ds_read_b128 v[216:219], v175 offset:55296
	ds_read_b128 v[220:223], v175 offset:56320
	global_load_lds_dwordx4 v[170:171], off
	v_lshl_add_u64 v[170:171], v[176:177], 0, s[42:43]
	s_add_i32 m0, s54, 0x2000
	s_add_i32 s54, s55, s2
	global_load_lds_dwordx4 v[170:171], off
	v_lshl_add_u64 v[170:171], v[224:225], 0, s[42:43]
	s_mov_b32 m0, s54
	s_nop 0
	global_load_lds_dwordx4 v[170:171], off
	v_lshl_add_u64 v[170:171], v[226:227], 0, s[42:43]
	s_add_i32 m0, s54, 0x2000
	s_nop 0
	global_load_lds_dwordx4 v[170:171], off
	v_lshl_add_u64 v[170:171], v[228:229], 0, s[42:43]
	s_mov_b32 m0, s26
	s_nop 0
	global_load_lds_dwordx4 v[170:171], off
	v_lshl_add_u64 v[170:171], v[230:231], 0, s[42:43]
	s_mov_b32 m0, s45
	s_nop 0
	global_load_lds_dwordx4 v[170:171], off
	s_waitcnt vmcnt(8)
	s_waitcnt lgkmcnt(0)
	s_barrier
	s_setprio 1
	s_waitcnt lgkmcnt(0)
	v_mfma_f32_16x16x32_bf16 v[110:113], v[130:133], v[192:195], v[110:113]
	v_mfma_f32_16x16x32_bf16 v[78:81], v[150:153], v[192:195], v[78:81]
	v_mfma_f32_16x16x32_bf16 v[106:109], v[130:133], v[200:203], v[106:109]
	v_mfma_f32_16x16x32_bf16 v[74:77], v[150:153], v[200:203], v[74:77]
	v_mfma_f32_16x16x32_bf16 v[102:105], v[130:133], v[208:211], v[102:105]
	v_mfma_f32_16x16x32_bf16 v[70:73], v[150:153], v[208:211], v[70:73]
	v_mfma_f32_16x16x32_bf16 v[98:101], v[130:133], v[216:219], v[98:101]
	v_mfma_f32_16x16x32_bf16 v[66:69], v[150:153], v[216:219], v[66:69]
	v_mfma_f32_16x16x32_bf16 v[110:113], v[134:137], v[196:199], v[110:113]
	v_mfma_f32_16x16x32_bf16 v[78:81], v[154:157], v[196:199], v[78:81]
	v_mfma_f32_16x16x32_bf16 v[106:109], v[134:137], v[204:207], v[106:109]
	v_mfma_f32_16x16x32_bf16 v[74:77], v[154:157], v[204:207], v[74:77]
	v_mfma_f32_16x16x32_bf16 v[102:105], v[134:137], v[212:215], v[102:105]
	v_mfma_f32_16x16x32_bf16 v[70:73], v[154:157], v[212:215], v[70:73]
	v_mfma_f32_16x16x32_bf16 v[98:101], v[134:137], v[220:223], v[98:101]
	v_mfma_f32_16x16x32_bf16 v[66:69], v[154:157], v[220:223], v[66:69]
	v_mfma_f32_16x16x32_bf16 v[46:49], v[158:161], v[192:195], v[46:49]
	v_mfma_f32_16x16x32_bf16 v[14:17], v[166:169], v[192:195], v[14:17]
	v_mfma_f32_16x16x32_bf16 v[42:45], v[158:161], v[200:203], v[42:45]
	v_mfma_f32_16x16x32_bf16 v[10:13], v[166:169], v[200:203], v[10:13]
	v_mfma_f32_16x16x32_bf16 v[38:41], v[158:161], v[208:211], v[38:41]
	v_mfma_f32_16x16x32_bf16 v[6:9], v[166:169], v[208:211], v[6:9]
	v_mfma_f32_16x16x32_bf16 v[34:37], v[158:161], v[216:219], v[34:37]
	v_mfma_f32_16x16x32_bf16 v[2:5], v[166:169], v[216:219], v[2:5]
	v_mfma_f32_16x16x32_bf16 v[46:49], v[162:165], v[196:199], v[46:49]
	v_mfma_f32_16x16x32_bf16 v[14:17], v[188:191], v[196:199], v[14:17]
	v_mfma_f32_16x16x32_bf16 v[42:45], v[162:165], v[204:207], v[42:45]
	v_mfma_f32_16x16x32_bf16 v[10:13], v[188:191], v[204:207], v[10:13]
	v_mfma_f32_16x16x32_bf16 v[38:41], v[162:165], v[212:215], v[38:41]
	v_mfma_f32_16x16x32_bf16 v[6:9], v[188:191], v[212:215], v[6:9]
	v_mfma_f32_16x16x32_bf16 v[34:37], v[162:165], v[220:223], v[34:37]
	v_mfma_f32_16x16x32_bf16 v[2:5], v[188:191], v[220:223], v[2:5]
	s_setprio 0
	s_barrier
	s_add_u32 s60, s60, 0x100
	s_addc_u32 s61, s61, 0
	s_add_u32 s62, s62, 0x100
	s_addc_u32 s63, s63, 0
	s_cmp_ge_i32 s85, s9
	s_mov_b32 s84, s85
	s_cbranch_scc0 .LBB0_1465

; #define PG8_STAGE(bufoff, gbase, voff) do { _Pragma("unroll") for (int _i = 0; _i < 2; ++_i) \
;         __builtin_amdgcn_global_load_lds((const unsigned*)((const char*)(gbase) + (voff)[_i]), (PG8_LAS unsigned*)(lds + (bufoff) + ldsw + _i * 8192), 16, 0, 0); } while (0)
; #define PG8_LDA(dst, b, h) do { _Pragma("unroll") for (int m = 0; m < 4; ++m) _Pragma("unroll") for (int k = 0; k < 2; ++k) dst[m][k] = *(const PG8_LAS bf16x8*)(lds + PG8_SA(b, h) + aoff + m * 2048 + k * 1024); } while (0)
; #define PG8_LDB(dst, b, h) do { _Pragma("unroll") for (int n = 0; n < 2; ++n) _Pragma("unroll") for (int k = 0; k < 2; ++k) dst[n][k] = *(const PG8_LAS bf16x8*)(lds + PG8_SB(b, h) + boff + n * 2048 + k * 1024); } while (0)
; #define PG8_MMA(ai, bj, At, Bt) do { __builtin_amdgcn_s_setprio(1); _Pragma("unroll") for (int m = 0; m < 4; ++m) _Pragma("unroll") for (int n = 0; n < 2; ++n) _Pragma("unroll") for (int k = 0; k < 2; ++k) \
;         acc[ai][bj][m][n] = __builtin_amdgcn_mfma_f32_16x16x32_bf16(Bt[n][k], At[m][k], acc[ai][bj][m][n], 0, 0, 0); __builtin_amdgcn_s_setprio(0); } while (0)
; #define PG8_WAIT_V(n) asm volatile("s_waitcnt vmcnt(" #n ")" ::: "memory")
; template <class Epi, class Sched, bool ALIGN_EPI = false, bool SP2 = false>
; __device__ __forceinline__ void gemm_phase(PG8_LAS unsigned char* lds, const Gemm g, const Sched& S, const Epi& E) {
;     ...
;             PG8_LDB(B0, 0, 0); PG8_LDB(B1, 0, 1); PG8_SCHED; PG8_LDA(At, 0, 0); PG8_STAGE(PG8_SA(1, 1), a1 + hstep, voffA);
;             PG8_WAIT_V(8); PG8_WAIT_L(0); PG8_BAR; PG8_MMA(0, 0, At, B0); PG8_MMA(0, 1, At, B1); PG8_BAR; PG8_SCHED;
;             PG8_LDA(At, 0, 1); PG8_STAGE(PG8_SB(0, 0), b2, voffB); PG8_STAGE(PG8_SB(0, 1), b2 + hstep, voffB); PG8_STAGE(PG8_SA(0, 0), a2, voffA);
;             PG8_WAIT_V(8); PG8_WAIT_L(0); PG8_BAR; PG8_MMA(1, 0, At, B0); PG8_MMA(1, 1, At, B1); PG8_BAR; PG8_SCHED;
;             PG8_LDB(B0, 1, 0); PG8_LDB(B1, 1, 1); PG8_SCHED; PG8_LDA(At, 1, 0); PG8_STAGE(PG8_SA(0, 1), a2 + hstep, voffA);
;             PG8_WAIT_V(8); PG8_WAIT_L(0); PG8_BAR; PG8_MMA(0, 0, At, B0); PG8_MMA(0, 1, At, B1); PG8_BAR; PG8_SCHED;
;             PG8_LDA(At, 1, 1); PG8_STAGE(PG8_SB(1, 0), b3, voffB); PG8_STAGE(PG8_SB(1, 1), b3 + hstep, voffB); PG8_STAGE(PG8_SA(1, 0), a3, voffA);
;             PG8_WAIT_V(8); PG8_WAIT_L(0); PG8_BAR; PG8_MMA(1, 0, At, B0); PG8_MMA(1, 1, At, B1); PG8_BAR; PG8_SCHED;
.LBB0_1574:
	s_cmpk_gt_i32 s45, 0x43
	s_mov_b64 s[30:31], s[6:7]
	s_cselect_b64 s[6:7], -1, 0
	s_cmpk_lt_i32 s45, 0x88
	s_mov_b64 s[28:29], s[8:9]
	s_cselect_b64 s[8:9], -1, 0
	v_cndmask_b32_e64 v2, 0, 1, s[6:7]
	s_mov_b32 s22, s58
	s_and_b64 s[6:7], s[8:9], exec
	v_readfirstlane_b32 s58, v2
	s_cselect_b32 s6, s58, s22
	s_ashr_i32 s7, s6, 31
	s_lshl_b64 s[6:7], s[6:7], 17
	s_add_u32 s6, s3, s6
	s_addc_u32 s7, s4, s7
	s_cmpk_lt_i32 s45, 0x88
	s_cselect_b64 s[8:9], -1, 0
	s_and_b64 s[8:9], s[8:9], exec
	s_cselect_b32 s8, s45, s59
	s_cselect_b32 s24, s6, s30
	s_cselect_b32 s25, s7, s31
	s_ashr_i32 s9, s8, 31
	ds_read_b128 v[2:5], v78
	ds_read_b128 v[6:9], v78 offset:1024
	ds_read_b128 v[10:13], v78 offset:2048
	ds_read_b128 v[14:17], v78 offset:3072
	s_lshl_b64 s[8:9], s[8:9], 17
	s_add_u32 s8, s38, s8
	s_addc_u32 s9, s39, s9
	s_cmpk_lt_i32 s45, 0x88
	s_cselect_b64 s[22:23], -1, 0
	s_and_b64 s[26:27], s[22:23], exec
	s_cselect_b32 s27, s9, s29
	s_cselect_b32 s26, s8, s28
	s_add_u32 s60, s28, 0x10080
	s_addc_u32 s61, s29, 0
	s_mov_b32 m0, s52
	v_lshl_add_u64 v[50:51], s[60:61], 0, v[72:73]
	ds_read_b128 v[18:21], v79
	ds_read_b128 v[22:25], v79 offset:1024
	ds_read_b128 v[26:29], v79 offset:2048
	ds_read_b128 v[30:33], v79 offset:3072
	ds_read_b128 v[34:37], v79 offset:4096
	ds_read_b128 v[38:41], v79 offset:5120
	ds_read_b128 v[42:45], v79 offset:6144
	ds_read_b128 v[46:49], v79 offset:7168
	global_load_lds_dwordx4 v[50:51], off
	v_lshl_add_u64 v[50:51], s[60:61], 0, v[68:69]
	s_mov_b32 m0, s53
	s_nop 0
	global_load_lds_dwordx4 v[50:51], off
	s_waitcnt vmcnt(8)
	s_waitcnt lgkmcnt(0)
	s_barrier
	s_setprio 1
	s_waitcnt lgkmcnt(0)
	v_mfma_f32_16x16x32_bf16 v[50:53], v[2:5], v[18:21], 0
	v_mfma_f32_16x16x32_bf16 v[18:21], v[10:13], v[18:21], 0
	v_mfma_f32_16x16x32_bf16 v[50:53], v[6:9], v[22:25], v[50:53]
	v_mfma_f32_16x16x32_bf16 v[18:21], v[14:17], v[22:25], v[18:21]
	v_mfma_f32_16x16x32_bf16 v[22:25], v[2:5], v[26:29], 0
	v_mfma_f32_16x16x32_bf16 v[26:29], v[10:13], v[26:29], 0
	v_mfma_f32_16x16x32_bf16 v[22:25], v[6:9], v[30:33], v[22:25]
	v_mfma_f32_16x16x32_bf16 v[26:29], v[14:17], v[30:33], v[26:29]
	v_mfma_f32_16x16x32_bf16 v[30:33], v[2:5], v[34:37], 0
	v_mfma_f32_16x16x32_bf16 v[34:37], v[10:13], v[34:37], 0
	v_mfma_f32_16x16x32_bf16 v[30:33], v[6:9], v[38:41], v[30:33]
	v_mfma_f32_16x16x32_bf16 v[34:37], v[14:17], v[38:41], v[34:37]
	v_mfma_f32_16x16x32_bf16 v[38:41], v[2:5], v[42:45], 0
	v_mfma_f32_16x16x32_bf16 v[42:45], v[10:13], v[42:45], 0
	v_mfma_f32_16x16x32_bf16 v[38:41], v[6:9], v[46:49], v[38:41]
	v_mfma_f32_16x16x32_bf16 v[42:45], v[14:17], v[46:49], v[42:45]
	s_setprio 0
	s_barrier
	v_lshl_add_u64 v[130:131], s[30:31], 0, v[70:71]
	s_mov_b32 m0, s54
	v_lshl_add_u64 v[98:99], v[130:131], 0, s[18:19]
	v_lshl_add_u64 v[132:133], s[30:31], 0, v[66:67]
	s_add_u32 s60, s30, 0x10100
	ds_read_b128 v[46:49], v79 offset:16384
	ds_read_b128 v[54:57], v79 offset:17408
	ds_read_b128 v[58:61], v79 offset:18432
	ds_read_b128 v[62:65], v79 offset:19456
	ds_read_b128 v[82:85], v79 offset:20480
	ds_read_b128 v[86:89], v79 offset:21504
	ds_read_b128 v[90:93], v79 offset:22528
	ds_read_b128 v[94:97], v79 offset:23552
	global_load_lds_dwordx4 v[98:99], off
	v_lshl_add_u64 v[98:99], v[132:133], 0, s[18:19]
	s_mov_b32 m0, s55
	s_addc_u32 s61, s31, 0
	global_load_lds_dwordx4 v[98:99], off
	v_lshl_add_u64 v[98:99], s[60:61], 0, v[70:71]
	s_mov_b32 m0, s33
	v_lshl_add_u64 v[134:135], s[28:29], 0, v[72:73]
	global_load_lds_dwordx4 v[98:99], off
	v_lshl_add_u64 v[98:99], s[60:61], 0, v[66:67]
	s_mov_b32 m0, s34
	v_lshl_add_u64 v[136:137], s[28:29], 0, v[68:69]
	global_load_lds_dwordx4 v[98:99], off
	v_lshl_add_u64 v[98:99], v[134:135], 0, s[18:19]
	s_mov_b32 m0, s5
	s_nop 0
	global_load_lds_dwordx4 v[98:99], off
	v_lshl_add_u64 v[98:99], v[136:137], 0, s[18:19]
	s_mov_b32 m0, s35
	s_nop 0
	global_load_lds_dwordx4 v[98:99], off
	s_waitcnt vmcnt(8)
	s_waitcnt lgkmcnt(0)
	s_barrier
	s_setprio 1
	s_waitcnt lgkmcnt(0)
	v_mfma_f32_16x16x32_bf16 v[98:101], v[2:5], v[46:49], 0
	v_mfma_f32_16x16x32_bf16 v[46:49], v[10:13], v[46:49], 0
	v_mfma_f32_16x16x32_bf16 v[98:101], v[6:9], v[54:57], v[98:101]
	v_mfma_f32_16x16x32_bf16 v[46:49], v[14:17], v[54:57], v[46:49]
	v_mfma_f32_16x16x32_bf16 v[54:57], v[2:5], v[58:61], 0
	v_mfma_f32_16x16x32_bf16 v[58:61], v[10:13], v[58:61], 0
	v_mfma_f32_16x16x32_bf16 v[54:57], v[6:9], v[62:65], v[54:57]
	v_mfma_f32_16x16x32_bf16 v[58:61], v[14:17], v[62:65], v[58:61]
	v_mfma_f32_16x16x32_bf16 v[62:65], v[2:5], v[82:85], 0
	v_mfma_f32_16x16x32_bf16 v[2:5], v[2:5], v[90:93], 0
	v_mfma_f32_16x16x32_bf16 v[62:65], v[6:9], v[86:89], v[62:65]
	v_mfma_f32_16x16x32_bf16 v[2:5], v[6:9], v[94:97], v[2:5]
	v_mfma_f32_16x16x32_bf16 v[6:9], v[10:13], v[90:93], 0
	v_mfma_f32_16x16x32_bf16 v[82:85], v[10:13], v[82:85], 0
	v_mfma_f32_16x16x32_bf16 v[6:9], v[14:17], v[94:97], v[6:9]
	v_mfma_f32_16x16x32_bf16 v[82:85], v[14:17], v[86:89], v[82:85]
	s_setprio 0
	s_barrier
	ds_read_b128 v[10:13], v80
	ds_read_b128 v[14:17], v80 offset:1024
	ds_read_b128 v[86:89], v80 offset:2048
	ds_read_b128 v[90:93], v80 offset:3072
	s_add_u32 s60, s28, 0x10100
	s_addc_u32 s61, s29, 0
	s_mov_b32 m0, s36
	v_lshl_add_u64 v[138:139], s[60:61], 0, v[72:73]
	ds_read_b128 v[94:97], v79 offset:32768
	ds_read_b128 v[102:105], v79 offset:33792
	ds_read_b128 v[106:109], v79 offset:34816
	ds_read_b128 v[110:113], v79 offset:35840
	ds_read_b128 v[114:117], v79 offset:36864
	ds_read_b128 v[118:121], v79 offset:37888
	ds_read_b128 v[122:125], v79 offset:38912
	ds_read_b128 v[126:129], v79 offset:39936
	global_load_lds_dwordx4 v[138:139], off
	v_lshl_add_u64 v[138:139], s[60:61], 0, v[68:69]
	s_mov_b32 m0, s37
	s_nop 0
	global_load_lds_dwordx4 v[138:139], off
	s_waitcnt vmcnt(8)
	s_waitcnt lgkmcnt(0)
	s_barrier
; #define PG8_STAGE(bufoff, gbase, voff) do { _Pragma("unroll") for (int _i = 0; _i < 2; ++_i) \
;         __builtin_amdgcn_global_load_lds((const unsigned*)((const char*)(gbase) + (voff)[_i]), (PG8_LAS unsigned*)(lds + (bufoff) + ldsw + _i * 8192), 16, 0, 0); } while (0)
; #define PG8_LDA(dst, b, h) do { _Pragma("unroll") for (int m = 0; m < 4; ++m) _Pragma("unroll") for (int k = 0; k < 2; ++k) dst[m][k] = *(const PG8_LAS bf16x8*)(lds + PG8_SA(b, h) + aoff + m * 2048 + k * 1024); } while (0)
; #define PG8_LDB(dst, b, h) do { _Pragma("unroll") for (int n = 0; n < 2; ++n) _Pragma("unroll") for (int k = 0; k < 2; ++k) dst[n][k] = *(const PG8_LAS bf16x8*)(lds + PG8_SB(b, h) + boff + n * 2048 + k * 1024); } while (0)
; #define PG8_MMA(ai, bj, At, Bt) do { __builtin_amdgcn_s_setprio(1); _Pragma("unroll") for (int m = 0; m < 4; ++m) _Pragma("unroll") for (int n = 0; n < 2; ++n) _Pragma("unroll") for (int k = 0; k < 2; ++k) \
;         acc[ai][bj][m][n] = __builtin_amdgcn_mfma_f32_16x16x32_bf16(Bt[n][k], At[m][k], acc[ai][bj][m][n], 0, 0, 0); __builtin_amdgcn_s_setprio(0); } while (0)
; #define PG8_WAIT_V(n) asm volatile("s_waitcnt vmcnt(" #n ")" ::: "memory")
; #define PG8_WAIT_L(n) asm volatile("s_waitcnt lgkmcnt(" #n ")" ::: "memory")
; #define PG8_BAR __builtin_amdgcn_s_barrier()
; #define PG8_SCHED __builtin_amdgcn_sched_barrier(0)
; template <class Epi, class Sched, bool ALIGN_EPI = false, bool SP2 = false>
; __device__ __forceinline__ void gemm_phase(PG8_LAS unsigned char* lds, const Gemm g, const Sched& S, const Epi& E) {
;     ...
;             PG8_WAIT_V(8); PG8_WAIT_L(0); PG8_BAR; PG8_MMA(1, 0, At, B0); PG8_MMA(1, 1, At, B1); PG8_BAR; PG8_SCHED;
;             PG8_LDB(B0, 1, 0); PG8_LDB(B1, 1, 1); PG8_SCHED; PG8_LDA(At, 1, 0); PG8_STAGE(PG8_SA(0, 1), a2 + hstep, voffA);
;             PG8_WAIT_V(8); PG8_WAIT_L(0); PG8_BAR; PG8_MMA(0, 0, At, B0); PG8_MMA(0, 1, At, B1); PG8_BAR; PG8_SCHED;
;             PG8_LDA(At, 1, 1); PG8_STAGE(PG8_SB(1, 0), b3, voffB); PG8_STAGE(PG8_SB(1, 1), b3 + hstep, voffB); PG8_STAGE(PG8_SA(1, 0), a3, voffA);
;             PG8_WAIT_V(8); PG8_WAIT_L(0); PG8_BAR; PG8_MMA(1, 0, At, B0); PG8_MMA(1, 1, At, B1); PG8_BAR; PG8_SCHED;
	s_setprio 1
	s_waitcnt lgkmcnt(0)
	v_mfma_f32_16x16x32_bf16 v[50:53], v[10:13], v[94:97], v[50:53]
	v_mfma_f32_16x16x32_bf16 v[18:21], v[86:89], v[94:97], v[18:21]
	v_mfma_f32_16x16x32_bf16 v[22:25], v[10:13], v[106:109], v[22:25]
	v_mfma_f32_16x16x32_bf16 v[26:29], v[86:89], v[106:109], v[26:29]
	v_mfma_f32_16x16x32_bf16 v[30:33], v[10:13], v[114:117], v[30:33]
	v_mfma_f32_16x16x32_bf16 v[34:37], v[86:89], v[114:117], v[34:37]
	v_mfma_f32_16x16x32_bf16 v[38:41], v[10:13], v[122:125], v[38:41]
	v_mfma_f32_16x16x32_bf16 v[42:45], v[86:89], v[122:125], v[42:45]
	v_mfma_f32_16x16x32_bf16 v[50:53], v[14:17], v[102:105], v[50:53]
	v_mfma_f32_16x16x32_bf16 v[18:21], v[90:93], v[102:105], v[18:21]
	v_mfma_f32_16x16x32_bf16 v[22:25], v[14:17], v[110:113], v[22:25]
	v_mfma_f32_16x16x32_bf16 v[26:29], v[90:93], v[110:113], v[26:29]
	v_mfma_f32_16x16x32_bf16 v[30:33], v[14:17], v[118:121], v[30:33]
	v_mfma_f32_16x16x32_bf16 v[34:37], v[90:93], v[118:121], v[34:37]
	v_mfma_f32_16x16x32_bf16 v[38:41], v[14:17], v[126:129], v[38:41]
	v_mfma_f32_16x16x32_bf16 v[42:45], v[90:93], v[126:129], v[42:45]
	s_setprio 0
	s_barrier
	s_mov_b32 m0, s56
	v_lshl_add_u64 v[130:131], v[130:131], 0, s[20:21]
	s_add_u32 s30, s30, 0x10180
	ds_read_b128 v[94:97], v79 offset:49152
	ds_read_b128 v[102:105], v79 offset:50176
	ds_read_b128 v[106:109], v79 offset:51200
	ds_read_b128 v[110:113], v79 offset:52224
	ds_read_b128 v[114:117], v79 offset:53248
	ds_read_b128 v[118:121], v79 offset:54272
	ds_read_b128 v[122:125], v79 offset:55296
	ds_read_b128 v[126:129], v79 offset:56320
	global_load_lds_dwordx4 v[130:131], off
	v_lshl_add_u64 v[130:131], v[132:133], 0, s[20:21]
	s_mov_b32 m0, s57
	s_addc_u32 s31, s31, 0
	global_load_lds_dwordx4 v[130:131], off
	v_lshl_add_u64 v[130:131], s[30:31], 0, v[70:71]
	s_mov_b32 m0, s43
	s_nop 0
	global_load_lds_dwordx4 v[130:131], off
	v_lshl_add_u64 v[130:131], s[30:31], 0, v[66:67]
	s_mov_b32 m0, s44
	s_nop 0
	global_load_lds_dwordx4 v[130:131], off
	v_lshl_add_u64 v[130:131], v[134:135], 0, s[20:21]
	s_mov_b32 m0, s41
	s_nop 0
	global_load_lds_dwordx4 v[130:131], off
	v_lshl_add_u64 v[130:131], v[136:137], 0, s[20:21]
	s_mov_b32 m0, s42
	s_nop 0
	global_load_lds_dwordx4 v[130:131], off
	s_waitcnt vmcnt(8)
	s_waitcnt lgkmcnt(0)
	s_barrier
	s_setprio 1
	s_waitcnt lgkmcnt(0)
	v_mfma_f32_16x16x32_bf16 v[46:49], v[86:89], v[94:97], v[46:49]
	v_mfma_f32_16x16x32_bf16 v[54:57], v[10:13], v[106:109], v[54:57]
	v_mfma_f32_16x16x32_bf16 v[58:61], v[86:89], v[106:109], v[58:61]
	v_mfma_f32_16x16x32_bf16 v[62:65], v[10:13], v[114:117], v[62:65]
	v_mfma_f32_16x16x32_bf16 v[2:5], v[10:13], v[122:125], v[2:5]
	v_mfma_f32_16x16x32_bf16 v[6:9], v[86:89], v[122:125], v[6:9]
	v_mfma_f32_16x16x32_bf16 v[98:101], v[10:13], v[94:97], v[98:101]
	v_mfma_f32_16x16x32_bf16 v[46:49], v[90:93], v[102:105], v[46:49]
	v_mfma_f32_16x16x32_bf16 v[54:57], v[14:17], v[110:113], v[54:57]
	v_mfma_f32_16x16x32_bf16 v[58:61], v[90:93], v[110:113], v[58:61]
	v_mfma_f32_16x16x32_bf16 v[62:65], v[14:17], v[118:121], v[62:65]
	v_mfma_f32_16x16x32_bf16 v[82:85], v[86:89], v[114:117], v[82:85]
	v_mfma_f32_16x16x32_bf16 v[2:5], v[14:17], v[126:129], v[2:5]
	v_mfma_f32_16x16x32_bf16 v[6:9], v[90:93], v[126:129], v[6:9]
	v_mfma_f32_16x16x32_bf16 v[98:101], v[14:17], v[102:105], v[98:101]
	v_mfma_f32_16x16x32_bf16 v[82:85], v[90:93], v[118:121], v[82:85]
	s_setprio 0
	s_barrier
	ds_read_b128 v[10:13], v78
	ds_read_b128 v[14:17], v78 offset:1024
	ds_read_b128 v[86:89], v78 offset:2048
	ds_read_b128 v[90:93], v78 offset:3072
	s_add_u32 s28, s28, 0x10180
	s_addc_u32 s29, s29, 0
	s_mov_b32 m0, s52
	v_lshl_add_u64 v[130:131], s[28:29], 0, v[72:73]
	ds_read_b128 v[94:97], v79
	ds_read_b128 v[102:105], v79 offset:1024
	ds_read_b128 v[106:109], v79 offset:2048
	ds_read_b128 v[110:113], v79 offset:3072
	ds_read_b128 v[114:117], v79 offset:4096
	ds_read_b128 v[118:121], v79 offset:5120
	ds_read_b128 v[122:125], v79 offset:6144
	ds_read_b128 v[126:129], v79 offset:7168
	global_load_lds_dwordx4 v[130:131], off
	v_lshl_add_u64 v[130:131], s[28:29], 0, v[68:69]
	s_mov_b32 m0, s53
	s_nop 0
	global_load_lds_dwordx4 v[130:131], off
	s_waitcnt vmcnt(8)
	s_waitcnt lgkmcnt(0)
	s_barrier
	s_setprio 1
	s_waitcnt lgkmcnt(0)
	v_mfma_f32_16x16x32_bf16 v[26:29], v[86:89], v[106:109], v[26:29]
	v_mfma_f32_16x16x32_bf16 v[50:53], v[10:13], v[94:97], v[50:53]
	v_mfma_f32_16x16x32_bf16 v[18:21], v[86:89], v[94:97], v[18:21]
	v_mfma_f32_16x16x32_bf16 v[94:97], v[90:93], v[110:113], v[26:29]
	v_mfma_f32_16x16x32_bf16 v[26:29], v[10:13], v[114:117], v[30:33]
	v_mfma_f32_16x16x32_bf16 v[50:53], v[14:17], v[102:105], v[50:53]
	v_mfma_f32_16x16x32_bf16 v[18:21], v[90:93], v[102:105], v[18:21]
	v_mfma_f32_16x16x32_bf16 v[102:105], v[14:17], v[118:121], v[26:29]
	v_mfma_f32_16x16x32_bf16 v[26:29], v[86:89], v[114:117], v[34:37]
	v_mfma_f32_16x16x32_bf16 v[34:37], v[90:93], v[118:121], v[26:29]
	v_mfma_f32_16x16x32_bf16 v[26:29], v[10:13], v[122:125], v[38:41]
	v_mfma_f32_16x16x32_bf16 v[22:25], v[10:13], v[106:109], v[22:25]
	v_mfma_f32_16x16x32_bf16 v[38:41], v[14:17], v[126:129], v[26:29]
	v_mfma_f32_16x16x32_bf16 v[26:29], v[86:89], v[122:125], v[42:45]
	v_mfma_f32_16x16x32_bf16 v[22:25], v[14:17], v[110:113], v[22:25]
	v_mfma_f32_16x16x32_bf16 v[42:45], v[90:93], v[126:129], v[26:29]
	s_setprio 0
	s_barrier
; #define PG8_STAGE(bufoff, gbase, voff) do { _Pragma("unroll") for (int _i = 0; _i < 2; ++_i) \
;         __builtin_amdgcn_global_load_lds((const unsigned*)((const char*)(gbase) + (voff)[_i]), (PG8_LAS unsigned*)(lds + (bufoff) + ldsw + _i * 8192), 16, 0, 0); } while (0)
; #define PG8_LDA(dst, b, h) do { _Pragma("unroll") for (int m = 0; m < 4; ++m) _Pragma("unroll") for (int k = 0; k < 2; ++k) dst[m][k] = *(const PG8_LAS bf16x8*)(lds + PG8_SA(b, h) + aoff + m * 2048 + k * 1024); } while (0)
; #define PG8_LDB(dst, b, h) do { _Pragma("unroll") for (int n = 0; n < 2; ++n) _Pragma("unroll") for (int k = 0; k < 2; ++k) dst[n][k] = *(const PG8_LAS bf16x8*)(lds + PG8_SB(b, h) + boff + n * 2048 + k * 1024); } while (0)
; #define PG8_MMA(ai, bj, At, Bt) do { __builtin_amdgcn_s_setprio(1); _Pragma("unroll") for (int m = 0; m < 4; ++m) _Pragma("unroll") for (int n = 0; n < 2; ++n) _Pragma("unroll") for (int k = 0; k < 2; ++k) \
;         acc[ai][bj][m][n] = __builtin_amdgcn_mfma_f32_16x16x32_bf16(Bt[n][k], At[m][k], acc[ai][bj][m][n], 0, 0, 0); __builtin_amdgcn_s_setprio(0); } while (0)
; #define PG8_WAIT_V(n) asm volatile("s_waitcnt vmcnt(" #n ")" ::: "memory")
; #define PG8_WAIT_L(n) asm volatile("s_waitcnt lgkmcnt(" #n ")" ::: "memory")
; #define PG8_BAR __builtin_amdgcn_s_barrier()
; #define PG8_SCHED __builtin_amdgcn_sched_barrier(0)
; template <class Epi, class Sched, bool ALIGN_EPI = false, bool SP2 = false>
; __device__ __forceinline__ void gemm_phase(PG8_LAS unsigned char* lds, const Gemm g, const Sched& S, const Epi& E) {
;     ...
;             PG8_WAIT_V(8); PG8_WAIT_L(0); PG8_BAR; PG8_MMA(1, 0, At, B0); PG8_MMA(1, 1, At, B1); PG8_BAR; PG8_SCHED;
;             PG8_LDB(B0, 1, 0); PG8_LDB(B1, 1, 1); PG8_SCHED; PG8_LDA(At, 1, 0); PG8_STAGE(PG8_SA(0, 1), a2 + hstep, voffA);
;             PG8_WAIT_V(8); PG8_WAIT_L(0); PG8_BAR; PG8_MMA(0, 0, At, B0); PG8_MMA(0, 1, At, B1); PG8_BAR; PG8_SCHED;
;             PG8_LDA(At, 1, 1); PG8_STAGE(PG8_SB(1, 0), b3, voffB); PG8_STAGE(PG8_SB(1, 1), b3 + hstep, voffB); PG8_STAGE(PG8_SA(1, 0), a3, voffA);
;             PG8_WAIT_V(8); PG8_WAIT_L(0); PG8_BAR; PG8_MMA(1, 0, At, B0); PG8_MMA(1, 1, At, B1); PG8_BAR; PG8_SCHED;
;     ...
;         if constexpr (ALIGN_EPI) { if (wr == 0) PG8_BAR; }
	s_mov_b32 m0, s54
	v_lshl_add_u64 v[142:143], s[24:25], 0, v[70:71]
	s_add_u32 s28, s24, 0x10000
	ds_read_b128 v[26:29], v79 offset:16384
	ds_read_b128 v[30:33], v79 offset:17408
	ds_read_b128 v[106:109], v79 offset:18432
	ds_read_b128 v[110:113], v79 offset:19456
	ds_read_b128 v[114:117], v79 offset:20480
	ds_read_b128 v[118:121], v79 offset:21504
	ds_read_b128 v[122:125], v79 offset:22528
	ds_read_b128 v[126:129], v79 offset:23552
	global_load_lds_dwordx4 v[142:143], off
	v_lshl_add_u64 v[144:145], s[24:25], 0, v[66:67]
	s_mov_b32 m0, s55
	s_addc_u32 s29, s25, 0
	global_load_lds_dwordx4 v[144:145], off
	v_lshl_add_u64 v[130:131], s[28:29], 0, v[70:71]
	s_mov_b32 m0, s33
	v_lshl_add_u64 v[146:147], s[26:27], 0, v[72:73]
	global_load_lds_dwordx4 v[130:131], off
	v_lshl_add_u64 v[130:131], s[28:29], 0, v[66:67]
	s_mov_b32 m0, s34
	v_lshl_add_u64 v[148:149], s[26:27], 0, v[68:69]
	global_load_lds_dwordx4 v[130:131], off
	s_mov_b32 m0, s5
	s_nop 0
	global_load_lds_dwordx4 v[146:147], off
	s_mov_b32 m0, s35
	s_nop 0
	global_load_lds_dwordx4 v[148:149], off
	s_waitcnt vmcnt(8)
	s_waitcnt lgkmcnt(0)
	s_barrier
	s_setprio 1
	s_waitcnt lgkmcnt(0)
	v_mfma_f32_16x16x32_bf16 v[98:101], v[10:13], v[26:29], v[98:101]
	v_mfma_f32_16x16x32_bf16 v[26:29], v[86:89], v[26:29], v[46:49]
	v_mfma_f32_16x16x32_bf16 v[46:49], v[90:93], v[30:33], v[26:29]
	v_mfma_f32_16x16x32_bf16 v[26:29], v[10:13], v[106:109], v[54:57]
	v_mfma_f32_16x16x32_bf16 v[54:57], v[14:17], v[110:113], v[26:29]
	v_mfma_f32_16x16x32_bf16 v[26:29], v[86:89], v[106:109], v[58:61]
	v_mfma_f32_16x16x32_bf16 v[106:109], v[90:93], v[110:113], v[26:29]
	v_mfma_f32_16x16x32_bf16 v[26:29], v[10:13], v[114:117], v[62:65]
	v_mfma_f32_16x16x32_bf16 v[2:5], v[10:13], v[122:125], v[2:5]
	v_mfma_f32_16x16x32_bf16 v[110:113], v[14:17], v[118:121], v[26:29]
	v_mfma_f32_16x16x32_bf16 v[26:29], v[86:89], v[114:117], v[82:85]
	v_mfma_f32_16x16x32_bf16 v[114:117], v[14:17], v[126:129], v[2:5]
	v_mfma_f32_16x16x32_bf16 v[2:5], v[86:89], v[122:125], v[6:9]
	v_mfma_f32_16x16x32_bf16 v[98:101], v[14:17], v[30:33], v[98:101]
	v_mfma_f32_16x16x32_bf16 v[82:85], v[90:93], v[118:121], v[26:29]
	v_mfma_f32_16x16x32_bf16 v[86:89], v[90:93], v[126:129], v[2:5]
	s_setprio 0
	s_barrier
	ds_read_b128 v[90:93], v80
	ds_read_b128 v[118:121], v80 offset:1024
	ds_read_b128 v[122:125], v80 offset:2048
	ds_read_b128 v[126:129], v80 offset:3072
	s_add_u32 s26, s26, 0x10000
	s_addc_u32 s27, s27, 0
	s_mov_b32 m0, s36
	v_lshl_add_u64 v[26:27], s[26:27], 0, v[72:73]
	ds_read_b128 v[2:5], v79 offset:32768
	ds_read_b128 v[6:9], v79 offset:33792
	ds_read_b128 v[10:13], v79 offset:34816
	ds_read_b128 v[14:17], v79 offset:35840
	ds_read_b128 v[58:61], v79 offset:36864
	ds_read_b128 v[62:65], v79 offset:37888
	ds_read_b128 v[130:133], v79 offset:38912
	ds_read_b128 v[134:137], v79 offset:39936
	global_load_lds_dwordx4 v[26:27], off
	v_lshl_add_u64 v[26:27], s[26:27], 0, v[68:69]
	s_mov_b32 m0, s37
	s_nop 0
	global_load_lds_dwordx4 v[26:27], off
	s_waitcnt vmcnt(8)
	s_waitcnt lgkmcnt(0)
	s_barrier
	s_setprio 1
	s_waitcnt lgkmcnt(0)
	v_mfma_f32_16x16x32_bf16 v[26:29], v[90:93], v[2:5], v[50:53]
	v_mfma_f32_16x16x32_bf16 v[2:5], v[122:125], v[2:5], v[18:21]
	v_mfma_f32_16x16x32_bf16 v[30:33], v[126:129], v[6:9], v[2:5]
	v_mfma_f32_16x16x32_bf16 v[2:5], v[90:93], v[10:13], v[22:25]
	v_mfma_f32_16x16x32_bf16 v[18:21], v[118:121], v[14:17], v[2:5]
	v_mfma_f32_16x16x32_bf16 v[2:5], v[122:125], v[10:13], v[94:97]
	v_mfma_f32_16x16x32_bf16 v[22:25], v[126:129], v[14:17], v[2:5]
	v_mfma_f32_16x16x32_bf16 v[2:5], v[90:93], v[58:61], v[102:105]
	v_mfma_f32_16x16x32_bf16 v[10:13], v[118:121], v[62:65], v[2:5]
	v_mfma_f32_16x16x32_bf16 v[2:5], v[122:125], v[58:61], v[34:37]
	v_mfma_f32_16x16x32_bf16 v[26:29], v[118:121], v[6:9], v[26:29]
	v_mfma_f32_16x16x32_bf16 v[14:17], v[126:129], v[62:65], v[2:5]
	v_mfma_f32_16x16x32_bf16 v[2:5], v[90:93], v[130:133], v[38:41]
	v_mfma_f32_16x16x32_bf16 v[6:9], v[122:125], v[130:133], v[42:45]
	v_mfma_f32_16x16x32_bf16 v[2:5], v[118:121], v[134:137], v[2:5]
	v_mfma_f32_16x16x32_bf16 v[6:9], v[126:129], v[134:137], v[6:9]
	s_setprio 0
	s_barrier
	s_mov_b32 m0, s56
	v_lshl_add_u64 v[50:51], v[142:143], 0, s[16:17]
	s_add_u32 s24, s24, 0x10080
	ds_read_b128 v[34:37], v79 offset:49152
	ds_read_b128 v[38:41], v79 offset:50176
	ds_read_b128 v[42:45], v79 offset:51200
	ds_read_b128 v[94:97], v79 offset:52224
	ds_read_b128 v[102:105], v79 offset:53248
	ds_read_b128 v[130:133], v79 offset:54272
	ds_read_b128 v[134:137], v79 offset:55296
	ds_read_b128 v[138:141], v79 offset:56320
	global_load_lds_dwordx4 v[50:51], off
	v_lshl_add_u64 v[50:51], v[144:145], 0, s[16:17]
	s_mov_b32 m0, s57
	s_addc_u32 s25, s25, 0
	global_load_lds_dwordx4 v[50:51], off
	v_lshl_add_u64 v[50:51], s[24:25], 0, v[70:71]
	s_mov_b32 m0, s43
	s_nop 0
	global_load_lds_dwordx4 v[50:51], off
	v_lshl_add_u64 v[50:51], s[24:25], 0, v[66:67]
	s_mov_b32 m0, s44
	s_nop 0
	global_load_lds_dwordx4 v[50:51], off
	v_lshl_add_u64 v[50:51], v[146:147], 0, s[16:17]
	s_mov_b32 m0, s41
	s_nop 0
	global_load_lds_dwordx4 v[50:51], off
	v_lshl_add_u64 v[50:51], v[148:149], 0, s[16:17]
	s_mov_b32 m0, s42
	s_nop 0
	global_load_lds_dwordx4 v[50:51], off
	s_waitcnt vmcnt(8)
	s_waitcnt lgkmcnt(0)
	s_barrier
	s_setprio 1
	s_waitcnt lgkmcnt(0)
	v_mfma_f32_16x16x32_bf16 v[50:53], v[90:93], v[34:37], v[98:101]
	v_mfma_f32_16x16x32_bf16 v[34:37], v[122:125], v[34:37], v[46:49]
	v_mfma_f32_16x16x32_bf16 v[62:65], v[126:129], v[38:41], v[34:37]
	v_mfma_f32_16x16x32_bf16 v[34:37], v[90:93], v[42:45], v[54:57]
	v_mfma_f32_16x16x32_bf16 v[58:61], v[118:121], v[38:41], v[50:53]
	v_mfma_f32_16x16x32_bf16 v[50:53], v[118:121], v[94:97], v[34:37]
	v_mfma_f32_16x16x32_bf16 v[34:37], v[122:125], v[42:45], v[106:109]
	v_mfma_f32_16x16x32_bf16 v[54:57], v[126:129], v[94:97], v[34:37]
	v_mfma_f32_16x16x32_bf16 v[34:37], v[90:93], v[102:105], v[110:113]
	v_mfma_f32_16x16x32_bf16 v[42:45], v[118:121], v[130:133], v[34:37]
	v_mfma_f32_16x16x32_bf16 v[34:37], v[122:125], v[102:105], v[82:85]
	v_mfma_f32_16x16x32_bf16 v[46:49], v[126:129], v[130:133], v[34:37]
	v_mfma_f32_16x16x32_bf16 v[34:37], v[90:93], v[134:137], v[114:117]
	v_mfma_f32_16x16x32_bf16 v[38:41], v[122:125], v[134:137], v[86:89]
	v_mfma_f32_16x16x32_bf16 v[34:37], v[118:121], v[138:141], v[34:37]
	v_mfma_f32_16x16x32_bf16 v[38:41], v[126:129], v[138:141], v[38:41]
	s_setprio 0
	s_barrier
	s_and_b64 vcc, exec, s[0:1]
	s_cbranch_vccnz .LBB0_1576
	s_barrier

; #define PG8_STAGE(bufoff, gbase, voff) do { _Pragma("unroll") for (int _i = 0; _i < 2; ++_i) \
;         __builtin_amdgcn_global_load_lds((const unsigned*)((const char*)(gbase) + (voff)[_i]), (PG8_LAS unsigned*)(lds + (bufoff) + ldsw + _i * 8192), 16, 0, 0); } while (0)
; #define PG8_LDA(dst, b, h) do { _Pragma("unroll") for (int m = 0; m < 4; ++m) _Pragma("unroll") for (int k = 0; k < 2; ++k) dst[m][k] = *(const PG8_LAS bf16x8*)(lds + PG8_SA(b, h) + aoff + m * 2048 + k * 1024); } while (0)
; #define PG8_LDB(dst, b, h) do { _Pragma("unroll") for (int n = 0; n < 2; ++n) _Pragma("unroll") for (int k = 0; k < 2; ++k) dst[n][k] = *(const PG8_LAS bf16x8*)(lds + PG8_SB(b, h) + boff + n * 2048 + k * 1024); } while (0)
; #define PG8_MMA(ai, bj, At, Bt) do { __builtin_amdgcn_s_setprio(1); _Pragma("unroll") for (int m = 0; m < 4; ++m) _Pragma("unroll") for (int n = 0; n < 2; ++n) _Pragma("unroll") for (int k = 0; k < 2; ++k) \
;         acc[ai][bj][m][n] = __builtin_amdgcn_mfma_f32_16x16x32_bf16(Bt[n][k], At[m][k], acc[ai][bj][m][n], 0, 0, 0); __builtin_amdgcn_s_setprio(0); } while (0)
; #define PG8_WAIT_V(n) asm volatile("s_waitcnt vmcnt(" #n ")" ::: "memory")
; #define PG8_WAIT_L(n) asm volatile("s_waitcnt lgkmcnt(" #n ")" ::: "memory")
; #define PG8_BAR __builtin_amdgcn_s_barrier()
; #define PG8_SCHED __builtin_amdgcn_sched_barrier(0)
; template <class Epi, class Sched, bool ALIGN_EPI = false, bool SP2 = false>
; __device__ __forceinline__ void gemm_phase(PG8_LAS unsigned char* lds, const Gemm g, const Sched& S, const Epi& E) {
;     ...
;             PG8_LDB(B0, 0, 0); PG8_LDB(B1, 0, 1); PG8_SCHED; PG8_LDA(At, 0, 0); PG8_STAGE(PG8_SA(1, 1), a1 + hstep, voffA);
;             PG8_WAIT_V(8); PG8_WAIT_L(0); PG8_BAR; PG8_MMA(0, 0, At, B0); PG8_MMA(0, 1, At, B1); PG8_BAR; PG8_SCHED;
;             PG8_LDA(At, 0, 1); PG8_STAGE(PG8_SB(0, 0), b2, voffB); PG8_STAGE(PG8_SB(0, 1), b2 + hstep, voffB); PG8_STAGE(PG8_SA(0, 0), a2, voffA);
.LBB0_2528:
	ds_read_b128 v[130:133], v147
	ds_read_b128 v[134:137], v147 offset:1024
	ds_read_b128 v[156:159], v147 offset:2048
	ds_read_b128 v[164:167], v147 offset:3072
	ds_read_b128 v[168:171], v162
	ds_read_b128 v[172:175], v162 offset:1024
	ds_read_b128 v[176:179], v162 offset:2048
	ds_read_b128 v[180:183], v162 offset:3072
	s_add_u32 s24, s22, 0xfffc0080
	s_addc_u32 s25, s23, -1
	s_cmp_eq_u32 s44, 12
	s_cselect_b32 s27, s15, s25
	s_cselect_b32 s26, s40, s24
	s_cselect_b32 s25, s13, s43
	s_cselect_b32 s24, s41, s42
	v_lshl_add_u64 v[160:161], s[22:23], 0, v[148:149]
	s_add_i32 m0, s21, 0xc000
	ds_read_b128 v[184:187], v163
	ds_read_b128 v[188:191], v163 offset:1024
	ds_read_b128 v[192:195], v163 offset:2048
	ds_read_b128 v[196:199], v163 offset:3072
	ds_read_b128 v[200:203], v163 offset:4096
	ds_read_b128 v[204:207], v163 offset:5120
	ds_read_b128 v[208:211], v163 offset:6144
	ds_read_b128 v[212:215], v163 offset:7168
	global_load_lds_dwordx4 v[160:161], off
	v_lshl_add_u64 v[160:161], s[22:23], 0, v[150:151]
	s_add_i32 m0, s21, 0xe000
	s_nop 0
	global_load_lds_dwordx4 v[160:161], off
	s_waitcnt vmcnt(8)
	s_waitcnt lgkmcnt(0)
	s_barrier
	s_setprio 1
	s_waitcnt lgkmcnt(0)
	v_mfma_f32_16x16x32_bf16 v[126:129], v[130:133], v[184:187], v[126:129]
	v_mfma_f32_16x16x32_bf16 v[122:125], v[156:159], v[184:187], v[122:125]
	v_mfma_f32_16x16x32_bf16 v[118:121], v[130:133], v[192:195], v[118:121]
	v_mfma_f32_16x16x32_bf16 v[114:117], v[156:159], v[192:195], v[114:117]
	v_mfma_f32_16x16x32_bf16 v[94:97], v[130:133], v[200:203], v[94:97]
	v_mfma_f32_16x16x32_bf16 v[90:93], v[156:159], v[200:203], v[90:93]
	v_mfma_f32_16x16x32_bf16 v[82:85], v[130:133], v[208:211], v[82:85]
	v_mfma_f32_16x16x32_bf16 v[74:77], v[156:159], v[208:211], v[74:77]
	v_mfma_f32_16x16x32_bf16 v[126:129], v[134:137], v[188:191], v[126:129]
	v_mfma_f32_16x16x32_bf16 v[122:125], v[164:167], v[188:191], v[122:125]
	v_mfma_f32_16x16x32_bf16 v[118:121], v[134:137], v[196:199], v[118:121]
	v_mfma_f32_16x16x32_bf16 v[114:117], v[164:167], v[196:199], v[114:117]
	v_mfma_f32_16x16x32_bf16 v[94:97], v[134:137], v[204:207], v[94:97]
	v_mfma_f32_16x16x32_bf16 v[90:93], v[164:167], v[204:207], v[90:93]
	v_mfma_f32_16x16x32_bf16 v[82:85], v[134:137], v[212:215], v[82:85]
	v_mfma_f32_16x16x32_bf16 v[74:77], v[164:167], v[212:215], v[74:77]
	v_mfma_f32_16x16x32_bf16 v[110:113], v[168:171], v[184:187], v[110:113]
	v_mfma_f32_16x16x32_bf16 v[106:109], v[176:179], v[184:187], v[106:109]
	v_mfma_f32_16x16x32_bf16 v[102:105], v[168:171], v[192:195], v[102:105]
	v_mfma_f32_16x16x32_bf16 v[98:101], v[176:179], v[192:195], v[98:101]
	v_mfma_f32_16x16x32_bf16 v[86:89], v[168:171], v[200:203], v[86:89]
	v_mfma_f32_16x16x32_bf16 v[78:81], v[176:179], v[200:203], v[78:81]
	v_mfma_f32_16x16x32_bf16 v[70:73], v[168:171], v[208:211], v[70:73]
	v_mfma_f32_16x16x32_bf16 v[66:69], v[176:179], v[208:211], v[66:69]
	v_mfma_f32_16x16x32_bf16 v[110:113], v[172:175], v[188:191], v[110:113]
	v_mfma_f32_16x16x32_bf16 v[106:109], v[180:183], v[188:191], v[106:109]
	v_mfma_f32_16x16x32_bf16 v[102:105], v[172:175], v[196:199], v[102:105]
	v_mfma_f32_16x16x32_bf16 v[98:101], v[180:183], v[196:199], v[98:101]
	v_mfma_f32_16x16x32_bf16 v[86:89], v[172:175], v[204:207], v[86:89]
	v_mfma_f32_16x16x32_bf16 v[78:81], v[180:183], v[204:207], v[78:81]
	v_mfma_f32_16x16x32_bf16 v[70:73], v[172:175], v[212:215], v[70:73]
	v_mfma_f32_16x16x32_bf16 v[66:69], v[180:183], v[212:215], v[66:69]
	s_setprio 0
	s_barrier
	s_add_i32 s45, s37, s28
	v_lshl_add_u64 v[160:161], s[24:25], 0, v[140:141]
	s_mov_b32 m0, s45
	ds_read_b128 v[184:187], v163 offset:16384
	ds_read_b128 v[188:191], v163 offset:17408
	ds_read_b128 v[192:195], v163 offset:18432
	ds_read_b128 v[196:199], v163 offset:19456
	ds_read_b128 v[200:203], v163 offset:20480
	ds_read_b128 v[204:207], v163 offset:21504
	ds_read_b128 v[208:211], v163 offset:22528
	ds_read_b128 v[212:215], v163 offset:23552
	global_load_lds_dwordx4 v[160:161], off
	s_add_i32 m0, s45, 0x2000
	s_add_u32 s46, s24, 0x40000
	v_lshl_add_u64 v[216:217], s[24:25], 0, v[144:145]
	s_addc_u32 s47, s25, 0
	s_add_i32 s45, s38, s28
	global_load_lds_dwordx4 v[216:217], off
	v_lshl_add_u64 v[218:219], s[46:47], 0, v[140:141]
	s_mov_b32 m0, s45
	v_lshl_add_u64 v[220:221], s[26:27], 0, v[142:143]
	global_load_lds_dwordx4 v[218:219], off
	v_lshl_add_u64 v[218:219], s[46:47], 0, v[144:145]
	s_add_i32 m0, s45, 0x2000
	s_nop 0
	global_load_lds_dwordx4 v[218:219], off
	v_lshl_add_u64 v[218:219], s[26:27], 0, v[138:139]
	s_mov_b32 m0, s21
	s_nop 0
	global_load_lds_dwordx4 v[218:219], off
	s_mov_b32 m0, s29
	s_nop 0
	global_load_lds_dwordx4 v[220:221], off
	s_waitcnt vmcnt(8)
	s_waitcnt lgkmcnt(0)
	s_barrier
; #define PG8_STAGE(bufoff, gbase, voff) do { _Pragma("unroll") for (int _i = 0; _i < 2; ++_i) \
;         __builtin_amdgcn_global_load_lds((const unsigned*)((const char*)(gbase) + (voff)[_i]), (PG8_LAS unsigned*)(lds + (bufoff) + ldsw + _i * 8192), 16, 0, 0); } while (0)
; #define PG8_LDA(dst, b, h) do { _Pragma("unroll") for (int m = 0; m < 4; ++m) _Pragma("unroll") for (int k = 0; k < 2; ++k) dst[m][k] = *(const PG8_LAS bf16x8*)(lds + PG8_SA(b, h) + aoff + m * 2048 + k * 1024); } while (0)
; #define PG8_LDB(dst, b, h) do { _Pragma("unroll") for (int n = 0; n < 2; ++n) _Pragma("unroll") for (int k = 0; k < 2; ++k) dst[n][k] = *(const PG8_LAS bf16x8*)(lds + PG8_SB(b, h) + boff + n * 2048 + k * 1024); } while (0)
; #define PG8_MMA(ai, bj, At, Bt) do { __builtin_amdgcn_s_setprio(1); _Pragma("unroll") for (int m = 0; m < 4; ++m) _Pragma("unroll") for (int n = 0; n < 2; ++n) _Pragma("unroll") for (int k = 0; k < 2; ++k) \
;         acc[ai][bj][m][n] = __builtin_amdgcn_mfma_f32_16x16x32_bf16(Bt[n][k], At[m][k], acc[ai][bj][m][n], 0, 0, 0); __builtin_amdgcn_s_setprio(0); } while (0)
; #define PG8_WAIT_V(n) asm volatile("s_waitcnt vmcnt(" #n ")" ::: "memory")
; #define PG8_WAIT_L(n) asm volatile("s_waitcnt lgkmcnt(" #n ")" ::: "memory")
; #define PG8_BAR __builtin_amdgcn_s_barrier()
; #define PG8_SCHED __builtin_amdgcn_sched_barrier(0)
; template <class Epi, class Sched, bool ALIGN_EPI = false, bool SP2 = false>
; __device__ __forceinline__ void gemm_phase(PG8_LAS unsigned char* lds, const Gemm g, const Sched& S, const Epi& E) {
;     ...
;             PG8_WAIT_V(8); PG8_WAIT_L(0); PG8_BAR; PG8_MMA(1, 0, At, B0); PG8_MMA(1, 1, At, B1); PG8_BAR; PG8_SCHED;
;             PG8_LDB(B0, 1, 0); PG8_LDB(B1, 1, 1); PG8_SCHED; PG8_LDA(At, 1, 0); PG8_STAGE(PG8_SA(0, 1), a2 + hstep, voffA);
;             PG8_WAIT_V(8); PG8_WAIT_L(0); PG8_BAR; PG8_MMA(0, 0, At, B0); PG8_MMA(0, 1, At, B1); PG8_BAR; PG8_SCHED;
	s_setprio 1
	s_waitcnt lgkmcnt(0)
	v_mfma_f32_16x16x32_bf16 v[62:65], v[130:133], v[184:187], v[62:65]
	v_mfma_f32_16x16x32_bf16 v[58:61], v[156:159], v[184:187], v[58:61]
	v_mfma_f32_16x16x32_bf16 v[46:49], v[130:133], v[192:195], v[46:49]
	v_mfma_f32_16x16x32_bf16 v[42:45], v[156:159], v[192:195], v[42:45]
	v_mfma_f32_16x16x32_bf16 v[38:41], v[130:133], v[200:203], v[38:41]
	v_mfma_f32_16x16x32_bf16 v[30:33], v[156:159], v[200:203], v[30:33]
	v_mfma_f32_16x16x32_bf16 v[22:25], v[130:133], v[208:211], v[22:25]
	v_mfma_f32_16x16x32_bf16 v[14:17], v[156:159], v[208:211], v[14:17]
	v_mfma_f32_16x16x32_bf16 v[62:65], v[134:137], v[188:191], v[62:65]
	v_mfma_f32_16x16x32_bf16 v[58:61], v[164:167], v[188:191], v[58:61]
	v_mfma_f32_16x16x32_bf16 v[46:49], v[134:137], v[196:199], v[46:49]
	v_mfma_f32_16x16x32_bf16 v[42:45], v[164:167], v[196:199], v[42:45]
	v_mfma_f32_16x16x32_bf16 v[38:41], v[134:137], v[204:207], v[38:41]
	v_mfma_f32_16x16x32_bf16 v[30:33], v[164:167], v[204:207], v[30:33]
	v_mfma_f32_16x16x32_bf16 v[22:25], v[134:137], v[212:215], v[22:25]
	v_mfma_f32_16x16x32_bf16 v[14:17], v[164:167], v[212:215], v[14:17]
	v_mfma_f32_16x16x32_bf16 v[54:57], v[168:171], v[184:187], v[54:57]
	v_mfma_f32_16x16x32_bf16 v[50:53], v[176:179], v[184:187], v[50:53]
	v_mfma_f32_16x16x32_bf16 v[34:37], v[168:171], v[192:195], v[34:37]
	v_mfma_f32_16x16x32_bf16 v[26:29], v[176:179], v[192:195], v[26:29]
	v_mfma_f32_16x16x32_bf16 v[18:21], v[168:171], v[200:203], v[18:21]
	v_mfma_f32_16x16x32_bf16 v[10:13], v[176:179], v[200:203], v[10:13]
	v_mfma_f32_16x16x32_bf16 v[6:9], v[168:171], v[208:211], v[6:9]
	v_mfma_f32_16x16x32_bf16 v[2:5], v[176:179], v[208:211], v[2:5]
	v_mfma_f32_16x16x32_bf16 v[54:57], v[172:175], v[188:191], v[54:57]
	v_mfma_f32_16x16x32_bf16 v[50:53], v[180:183], v[188:191], v[50:53]
	v_mfma_f32_16x16x32_bf16 v[34:37], v[172:175], v[196:199], v[34:37]
	v_mfma_f32_16x16x32_bf16 v[26:29], v[180:183], v[196:199], v[26:29]
	v_mfma_f32_16x16x32_bf16 v[18:21], v[172:175], v[204:207], v[18:21]
	v_mfma_f32_16x16x32_bf16 v[10:13], v[180:183], v[204:207], v[10:13]
	v_mfma_f32_16x16x32_bf16 v[6:9], v[172:175], v[212:215], v[6:9]
	v_mfma_f32_16x16x32_bf16 v[2:5], v[180:183], v[212:215], v[2:5]
	s_setprio 0
	s_barrier
	s_add_i32 s45, 0, 0x18000
	s_add_i32 s46, 0, 0x1c000
	v_add_u32_e32 v164, s45, v1
	v_add_u32_e32 v180, s46, v1
	ds_read_b128 v[130:133], v164
	ds_read_b128 v[134:137], v164 offset:1024
	ds_read_b128 v[156:159], v164 offset:2048
	ds_read_b128 v[164:167], v164 offset:3072
	ds_read_b128 v[168:171], v180
	ds_read_b128 v[172:175], v180 offset:1024
	ds_read_b128 v[176:179], v180 offset:2048
	ds_read_b128 v[180:183], v180 offset:3072
	s_add_u32 s26, s26, 0x40000
	s_addc_u32 s27, s27, 0
	s_mov_b32 m0, s30
	v_lshl_add_u64 v[222:223], s[26:27], 0, v[138:139]
	ds_read_b128 v[184:187], v163 offset:32768
	ds_read_b128 v[188:191], v163 offset:33792
	ds_read_b128 v[192:195], v163 offset:34816
	ds_read_b128 v[196:199], v163 offset:35840
	ds_read_b128 v[200:203], v163 offset:36864
	ds_read_b128 v[204:207], v163 offset:37888
	ds_read_b128 v[208:211], v163 offset:38912
	ds_read_b128 v[212:215], v163 offset:39936
	global_load_lds_dwordx4 v[222:223], off
	v_lshl_add_u64 v[222:223], s[26:27], 0, v[142:143]
	s_mov_b32 m0, s31
	s_nop 0
	global_load_lds_dwordx4 v[222:223], off
	s_waitcnt vmcnt(8)
	s_waitcnt lgkmcnt(0)
	s_barrier
	s_setprio 1
	s_waitcnt lgkmcnt(0)
	v_mfma_f32_16x16x32_bf16 v[126:129], v[130:133], v[184:187], v[126:129]
	v_mfma_f32_16x16x32_bf16 v[122:125], v[156:159], v[184:187], v[122:125]
	v_mfma_f32_16x16x32_bf16 v[118:121], v[130:133], v[192:195], v[118:121]
	v_mfma_f32_16x16x32_bf16 v[114:117], v[156:159], v[192:195], v[114:117]
	v_mfma_f32_16x16x32_bf16 v[94:97], v[130:133], v[200:203], v[94:97]
	v_mfma_f32_16x16x32_bf16 v[90:93], v[156:159], v[200:203], v[90:93]
	v_mfma_f32_16x16x32_bf16 v[82:85], v[130:133], v[208:211], v[82:85]
	v_mfma_f32_16x16x32_bf16 v[74:77], v[156:159], v[208:211], v[74:77]
	v_mfma_f32_16x16x32_bf16 v[126:129], v[134:137], v[188:191], v[126:129]
	v_mfma_f32_16x16x32_bf16 v[122:125], v[164:167], v[188:191], v[122:125]
	v_mfma_f32_16x16x32_bf16 v[118:121], v[134:137], v[196:199], v[118:121]
	v_mfma_f32_16x16x32_bf16 v[114:117], v[164:167], v[196:199], v[114:117]
	v_mfma_f32_16x16x32_bf16 v[94:97], v[134:137], v[204:207], v[94:97]
	v_mfma_f32_16x16x32_bf16 v[90:93], v[164:167], v[204:207], v[90:93]
	v_mfma_f32_16x16x32_bf16 v[82:85], v[134:137], v[212:215], v[82:85]
	v_mfma_f32_16x16x32_bf16 v[74:77], v[164:167], v[212:215], v[74:77]
	v_mfma_f32_16x16x32_bf16 v[110:113], v[168:171], v[184:187], v[110:113]
	v_mfma_f32_16x16x32_bf16 v[106:109], v[176:179], v[184:187], v[106:109]
	v_mfma_f32_16x16x32_bf16 v[102:105], v[168:171], v[192:195], v[102:105]
	v_mfma_f32_16x16x32_bf16 v[98:101], v[176:179], v[192:195], v[98:101]
	v_mfma_f32_16x16x32_bf16 v[86:89], v[168:171], v[200:203], v[86:89]
	v_mfma_f32_16x16x32_bf16 v[78:81], v[176:179], v[200:203], v[78:81]
	v_mfma_f32_16x16x32_bf16 v[70:73], v[168:171], v[208:211], v[70:73]
	v_mfma_f32_16x16x32_bf16 v[66:69], v[176:179], v[208:211], v[66:69]
	v_mfma_f32_16x16x32_bf16 v[110:113], v[172:175], v[188:191], v[110:113]
	v_mfma_f32_16x16x32_bf16 v[106:109], v[180:183], v[188:191], v[106:109]
	v_mfma_f32_16x16x32_bf16 v[102:105], v[172:175], v[196:199], v[102:105]
	v_mfma_f32_16x16x32_bf16 v[98:101], v[180:183], v[196:199], v[98:101]
	v_mfma_f32_16x16x32_bf16 v[86:89], v[172:175], v[204:207], v[86:89]
	v_mfma_f32_16x16x32_bf16 v[78:81], v[180:183], v[204:207], v[78:81]
	v_mfma_f32_16x16x32_bf16 v[70:73], v[172:175], v[212:215], v[70:73]
	v_mfma_f32_16x16x32_bf16 v[66:69], v[180:183], v[212:215], v[66:69]
	s_setprio 0
	s_barrier
; #define PG8_STAGE(bufoff, gbase, voff) do { _Pragma("unroll") for (int _i = 0; _i < 2; ++_i) \
;         __builtin_amdgcn_global_load_lds((const unsigned*)((const char*)(gbase) + (voff)[_i]), (PG8_LAS unsigned*)(lds + (bufoff) + ldsw + _i * 8192), 16, 0, 0); } while (0)
; #define PG8_LDA(dst, b, h) do { _Pragma("unroll") for (int m = 0; m < 4; ++m) _Pragma("unroll") for (int k = 0; k < 2; ++k) dst[m][k] = *(const PG8_LAS bf16x8*)(lds + PG8_SA(b, h) + aoff + m * 2048 + k * 1024); } while (0)
; #define PG8_MMA(ai, bj, At, Bt) do { __builtin_amdgcn_s_setprio(1); _Pragma("unroll") for (int m = 0; m < 4; ++m) _Pragma("unroll") for (int n = 0; n < 2; ++n) _Pragma("unroll") for (int k = 0; k < 2; ++k) \
;         acc[ai][bj][m][n] = __builtin_amdgcn_mfma_f32_16x16x32_bf16(Bt[n][k], At[m][k], acc[ai][bj][m][n], 0, 0, 0); __builtin_amdgcn_s_setprio(0); } while (0)
; #define PG8_WAIT_V(n) asm volatile("s_waitcnt vmcnt(" #n ")" ::: "memory")
; #define PG8_WAIT_L(n) asm volatile("s_waitcnt lgkmcnt(" #n ")" ::: "memory")
; #define PG8_BAR __builtin_amdgcn_s_barrier()
; #define PG8_SCHED __builtin_amdgcn_sched_barrier(0)
; template <class Epi, class Sched, bool ALIGN_EPI = false, bool SP2 = false>
; __device__ __forceinline__ void gemm_phase(PG8_LAS unsigned char* lds, const Gemm g, const Sched& S, const Epi& E) {
;     ...
;             PG8_LDA(At, 1, 1); PG8_STAGE(PG8_SB(1, 0), b3, voffB); PG8_STAGE(PG8_SB(1, 1), b3 + hstep, voffB); PG8_STAGE(PG8_SA(1, 0), a3, voffA);
;             PG8_WAIT_V(8); PG8_WAIT_L(0); PG8_BAR; PG8_MMA(1, 0, At, B0); PG8_MMA(1, 1, At, B1); PG8_BAR; PG8_SCHED;
	s_add_i32 s26, s45, s28
	v_lshl_add_u64 v[160:161], v[160:161], 0, s[8:9]
	s_mov_b32 m0, s26
	ds_read_b128 v[184:187], v163 offset:49152
	ds_read_b128 v[188:191], v163 offset:50176
	ds_read_b128 v[192:195], v163 offset:51200
	ds_read_b128 v[196:199], v163 offset:52224
	ds_read_b128 v[200:203], v163 offset:53248
	ds_read_b128 v[204:207], v163 offset:54272
	ds_read_b128 v[208:211], v163 offset:55296
	ds_read_b128 v[212:215], v163 offset:56320
	global_load_lds_dwordx4 v[160:161], off
	s_add_i32 m0, s26, 0x2000
	s_add_u32 s24, s24, 0x40080
	v_lshl_add_u64 v[160:161], v[216:217], 0, s[8:9]
	s_addc_u32 s25, s25, 0
	s_add_i32 s26, s46, s28
	global_load_lds_dwordx4 v[160:161], off
	v_lshl_add_u64 v[160:161], s[24:25], 0, v[140:141]
	s_mov_b32 m0, s26
	s_nop 0
	global_load_lds_dwordx4 v[160:161], off
	v_lshl_add_u64 v[160:161], s[24:25], 0, v[144:145]
	s_add_i32 m0, s26, 0x2000
	s_nop 0
	global_load_lds_dwordx4 v[160:161], off
	v_lshl_add_u64 v[160:161], v[218:219], 0, s[8:9]
	s_mov_b32 m0, s34
	s_nop 0
	global_load_lds_dwordx4 v[160:161], off
	v_lshl_add_u64 v[160:161], v[220:221], 0, s[8:9]
	s_mov_b32 m0, s35
	s_nop 0
	global_load_lds_dwordx4 v[160:161], off
	s_waitcnt vmcnt(8)
	s_waitcnt lgkmcnt(0)
	s_barrier
	s_setprio 1
	s_waitcnt lgkmcnt(0)
	v_mfma_f32_16x16x32_bf16 v[62:65], v[130:133], v[184:187], v[62:65]
	v_mfma_f32_16x16x32_bf16 v[58:61], v[156:159], v[184:187], v[58:61]
	v_mfma_f32_16x16x32_bf16 v[46:49], v[130:133], v[192:195], v[46:49]
	v_mfma_f32_16x16x32_bf16 v[42:45], v[156:159], v[192:195], v[42:45]
	v_mfma_f32_16x16x32_bf16 v[38:41], v[130:133], v[200:203], v[38:41]
	v_mfma_f32_16x16x32_bf16 v[30:33], v[156:159], v[200:203], v[30:33]
	v_mfma_f32_16x16x32_bf16 v[22:25], v[130:133], v[208:211], v[22:25]
	v_mfma_f32_16x16x32_bf16 v[14:17], v[156:159], v[208:211], v[14:17]
	v_mfma_f32_16x16x32_bf16 v[62:65], v[134:137], v[188:191], v[62:65]
	v_mfma_f32_16x16x32_bf16 v[58:61], v[164:167], v[188:191], v[58:61]
	v_mfma_f32_16x16x32_bf16 v[46:49], v[134:137], v[196:199], v[46:49]
	v_mfma_f32_16x16x32_bf16 v[42:45], v[164:167], v[196:199], v[42:45]
	v_mfma_f32_16x16x32_bf16 v[38:41], v[134:137], v[204:207], v[38:41]
	v_mfma_f32_16x16x32_bf16 v[30:33], v[164:167], v[204:207], v[30:33]
	v_mfma_f32_16x16x32_bf16 v[22:25], v[134:137], v[212:215], v[22:25]
	v_mfma_f32_16x16x32_bf16 v[14:17], v[164:167], v[212:215], v[14:17]
	v_mfma_f32_16x16x32_bf16 v[54:57], v[168:171], v[184:187], v[54:57]
	v_mfma_f32_16x16x32_bf16 v[50:53], v[176:179], v[184:187], v[50:53]
	v_mfma_f32_16x16x32_bf16 v[34:37], v[168:171], v[192:195], v[34:37]
	v_mfma_f32_16x16x32_bf16 v[26:29], v[176:179], v[192:195], v[26:29]
	v_mfma_f32_16x16x32_bf16 v[18:21], v[168:171], v[200:203], v[18:21]
	v_mfma_f32_16x16x32_bf16 v[10:13], v[176:179], v[200:203], v[10:13]
	v_mfma_f32_16x16x32_bf16 v[6:9], v[168:171], v[208:211], v[6:9]
	v_mfma_f32_16x16x32_bf16 v[2:5], v[176:179], v[208:211], v[2:5]
	v_mfma_f32_16x16x32_bf16 v[54:57], v[172:175], v[188:191], v[54:57]
	v_mfma_f32_16x16x32_bf16 v[50:53], v[180:183], v[188:191], v[50:53]
	v_mfma_f32_16x16x32_bf16 v[34:37], v[172:175], v[196:199], v[34:37]
	v_mfma_f32_16x16x32_bf16 v[26:29], v[180:183], v[196:199], v[26:29]
	v_mfma_f32_16x16x32_bf16 v[18:21], v[172:175], v[204:207], v[18:21]
	v_mfma_f32_16x16x32_bf16 v[10:13], v[180:183], v[204:207], v[10:13]
	v_mfma_f32_16x16x32_bf16 v[6:9], v[172:175], v[212:215], v[6:9]
	v_mfma_f32_16x16x32_bf16 v[2:5], v[180:183], v[212:215], v[2:5]
	s_setprio 0
	s_barrier
	s_add_i32 s44, s44, 2
	s_add_u32 s22, s22, 0x100
	s_addc_u32 s23, s23, 0
	s_add_u32 s42, s42, 0x100
	s_addc_u32 s43, s43, 0
	s_cmp_gt_u32 s44, 13
	s_cbranch_scc0 .LBB0_2528
	s_and_b64 vcc, exec, s[10:11]
	s_cbranch_vccz .LBB0_2531
	s_barrier

; #define PG8_STAGE(bufoff, gbase, voff) do { _Pragma("unroll") for (int _i = 0; _i < 2; ++_i) \
;         __builtin_amdgcn_global_load_lds((const unsigned*)((const char*)(gbase) + (voff)[_i]), (PG8_LAS unsigned*)(lds + (bufoff) + ldsw + _i * 8192), 16, 0, 0); } while (0)
; #define PG8_LDA(dst, b, h) do { _Pragma("unroll") for (int m = 0; m < 4; ++m) _Pragma("unroll") for (int k = 0; k < 2; ++k) dst[m][k] = *(const PG8_LAS bf16x8*)(lds + PG8_SA(b, h) + aoff + m * 2048 + k * 1024); } while (0)
; #define PG8_LDB(dst, b, h) do { _Pragma("unroll") for (int n = 0; n < 2; ++n) _Pragma("unroll") for (int k = 0; k < 2; ++k) dst[n][k] = *(const PG8_LAS bf16x8*)(lds + PG8_SB(b, h) + boff + n * 2048 + k * 1024); } while (0)
; #define PG8_MMA(ai, bj, At, Bt) do { __builtin_amdgcn_s_setprio(1); _Pragma("unroll") for (int m = 0; m < 4; ++m) _Pragma("unroll") for (int n = 0; n < 2; ++n) _Pragma("unroll") for (int k = 0; k < 2; ++k) \
;         acc[ai][bj][m][n] = __builtin_amdgcn_mfma_f32_16x16x32_bf16(Bt[n][k], At[m][k], acc[ai][bj][m][n], 0, 0, 0); __builtin_amdgcn_s_setprio(0); } while (0)
; #define PG8_WAIT_V(n) asm volatile("s_waitcnt vmcnt(" #n ")" ::: "memory")
; #define PG8_WAIT_L(n) asm volatile("s_waitcnt lgkmcnt(" #n ")" ::: "memory")
; #define PG8_BAR __builtin_amdgcn_s_barrier()
; #define PG8_SCHED __builtin_amdgcn_sched_barrier(0)
; template <class Epi, class Sched, bool ALIGN_EPI = false, bool SP2 = false>
; __device__ __forceinline__ void gemm_phase(PG8_LAS unsigned char* lds, const Gemm g, const Sched& S, const Epi& E) {
;     ...
;             PG8_LDB(B0, 0, 0); PG8_LDB(B1, 0, 1); PG8_SCHED; PG8_LDA(At, 0, 0); PG8_STAGE(PG8_SA(1, 1), a1 + hstep, voffA);
;             PG8_WAIT_V(8); PG8_WAIT_L(0); PG8_BAR; PG8_MMA(0, 0, At, B0); PG8_MMA(0, 1, At, B1); PG8_BAR; PG8_SCHED;
;             PG8_LDA(At, 0, 1); PG8_STAGE(PG8_SB(0, 0), b2, voffB); PG8_STAGE(PG8_SB(0, 1), b2 + hstep, voffB); PG8_STAGE(PG8_SA(0, 0), a2, voffA);
.LBB0_2559:
	ds_read_b128 v[148:151], v156
	ds_read_b128 v[160:163], v156 offset:1024
	ds_read_b128 v[164:167], v156 offset:2048
	ds_read_b128 v[168:171], v156 offset:3072
	ds_read_b128 v[172:175], v157
	ds_read_b128 v[176:179], v157 offset:1024
	ds_read_b128 v[180:183], v157 offset:2048
	ds_read_b128 v[184:187], v157 offset:3072
	s_add_u32 s26, s24, 0xfffc0080
	s_addc_u32 s27, s25, -1
	s_cmp_eq_u32 s44, 12
	s_cselect_b32 s29, s17, s27
	s_cselect_b32 s28, s40, s26
	s_cselect_b32 s27, s15, s43
	s_cselect_b32 s26, s41, s42
	v_lshl_add_u64 v[152:153], s[24:25], 0, v[140:141]
	s_add_i32 m0, s3, 0xc000
	ds_read_b128 v[188:191], v158
	ds_read_b128 v[192:195], v158 offset:1024
	ds_read_b128 v[196:199], v158 offset:2048
	ds_read_b128 v[200:203], v158 offset:3072
	ds_read_b128 v[204:207], v158 offset:4096
	ds_read_b128 v[208:211], v158 offset:5120
	ds_read_b128 v[212:215], v158 offset:6144
	ds_read_b128 v[216:219], v158 offset:7168
	global_load_lds_dwordx4 v[152:153], off
	v_lshl_add_u64 v[152:153], s[24:25], 0, v[142:143]
	s_add_i32 m0, s3, 0xe000
	s_nop 0
	global_load_lds_dwordx4 v[152:153], off
	s_waitcnt vmcnt(8)
	s_waitcnt lgkmcnt(0)
	s_barrier
	s_setprio 1
	s_waitcnt lgkmcnt(0)
	v_mfma_f32_16x16x32_bf16 v[126:129], v[148:151], v[188:191], v[126:129]
	v_mfma_f32_16x16x32_bf16 v[122:125], v[164:167], v[188:191], v[122:125]
	v_mfma_f32_16x16x32_bf16 v[110:113], v[148:151], v[196:199], v[110:113]
	v_mfma_f32_16x16x32_bf16 v[106:109], v[164:167], v[196:199], v[106:109]
	v_mfma_f32_16x16x32_bf16 v[94:97], v[148:151], v[204:207], v[94:97]
	v_mfma_f32_16x16x32_bf16 v[90:93], v[164:167], v[204:207], v[90:93]
	v_mfma_f32_16x16x32_bf16 v[78:81], v[148:151], v[212:215], v[78:81]
	v_mfma_f32_16x16x32_bf16 v[74:77], v[164:167], v[212:215], v[74:77]
	v_mfma_f32_16x16x32_bf16 v[126:129], v[160:163], v[192:195], v[126:129]
	v_mfma_f32_16x16x32_bf16 v[122:125], v[168:171], v[192:195], v[122:125]
	v_mfma_f32_16x16x32_bf16 v[110:113], v[160:163], v[200:203], v[110:113]
	v_mfma_f32_16x16x32_bf16 v[106:109], v[168:171], v[200:203], v[106:109]
	v_mfma_f32_16x16x32_bf16 v[94:97], v[160:163], v[208:211], v[94:97]
	v_mfma_f32_16x16x32_bf16 v[90:93], v[168:171], v[208:211], v[90:93]
	v_mfma_f32_16x16x32_bf16 v[78:81], v[160:163], v[216:219], v[78:81]
	v_mfma_f32_16x16x32_bf16 v[74:77], v[168:171], v[216:219], v[74:77]
	v_mfma_f32_16x16x32_bf16 v[118:121], v[172:175], v[188:191], v[118:121]
	v_mfma_f32_16x16x32_bf16 v[114:117], v[180:183], v[188:191], v[114:117]
	v_mfma_f32_16x16x32_bf16 v[102:105], v[172:175], v[196:199], v[102:105]
	v_mfma_f32_16x16x32_bf16 v[98:101], v[180:183], v[196:199], v[98:101]
	v_mfma_f32_16x16x32_bf16 v[86:89], v[172:175], v[204:207], v[86:89]
	v_mfma_f32_16x16x32_bf16 v[82:85], v[180:183], v[204:207], v[82:85]
	v_mfma_f32_16x16x32_bf16 v[70:73], v[172:175], v[212:215], v[70:73]
	v_mfma_f32_16x16x32_bf16 v[66:69], v[180:183], v[212:215], v[66:69]
	v_mfma_f32_16x16x32_bf16 v[118:121], v[176:179], v[192:195], v[118:121]
	v_mfma_f32_16x16x32_bf16 v[114:117], v[184:187], v[192:195], v[114:117]
	v_mfma_f32_16x16x32_bf16 v[102:105], v[176:179], v[200:203], v[102:105]
	v_mfma_f32_16x16x32_bf16 v[98:101], v[184:187], v[200:203], v[98:101]
	v_mfma_f32_16x16x32_bf16 v[86:89], v[176:179], v[208:211], v[86:89]
	v_mfma_f32_16x16x32_bf16 v[82:85], v[184:187], v[208:211], v[82:85]
	v_mfma_f32_16x16x32_bf16 v[70:73], v[176:179], v[216:219], v[70:73]
	v_mfma_f32_16x16x32_bf16 v[66:69], v[184:187], v[216:219], v[66:69]
	s_setprio 0
	s_barrier
	s_add_i32 s45, s38, s2
	v_lshl_add_u64 v[152:153], s[26:27], 0, v[132:133]
	s_mov_b32 m0, s45
	ds_read_b128 v[188:191], v158 offset:16384
	ds_read_b128 v[192:195], v158 offset:17408
	ds_read_b128 v[196:199], v158 offset:18432
	ds_read_b128 v[200:203], v158 offset:19456
	ds_read_b128 v[204:207], v158 offset:20480
	ds_read_b128 v[208:211], v158 offset:21504
	ds_read_b128 v[212:215], v158 offset:22528
	ds_read_b128 v[216:219], v158 offset:23552
	global_load_lds_dwordx4 v[152:153], off
	s_add_i32 m0, s45, 0x2000
	s_add_u32 s46, s26, 0x40000
	v_lshl_add_u64 v[220:221], s[26:27], 0, v[136:137]
	s_addc_u32 s47, s27, 0
	s_add_i32 s45, s39, s2
	global_load_lds_dwordx4 v[220:221], off
	v_lshl_add_u64 v[222:223], s[46:47], 0, v[132:133]
	s_mov_b32 m0, s45
	v_lshl_add_u64 v[224:225], s[28:29], 0, v[134:135]
	global_load_lds_dwordx4 v[222:223], off
	v_lshl_add_u64 v[222:223], s[46:47], 0, v[136:137]
	s_add_i32 m0, s45, 0x2000
	s_nop 0
	global_load_lds_dwordx4 v[222:223], off
	v_lshl_add_u64 v[222:223], s[28:29], 0, v[130:131]
	s_mov_b32 m0, s3
	s_nop 0
	global_load_lds_dwordx4 v[222:223], off
	s_mov_b32 m0, s30
	s_nop 0
	global_load_lds_dwordx4 v[224:225], off
	s_waitcnt vmcnt(8)
	s_waitcnt lgkmcnt(0)
	s_barrier
; #define PG8_STAGE(bufoff, gbase, voff) do { _Pragma("unroll") for (int _i = 0; _i < 2; ++_i) \
;         __builtin_amdgcn_global_load_lds((const unsigned*)((const char*)(gbase) + (voff)[_i]), (PG8_LAS unsigned*)(lds + (bufoff) + ldsw + _i * 8192), 16, 0, 0); } while (0)
; #define PG8_LDA(dst, b, h) do { _Pragma("unroll") for (int m = 0; m < 4; ++m) _Pragma("unroll") for (int k = 0; k < 2; ++k) dst[m][k] = *(const PG8_LAS bf16x8*)(lds + PG8_SA(b, h) + aoff + m * 2048 + k * 1024); } while (0)
; #define PG8_LDB(dst, b, h) do { _Pragma("unroll") for (int n = 0; n < 2; ++n) _Pragma("unroll") for (int k = 0; k < 2; ++k) dst[n][k] = *(const PG8_LAS bf16x8*)(lds + PG8_SB(b, h) + boff + n * 2048 + k * 1024); } while (0)
; #define PG8_MMA(ai, bj, At, Bt) do { __builtin_amdgcn_s_setprio(1); _Pragma("unroll") for (int m = 0; m < 4; ++m) _Pragma("unroll") for (int n = 0; n < 2; ++n) _Pragma("unroll") for (int k = 0; k < 2; ++k) \
;         acc[ai][bj][m][n] = __builtin_amdgcn_mfma_f32_16x16x32_bf16(Bt[n][k], At[m][k], acc[ai][bj][m][n], 0, 0, 0); __builtin_amdgcn_s_setprio(0); } while (0)
; #define PG8_WAIT_V(n) asm volatile("s_waitcnt vmcnt(" #n ")" ::: "memory")
; #define PG8_WAIT_L(n) asm volatile("s_waitcnt lgkmcnt(" #n ")" ::: "memory")
; #define PG8_BAR __builtin_amdgcn_s_barrier()
; #define PG8_SCHED __builtin_amdgcn_sched_barrier(0)
; template <class Epi, class Sched, bool ALIGN_EPI = false, bool SP2 = false>
; __device__ __forceinline__ void gemm_phase(PG8_LAS unsigned char* lds, const Gemm g, const Sched& S, const Epi& E) {
;     ...
;             PG8_WAIT_V(8); PG8_WAIT_L(0); PG8_BAR; PG8_MMA(1, 0, At, B0); PG8_MMA(1, 1, At, B1); PG8_BAR; PG8_SCHED;
;             PG8_LDB(B0, 1, 0); PG8_LDB(B1, 1, 1); PG8_SCHED; PG8_LDA(At, 1, 0); PG8_STAGE(PG8_SA(0, 1), a2 + hstep, voffA);
;             PG8_WAIT_V(8); PG8_WAIT_L(0); PG8_BAR; PG8_MMA(0, 0, At, B0); PG8_MMA(0, 1, At, B1); PG8_BAR; PG8_SCHED;
	s_setprio 1
	s_waitcnt lgkmcnt(0)
	v_mfma_f32_16x16x32_bf16 v[62:65], v[148:151], v[188:191], v[62:65]
	v_mfma_f32_16x16x32_bf16 v[58:61], v[164:167], v[188:191], v[58:61]
	v_mfma_f32_16x16x32_bf16 v[46:49], v[148:151], v[196:199], v[46:49]
	v_mfma_f32_16x16x32_bf16 v[42:45], v[164:167], v[196:199], v[42:45]
	v_mfma_f32_16x16x32_bf16 v[30:33], v[148:151], v[204:207], v[30:33]
	v_mfma_f32_16x16x32_bf16 v[26:29], v[164:167], v[204:207], v[26:29]
	v_mfma_f32_16x16x32_bf16 v[14:17], v[148:151], v[212:215], v[14:17]
	v_mfma_f32_16x16x32_bf16 v[10:13], v[164:167], v[212:215], v[10:13]
	v_mfma_f32_16x16x32_bf16 v[62:65], v[160:163], v[192:195], v[62:65]
	v_mfma_f32_16x16x32_bf16 v[58:61], v[168:171], v[192:195], v[58:61]
	v_mfma_f32_16x16x32_bf16 v[46:49], v[160:163], v[200:203], v[46:49]
	v_mfma_f32_16x16x32_bf16 v[42:45], v[168:171], v[200:203], v[42:45]
	v_mfma_f32_16x16x32_bf16 v[30:33], v[160:163], v[208:211], v[30:33]
	v_mfma_f32_16x16x32_bf16 v[26:29], v[168:171], v[208:211], v[26:29]
	v_mfma_f32_16x16x32_bf16 v[14:17], v[160:163], v[216:219], v[14:17]
	v_mfma_f32_16x16x32_bf16 v[10:13], v[168:171], v[216:219], v[10:13]
	v_mfma_f32_16x16x32_bf16 v[54:57], v[172:175], v[188:191], v[54:57]
	v_mfma_f32_16x16x32_bf16 v[50:53], v[180:183], v[188:191], v[50:53]
	v_mfma_f32_16x16x32_bf16 v[38:41], v[172:175], v[196:199], v[38:41]
	v_mfma_f32_16x16x32_bf16 v[34:37], v[180:183], v[196:199], v[34:37]
	v_mfma_f32_16x16x32_bf16 v[22:25], v[172:175], v[204:207], v[22:25]
	v_mfma_f32_16x16x32_bf16 v[18:21], v[180:183], v[204:207], v[18:21]
	v_mfma_f32_16x16x32_bf16 v[6:9], v[172:175], v[212:215], v[6:9]
	v_mfma_f32_16x16x32_bf16 v[2:5], v[180:183], v[212:215], v[2:5]
	v_mfma_f32_16x16x32_bf16 v[54:57], v[176:179], v[192:195], v[54:57]
	v_mfma_f32_16x16x32_bf16 v[50:53], v[184:187], v[192:195], v[50:53]
	v_mfma_f32_16x16x32_bf16 v[38:41], v[176:179], v[200:203], v[38:41]
	v_mfma_f32_16x16x32_bf16 v[34:37], v[184:187], v[200:203], v[34:37]
	v_mfma_f32_16x16x32_bf16 v[22:25], v[176:179], v[208:211], v[22:25]
	v_mfma_f32_16x16x32_bf16 v[18:21], v[184:187], v[208:211], v[18:21]
	v_mfma_f32_16x16x32_bf16 v[6:9], v[176:179], v[216:219], v[6:9]
	v_mfma_f32_16x16x32_bf16 v[2:5], v[184:187], v[216:219], v[2:5]
	s_setprio 0
	s_barrier
	s_add_i32 s45, 0, 0x18000
	v_add_u32_e32 v159, s45, v1
	s_add_i32 s46, 0, 0x1c000
	ds_read_b128 v[148:151], v159
	ds_read_b128 v[160:163], v159 offset:1024
	ds_read_b128 v[164:167], v159 offset:2048
	ds_read_b128 v[168:171], v159 offset:3072
	v_add_u32_e32 v159, s46, v1
	ds_read_b128 v[172:175], v159
	ds_read_b128 v[176:179], v159 offset:1024
	ds_read_b128 v[180:183], v159 offset:2048
	ds_read_b128 v[184:187], v159 offset:3072
	s_add_u32 s28, s28, 0x40000
	s_addc_u32 s29, s29, 0
	s_mov_b32 m0, s31
	v_lshl_add_u64 v[226:227], s[28:29], 0, v[130:131]
	ds_read_b128 v[188:191], v158 offset:32768
	ds_read_b128 v[192:195], v158 offset:33792
	ds_read_b128 v[196:199], v158 offset:34816
	ds_read_b128 v[200:203], v158 offset:35840
	ds_read_b128 v[204:207], v158 offset:36864
	ds_read_b128 v[208:211], v158 offset:37888
	ds_read_b128 v[212:215], v158 offset:38912
	ds_read_b128 v[216:219], v158 offset:39936
	global_load_lds_dwordx4 v[226:227], off
	v_lshl_add_u64 v[226:227], s[28:29], 0, v[134:135]
	s_mov_b32 m0, s33
	s_nop 0
	global_load_lds_dwordx4 v[226:227], off
	s_waitcnt vmcnt(8)
	s_waitcnt lgkmcnt(0)
	s_barrier
	s_setprio 1
	s_waitcnt lgkmcnt(0)
	v_mfma_f32_16x16x32_bf16 v[126:129], v[148:151], v[188:191], v[126:129]
	v_mfma_f32_16x16x32_bf16 v[122:125], v[164:167], v[188:191], v[122:125]
	v_mfma_f32_16x16x32_bf16 v[110:113], v[148:151], v[196:199], v[110:113]
	v_mfma_f32_16x16x32_bf16 v[106:109], v[164:167], v[196:199], v[106:109]
	v_mfma_f32_16x16x32_bf16 v[94:97], v[148:151], v[204:207], v[94:97]
	v_mfma_f32_16x16x32_bf16 v[90:93], v[164:167], v[204:207], v[90:93]
	v_mfma_f32_16x16x32_bf16 v[78:81], v[148:151], v[212:215], v[78:81]
	v_mfma_f32_16x16x32_bf16 v[74:77], v[164:167], v[212:215], v[74:77]
	v_mfma_f32_16x16x32_bf16 v[126:129], v[160:163], v[192:195], v[126:129]
	v_mfma_f32_16x16x32_bf16 v[122:125], v[168:171], v[192:195], v[122:125]
	v_mfma_f32_16x16x32_bf16 v[110:113], v[160:163], v[200:203], v[110:113]
	v_mfma_f32_16x16x32_bf16 v[106:109], v[168:171], v[200:203], v[106:109]
	v_mfma_f32_16x16x32_bf16 v[94:97], v[160:163], v[208:211], v[94:97]
	v_mfma_f32_16x16x32_bf16 v[90:93], v[168:171], v[208:211], v[90:93]
	v_mfma_f32_16x16x32_bf16 v[78:81], v[160:163], v[216:219], v[78:81]
	v_mfma_f32_16x16x32_bf16 v[74:77], v[168:171], v[216:219], v[74:77]
	v_mfma_f32_16x16x32_bf16 v[118:121], v[172:175], v[188:191], v[118:121]
	v_mfma_f32_16x16x32_bf16 v[114:117], v[180:183], v[188:191], v[114:117]
	v_mfma_f32_16x16x32_bf16 v[102:105], v[172:175], v[196:199], v[102:105]
	v_mfma_f32_16x16x32_bf16 v[98:101], v[180:183], v[196:199], v[98:101]
	v_mfma_f32_16x16x32_bf16 v[86:89], v[172:175], v[204:207], v[86:89]
	v_mfma_f32_16x16x32_bf16 v[82:85], v[180:183], v[204:207], v[82:85]
	v_mfma_f32_16x16x32_bf16 v[70:73], v[172:175], v[212:215], v[70:73]
	v_mfma_f32_16x16x32_bf16 v[66:69], v[180:183], v[212:215], v[66:69]
	v_mfma_f32_16x16x32_bf16 v[118:121], v[176:179], v[192:195], v[118:121]
	v_mfma_f32_16x16x32_bf16 v[114:117], v[184:187], v[192:195], v[114:117]
	v_mfma_f32_16x16x32_bf16 v[102:105], v[176:179], v[200:203], v[102:105]
	v_mfma_f32_16x16x32_bf16 v[98:101], v[184:187], v[200:203], v[98:101]
	v_mfma_f32_16x16x32_bf16 v[86:89], v[176:179], v[208:211], v[86:89]
	v_mfma_f32_16x16x32_bf16 v[82:85], v[184:187], v[208:211], v[82:85]
	v_mfma_f32_16x16x32_bf16 v[70:73], v[176:179], v[216:219], v[70:73]
	v_mfma_f32_16x16x32_bf16 v[66:69], v[184:187], v[216:219], v[66:69]
	s_setprio 0
	s_barrier
; #define PG8_STAGE(bufoff, gbase, voff) do { _Pragma("unroll") for (int _i = 0; _i < 2; ++_i) \
;         __builtin_amdgcn_global_load_lds((const unsigned*)((const char*)(gbase) + (voff)[_i]), (PG8_LAS unsigned*)(lds + (bufoff) + ldsw + _i * 8192), 16, 0, 0); } while (0)
; #define PG8_LDA(dst, b, h) do { _Pragma("unroll") for (int m = 0; m < 4; ++m) _Pragma("unroll") for (int k = 0; k < 2; ++k) dst[m][k] = *(const PG8_LAS bf16x8*)(lds + PG8_SA(b, h) + aoff + m * 2048 + k * 1024); } while (0)
; #define PG8_MMA(ai, bj, At, Bt) do { __builtin_amdgcn_s_setprio(1); _Pragma("unroll") for (int m = 0; m < 4; ++m) _Pragma("unroll") for (int n = 0; n < 2; ++n) _Pragma("unroll") for (int k = 0; k < 2; ++k) \
;         acc[ai][bj][m][n] = __builtin_amdgcn_mfma_f32_16x16x32_bf16(Bt[n][k], At[m][k], acc[ai][bj][m][n], 0, 0, 0); __builtin_amdgcn_s_setprio(0); } while (0)
; #define PG8_WAIT_V(n) asm volatile("s_waitcnt vmcnt(" #n ")" ::: "memory")
; #define PG8_WAIT_L(n) asm volatile("s_waitcnt lgkmcnt(" #n ")" ::: "memory")
; #define PG8_BAR __builtin_amdgcn_s_barrier()
; #define PG8_SCHED __builtin_amdgcn_sched_barrier(0)
; template <class Epi, class Sched, bool ALIGN_EPI = false, bool SP2 = false>
; __device__ __forceinline__ void gemm_phase(PG8_LAS unsigned char* lds, const Gemm g, const Sched& S, const Epi& E) {
;     ...
;             PG8_LDA(At, 1, 1); PG8_STAGE(PG8_SB(1, 0), b3, voffB); PG8_STAGE(PG8_SB(1, 1), b3 + hstep, voffB); PG8_STAGE(PG8_SA(1, 0), a3, voffA);
;             PG8_WAIT_V(8); PG8_WAIT_L(0); PG8_BAR; PG8_MMA(1, 0, At, B0); PG8_MMA(1, 1, At, B1); PG8_BAR; PG8_SCHED;
	s_add_i32 s28, s45, s2
	v_lshl_add_u64 v[152:153], v[152:153], 0, s[10:11]
	s_mov_b32 m0, s28
	ds_read_b128 v[188:191], v158 offset:49152
	ds_read_b128 v[192:195], v158 offset:50176
	ds_read_b128 v[196:199], v158 offset:51200
	ds_read_b128 v[200:203], v158 offset:52224
	ds_read_b128 v[204:207], v158 offset:53248
	ds_read_b128 v[208:211], v158 offset:54272
	ds_read_b128 v[212:215], v158 offset:55296
	ds_read_b128 v[216:219], v158 offset:56320
	global_load_lds_dwordx4 v[152:153], off
	s_add_i32 m0, s28, 0x2000
	s_add_u32 s26, s26, 0x40080
	v_lshl_add_u64 v[152:153], v[220:221], 0, s[10:11]
	s_addc_u32 s27, s27, 0
	s_add_i32 s28, s46, s2
	global_load_lds_dwordx4 v[152:153], off
	v_lshl_add_u64 v[152:153], s[26:27], 0, v[132:133]
	s_mov_b32 m0, s28
	s_nop 0
	global_load_lds_dwordx4 v[152:153], off
	v_lshl_add_u64 v[152:153], s[26:27], 0, v[136:137]
	s_add_i32 m0, s28, 0x2000
	s_nop 0
	global_load_lds_dwordx4 v[152:153], off
	v_lshl_add_u64 v[152:153], v[222:223], 0, s[10:11]
	s_mov_b32 m0, s35
	s_nop 0
	global_load_lds_dwordx4 v[152:153], off
	v_lshl_add_u64 v[152:153], v[224:225], 0, s[10:11]
	s_mov_b32 m0, s36
	s_nop 0
	global_load_lds_dwordx4 v[152:153], off
	s_waitcnt vmcnt(8)
	s_waitcnt lgkmcnt(0)
	s_barrier
	s_setprio 1
	s_waitcnt lgkmcnt(0)
	v_mfma_f32_16x16x32_bf16 v[62:65], v[148:151], v[188:191], v[62:65]
	v_mfma_f32_16x16x32_bf16 v[58:61], v[164:167], v[188:191], v[58:61]
	v_mfma_f32_16x16x32_bf16 v[46:49], v[148:151], v[196:199], v[46:49]
	v_mfma_f32_16x16x32_bf16 v[42:45], v[164:167], v[196:199], v[42:45]
	v_mfma_f32_16x16x32_bf16 v[30:33], v[148:151], v[204:207], v[30:33]
	v_mfma_f32_16x16x32_bf16 v[26:29], v[164:167], v[204:207], v[26:29]
	v_mfma_f32_16x16x32_bf16 v[14:17], v[148:151], v[212:215], v[14:17]
	v_mfma_f32_16x16x32_bf16 v[10:13], v[164:167], v[212:215], v[10:13]
	v_mfma_f32_16x16x32_bf16 v[62:65], v[160:163], v[192:195], v[62:65]
	v_mfma_f32_16x16x32_bf16 v[58:61], v[168:171], v[192:195], v[58:61]
	v_mfma_f32_16x16x32_bf16 v[46:49], v[160:163], v[200:203], v[46:49]
	v_mfma_f32_16x16x32_bf16 v[42:45], v[168:171], v[200:203], v[42:45]
	v_mfma_f32_16x16x32_bf16 v[30:33], v[160:163], v[208:211], v[30:33]
	v_mfma_f32_16x16x32_bf16 v[26:29], v[168:171], v[208:211], v[26:29]
	v_mfma_f32_16x16x32_bf16 v[14:17], v[160:163], v[216:219], v[14:17]
	v_mfma_f32_16x16x32_bf16 v[10:13], v[168:171], v[216:219], v[10:13]
	v_mfma_f32_16x16x32_bf16 v[54:57], v[172:175], v[188:191], v[54:57]
	v_mfma_f32_16x16x32_bf16 v[50:53], v[180:183], v[188:191], v[50:53]
	v_mfma_f32_16x16x32_bf16 v[38:41], v[172:175], v[196:199], v[38:41]
	v_mfma_f32_16x16x32_bf16 v[34:37], v[180:183], v[196:199], v[34:37]
	v_mfma_f32_16x16x32_bf16 v[22:25], v[172:175], v[204:207], v[22:25]
	v_mfma_f32_16x16x32_bf16 v[18:21], v[180:183], v[204:207], v[18:21]
	v_mfma_f32_16x16x32_bf16 v[6:9], v[172:175], v[212:215], v[6:9]
	v_mfma_f32_16x16x32_bf16 v[2:5], v[180:183], v[212:215], v[2:5]
	v_mfma_f32_16x16x32_bf16 v[54:57], v[176:179], v[192:195], v[54:57]
	v_mfma_f32_16x16x32_bf16 v[50:53], v[184:187], v[192:195], v[50:53]
	v_mfma_f32_16x16x32_bf16 v[38:41], v[176:179], v[200:203], v[38:41]
	v_mfma_f32_16x16x32_bf16 v[34:37], v[184:187], v[200:203], v[34:37]
	v_mfma_f32_16x16x32_bf16 v[22:25], v[176:179], v[208:211], v[22:25]
	v_mfma_f32_16x16x32_bf16 v[18:21], v[184:187], v[208:211], v[18:21]
	v_mfma_f32_16x16x32_bf16 v[6:9], v[176:179], v[216:219], v[6:9]
	v_mfma_f32_16x16x32_bf16 v[2:5], v[184:187], v[216:219], v[2:5]
	s_setprio 0
	s_barrier
	s_add_i32 s44, s44, 2
	s_add_u32 s24, s24, 0x100
	s_addc_u32 s25, s25, 0
	s_add_u32 s42, s42, 0x100
	s_addc_u32 s43, s43, 0
	s_cmp_gt_u32 s44, 13
	s_cbranch_scc0 .LBB0_2559
	s_and_b64 vcc, exec, s[12:13]
	s_cbranch_vccz .LBB0_2562
	s_barrier

; #define PG8_STAGE(bufoff, gbase, voff) do { _Pragma("unroll") for (int _i = 0; _i < 2; ++_i) \
;         __builtin_amdgcn_global_load_lds((const unsigned*)((const char*)(gbase) + (voff)[_i]), (PG8_LAS unsigned*)(lds + (bufoff) + ldsw + _i * 8192), 16, 0, 0); } while (0)
; #define PG8_LDA(dst, b, h) do { _Pragma("unroll") for (int m = 0; m < 4; ++m) _Pragma("unroll") for (int k = 0; k < 2; ++k) dst[m][k] = *(const PG8_LAS bf16x8*)(lds + PG8_SA(b, h) + aoff + m * 2048 + k * 1024); } while (0)
; #define PG8_LDB(dst, b, h) do { _Pragma("unroll") for (int n = 0; n < 2; ++n) _Pragma("unroll") for (int k = 0; k < 2; ++k) dst[n][k] = *(const PG8_LAS bf16x8*)(lds + PG8_SB(b, h) + boff + n * 2048 + k * 1024); } while (0)
; #define PG8_MMA(ai, bj, At, Bt) do { __builtin_amdgcn_s_setprio(1); _Pragma("unroll") for (int m = 0; m < 4; ++m) _Pragma("unroll") for (int n = 0; n < 2; ++n) _Pragma("unroll") for (int k = 0; k < 2; ++k) \
;         acc[ai][bj][m][n] = __builtin_amdgcn_mfma_f32_16x16x32_bf16(Bt[n][k], At[m][k], acc[ai][bj][m][n], 0, 0, 0); __builtin_amdgcn_s_setprio(0); } while (0)
; #define PG8_WAIT_V(n) asm volatile("s_waitcnt vmcnt(" #n ")" ::: "memory")
; #define PG8_WAIT_L(n) asm volatile("s_waitcnt lgkmcnt(" #n ")" ::: "memory")
; #define PG8_BAR __builtin_amdgcn_s_barrier()
; #define PG8_SCHED __builtin_amdgcn_sched_barrier(0)
; template <class Epi, class Sched, bool ALIGN_EPI = false, bool SP2 = false>
; __device__ __forceinline__ void gemm_phase(PG8_LAS unsigned char* lds, const Gemm g, const Sched& S, const Epi& E) {
;     ...
;             PG8_LDB(B0, 0, 0); PG8_LDB(B1, 0, 1); PG8_SCHED; PG8_LDA(At, 0, 0); PG8_STAGE(PG8_SA(1, 1), a1 + hstep, voffA);
;             PG8_WAIT_V(8); PG8_WAIT_L(0); PG8_BAR; PG8_MMA(0, 0, At, B0); PG8_MMA(0, 1, At, B1); PG8_BAR; PG8_SCHED;
;             PG8_LDA(At, 0, 1); PG8_STAGE(PG8_SB(0, 0), b2, voffB); PG8_STAGE(PG8_SB(0, 1), b2 + hstep, voffB); PG8_STAGE(PG8_SA(0, 0), a2, voffA);
.LBB0_2642:
	ds_read_b128 v[152:155], v149
	ds_read_b128 v[156:159], v149 offset:1024
	ds_read_b128 v[160:163], v149 offset:2048
	ds_read_b128 v[164:167], v149 offset:3072
	ds_read_b128 v[168:171], v150
	ds_read_b128 v[172:175], v150 offset:1024
	ds_read_b128 v[176:179], v150 offset:2048
	ds_read_b128 v[180:183], v150 offset:3072
	s_add_u32 s30, s28, 0xfff80080
	s_addc_u32 s31, s29, -1
	s_cmp_eq_u32 s51, 28
	s_cselect_b32 s35, s21, s31
	s_cselect_b32 s34, s45, s30
	s_cselect_b32 s31, s19, s50
	s_cselect_b32 s30, s46, s47
	v_lshl_add_u64 v[216:217], s[28:29], 0, v[138:139]
	s_add_i32 m0, s3, 0xc000
	ds_read_b128 v[184:187], v151
	ds_read_b128 v[188:191], v151 offset:1024
	ds_read_b128 v[192:195], v151 offset:2048
	ds_read_b128 v[196:199], v151 offset:3072
	ds_read_b128 v[200:203], v151 offset:4096
	ds_read_b128 v[204:207], v151 offset:5120
	ds_read_b128 v[208:211], v151 offset:6144
	ds_read_b128 v[212:215], v151 offset:7168
	global_load_lds_dwordx4 v[216:217], off
	v_lshl_add_u64 v[216:217], s[28:29], 0, v[140:141]
	s_add_i32 m0, s3, 0xe000
	s_nop 0
	global_load_lds_dwordx4 v[216:217], off
	s_waitcnt vmcnt(8)
	s_waitcnt lgkmcnt(0)
	s_barrier
	s_setprio 1
	s_waitcnt lgkmcnt(0)
	v_mfma_f32_16x16x32_bf16 v[126:129], v[152:155], v[184:187], v[126:129]
	v_mfma_f32_16x16x32_bf16 v[122:125], v[160:163], v[184:187], v[122:125]
	v_mfma_f32_16x16x32_bf16 v[118:121], v[152:155], v[192:195], v[118:121]
	v_mfma_f32_16x16x32_bf16 v[110:113], v[160:163], v[192:195], v[110:113]
	v_mfma_f32_16x16x32_bf16 v[102:105], v[152:155], v[200:203], v[102:105]
	v_mfma_f32_16x16x32_bf16 v[94:97], v[160:163], v[200:203], v[94:97]
	v_mfma_f32_16x16x32_bf16 v[86:89], v[152:155], v[208:211], v[86:89]
	v_mfma_f32_16x16x32_bf16 v[78:81], v[160:163], v[208:211], v[78:81]
	v_mfma_f32_16x16x32_bf16 v[126:129], v[156:159], v[188:191], v[126:129]
	v_mfma_f32_16x16x32_bf16 v[122:125], v[164:167], v[188:191], v[122:125]
	v_mfma_f32_16x16x32_bf16 v[118:121], v[156:159], v[196:199], v[118:121]
	v_mfma_f32_16x16x32_bf16 v[110:113], v[164:167], v[196:199], v[110:113]
	v_mfma_f32_16x16x32_bf16 v[102:105], v[156:159], v[204:207], v[102:105]
	v_mfma_f32_16x16x32_bf16 v[94:97], v[164:167], v[204:207], v[94:97]
	v_mfma_f32_16x16x32_bf16 v[86:89], v[156:159], v[212:215], v[86:89]
	v_mfma_f32_16x16x32_bf16 v[78:81], v[164:167], v[212:215], v[78:81]
	v_mfma_f32_16x16x32_bf16 v[114:117], v[168:171], v[184:187], v[114:117]
	v_mfma_f32_16x16x32_bf16 v[106:109], v[176:179], v[184:187], v[106:109]
	v_mfma_f32_16x16x32_bf16 v[98:101], v[168:171], v[192:195], v[98:101]
	v_mfma_f32_16x16x32_bf16 v[90:93], v[176:179], v[192:195], v[90:93]
	v_mfma_f32_16x16x32_bf16 v[82:85], v[168:171], v[200:203], v[82:85]
	v_mfma_f32_16x16x32_bf16 v[74:77], v[176:179], v[200:203], v[74:77]
	v_mfma_f32_16x16x32_bf16 v[70:73], v[168:171], v[208:211], v[70:73]
	v_mfma_f32_16x16x32_bf16 v[66:69], v[176:179], v[208:211], v[66:69]
	v_mfma_f32_16x16x32_bf16 v[114:117], v[172:175], v[188:191], v[114:117]
	v_mfma_f32_16x16x32_bf16 v[106:109], v[180:183], v[188:191], v[106:109]
	v_mfma_f32_16x16x32_bf16 v[98:101], v[172:175], v[196:199], v[98:101]
	v_mfma_f32_16x16x32_bf16 v[90:93], v[180:183], v[196:199], v[90:93]
	v_mfma_f32_16x16x32_bf16 v[82:85], v[172:175], v[204:207], v[82:85]
	v_mfma_f32_16x16x32_bf16 v[74:77], v[180:183], v[204:207], v[74:77]
	v_mfma_f32_16x16x32_bf16 v[70:73], v[172:175], v[212:215], v[70:73]
	v_mfma_f32_16x16x32_bf16 v[66:69], v[180:183], v[212:215], v[66:69]
	s_setprio 0
	s_barrier
	s_add_i32 s52, s40, s2
	v_lshl_add_u64 v[216:217], s[30:31], 0, v[132:133]
	s_mov_b32 m0, s52
	ds_read_b128 v[184:187], v151 offset:16384
	ds_read_b128 v[188:191], v151 offset:17408
	ds_read_b128 v[192:195], v151 offset:18432
	ds_read_b128 v[196:199], v151 offset:19456
	ds_read_b128 v[200:203], v151 offset:20480
	ds_read_b128 v[204:207], v151 offset:21504
	ds_read_b128 v[208:211], v151 offset:22528
	ds_read_b128 v[212:215], v151 offset:23552
	global_load_lds_dwordx4 v[216:217], off
	s_add_i32 m0, s52, 0x2000
	s_add_u32 s52, s30, 0x80000
	v_lshl_add_u64 v[218:219], s[30:31], 0, v[136:137]
	s_addc_u32 s53, s31, 0
	s_add_i32 s54, s41, s2
	global_load_lds_dwordx4 v[218:219], off
	v_lshl_add_u64 v[220:221], s[52:53], 0, v[132:133]
	s_mov_b32 m0, s54
	v_lshl_add_u64 v[222:223], s[34:35], 0, v[134:135]
	global_load_lds_dwordx4 v[220:221], off
	v_lshl_add_u64 v[220:221], s[52:53], 0, v[136:137]
	s_add_i32 m0, s54, 0x2000
	s_nop 0
	global_load_lds_dwordx4 v[220:221], off
	v_lshl_add_u64 v[220:221], s[34:35], 0, v[130:131]
	s_mov_b32 m0, s3
	s_nop 0
	global_load_lds_dwordx4 v[220:221], off
	s_mov_b32 m0, s27
	s_nop 0
	global_load_lds_dwordx4 v[222:223], off
	s_waitcnt vmcnt(8)
	s_waitcnt lgkmcnt(0)
	s_barrier
; #define PG8_STAGE(bufoff, gbase, voff) do { _Pragma("unroll") for (int _i = 0; _i < 2; ++_i) \
;         __builtin_amdgcn_global_load_lds((const unsigned*)((const char*)(gbase) + (voff)[_i]), (PG8_LAS unsigned*)(lds + (bufoff) + ldsw + _i * 8192), 16, 0, 0); } while (0)
; #define PG8_LDA(dst, b, h) do { _Pragma("unroll") for (int m = 0; m < 4; ++m) _Pragma("unroll") for (int k = 0; k < 2; ++k) dst[m][k] = *(const PG8_LAS bf16x8*)(lds + PG8_SA(b, h) + aoff + m * 2048 + k * 1024); } while (0)
; #define PG8_LDB(dst, b, h) do { _Pragma("unroll") for (int n = 0; n < 2; ++n) _Pragma("unroll") for (int k = 0; k < 2; ++k) dst[n][k] = *(const PG8_LAS bf16x8*)(lds + PG8_SB(b, h) + boff + n * 2048 + k * 1024); } while (0)
; #define PG8_MMA(ai, bj, At, Bt) do { __builtin_amdgcn_s_setprio(1); _Pragma("unroll") for (int m = 0; m < 4; ++m) _Pragma("unroll") for (int n = 0; n < 2; ++n) _Pragma("unroll") for (int k = 0; k < 2; ++k) \
;         acc[ai][bj][m][n] = __builtin_amdgcn_mfma_f32_16x16x32_bf16(Bt[n][k], At[m][k], acc[ai][bj][m][n], 0, 0, 0); __builtin_amdgcn_s_setprio(0); } while (0)
; #define PG8_WAIT_V(n) asm volatile("s_waitcnt vmcnt(" #n ")" ::: "memory")
; #define PG8_WAIT_L(n) asm volatile("s_waitcnt lgkmcnt(" #n ")" ::: "memory")
; #define PG8_BAR __builtin_amdgcn_s_barrier()
; #define PG8_SCHED __builtin_amdgcn_sched_barrier(0)
; template <class Epi, class Sched, bool ALIGN_EPI = false, bool SP2 = false>
; __device__ __forceinline__ void gemm_phase(PG8_LAS unsigned char* lds, const Gemm g, const Sched& S, const Epi& E) {
;     ...
;             PG8_WAIT_V(8); PG8_WAIT_L(0); PG8_BAR; PG8_MMA(1, 0, At, B0); PG8_MMA(1, 1, At, B1); PG8_BAR; PG8_SCHED;
;             PG8_LDB(B0, 1, 0); PG8_LDB(B1, 1, 1); PG8_SCHED; PG8_LDA(At, 1, 0); PG8_STAGE(PG8_SA(0, 1), a2 + hstep, voffA);
;             PG8_WAIT_V(8); PG8_WAIT_L(0); PG8_BAR; PG8_MMA(0, 0, At, B0); PG8_MMA(0, 1, At, B1); PG8_BAR; PG8_SCHED;
	s_setprio 1
	s_waitcnt lgkmcnt(0)
	v_mfma_f32_16x16x32_bf16 v[62:65], v[152:155], v[184:187], v[62:65]
	v_mfma_f32_16x16x32_bf16 v[58:61], v[160:163], v[184:187], v[58:61]
	v_mfma_f32_16x16x32_bf16 v[54:57], v[152:155], v[192:195], v[54:57]
	v_mfma_f32_16x16x32_bf16 v[46:49], v[160:163], v[192:195], v[46:49]
	v_mfma_f32_16x16x32_bf16 v[38:41], v[152:155], v[200:203], v[38:41]
	v_mfma_f32_16x16x32_bf16 v[34:37], v[160:163], v[200:203], v[34:37]
	v_mfma_f32_16x16x32_bf16 v[22:25], v[152:155], v[208:211], v[22:25]
	v_mfma_f32_16x16x32_bf16 v[18:21], v[160:163], v[208:211], v[18:21]
	v_mfma_f32_16x16x32_bf16 v[62:65], v[156:159], v[188:191], v[62:65]
	v_mfma_f32_16x16x32_bf16 v[58:61], v[164:167], v[188:191], v[58:61]
	v_mfma_f32_16x16x32_bf16 v[54:57], v[156:159], v[196:199], v[54:57]
	v_mfma_f32_16x16x32_bf16 v[46:49], v[164:167], v[196:199], v[46:49]
	v_mfma_f32_16x16x32_bf16 v[38:41], v[156:159], v[204:207], v[38:41]
	v_mfma_f32_16x16x32_bf16 v[34:37], v[164:167], v[204:207], v[34:37]
	v_mfma_f32_16x16x32_bf16 v[22:25], v[156:159], v[212:215], v[22:25]
	v_mfma_f32_16x16x32_bf16 v[18:21], v[164:167], v[212:215], v[18:21]
	v_mfma_f32_16x16x32_bf16 v[50:53], v[168:171], v[184:187], v[50:53]
	v_mfma_f32_16x16x32_bf16 v[42:45], v[176:179], v[184:187], v[42:45]
	v_mfma_f32_16x16x32_bf16 v[30:33], v[168:171], v[192:195], v[30:33]
	v_mfma_f32_16x16x32_bf16 v[26:29], v[176:179], v[192:195], v[26:29]
	v_mfma_f32_16x16x32_bf16 v[14:17], v[168:171], v[200:203], v[14:17]
	v_mfma_f32_16x16x32_bf16 v[10:13], v[176:179], v[200:203], v[10:13]
	v_mfma_f32_16x16x32_bf16 v[6:9], v[168:171], v[208:211], v[6:9]
	v_mfma_f32_16x16x32_bf16 v[2:5], v[176:179], v[208:211], v[2:5]
	v_mfma_f32_16x16x32_bf16 v[50:53], v[172:175], v[188:191], v[50:53]
	v_mfma_f32_16x16x32_bf16 v[42:45], v[180:183], v[188:191], v[42:45]
	v_mfma_f32_16x16x32_bf16 v[30:33], v[172:175], v[196:199], v[30:33]
	v_mfma_f32_16x16x32_bf16 v[26:29], v[180:183], v[196:199], v[26:29]
	v_mfma_f32_16x16x32_bf16 v[14:17], v[172:175], v[204:207], v[14:17]
	v_mfma_f32_16x16x32_bf16 v[10:13], v[180:183], v[204:207], v[10:13]
	v_mfma_f32_16x16x32_bf16 v[6:9], v[172:175], v[212:215], v[6:9]
	v_mfma_f32_16x16x32_bf16 v[2:5], v[180:183], v[212:215], v[2:5]
	s_setprio 0
	s_barrier
	s_add_i32 s52, 0, 0x18000
	s_add_i32 s53, 0, 0x1c000
	v_add_u32_e32 v164, s52, v1
	v_add_u32_e32 v180, s53, v1
	ds_read_b128 v[152:155], v164
	ds_read_b128 v[156:159], v164 offset:1024
	ds_read_b128 v[160:163], v164 offset:2048
	ds_read_b128 v[164:167], v164 offset:3072
	ds_read_b128 v[168:171], v180
	ds_read_b128 v[172:175], v180 offset:1024
	ds_read_b128 v[176:179], v180 offset:2048
	ds_read_b128 v[180:183], v180 offset:3072
	s_add_u32 s34, s34, 0x80000
	s_addc_u32 s35, s35, 0
	s_mov_b32 m0, s33
	v_lshl_add_u64 v[224:225], s[34:35], 0, v[130:131]
	ds_read_b128 v[184:187], v151 offset:32768
	ds_read_b128 v[188:191], v151 offset:33792
	ds_read_b128 v[192:195], v151 offset:34816
	ds_read_b128 v[196:199], v151 offset:35840
	ds_read_b128 v[200:203], v151 offset:36864
	ds_read_b128 v[204:207], v151 offset:37888
	ds_read_b128 v[208:211], v151 offset:38912
	ds_read_b128 v[212:215], v151 offset:39936
	global_load_lds_dwordx4 v[224:225], off
	v_lshl_add_u64 v[224:225], s[34:35], 0, v[134:135]
	s_mov_b32 m0, s36
	s_nop 0
	global_load_lds_dwordx4 v[224:225], off
	s_waitcnt vmcnt(8)
	s_waitcnt lgkmcnt(0)
	s_barrier
	s_setprio 1
	s_waitcnt lgkmcnt(0)
	v_mfma_f32_16x16x32_bf16 v[126:129], v[152:155], v[184:187], v[126:129]
	v_mfma_f32_16x16x32_bf16 v[122:125], v[160:163], v[184:187], v[122:125]
	v_mfma_f32_16x16x32_bf16 v[118:121], v[152:155], v[192:195], v[118:121]
	v_mfma_f32_16x16x32_bf16 v[110:113], v[160:163], v[192:195], v[110:113]
	v_mfma_f32_16x16x32_bf16 v[102:105], v[152:155], v[200:203], v[102:105]
	v_mfma_f32_16x16x32_bf16 v[94:97], v[160:163], v[200:203], v[94:97]
	v_mfma_f32_16x16x32_bf16 v[86:89], v[152:155], v[208:211], v[86:89]
	v_mfma_f32_16x16x32_bf16 v[78:81], v[160:163], v[208:211], v[78:81]
	v_mfma_f32_16x16x32_bf16 v[126:129], v[156:159], v[188:191], v[126:129]
	v_mfma_f32_16x16x32_bf16 v[122:125], v[164:167], v[188:191], v[122:125]
	v_mfma_f32_16x16x32_bf16 v[118:121], v[156:159], v[196:199], v[118:121]
	v_mfma_f32_16x16x32_bf16 v[110:113], v[164:167], v[196:199], v[110:113]
	v_mfma_f32_16x16x32_bf16 v[102:105], v[156:159], v[204:207], v[102:105]
	v_mfma_f32_16x16x32_bf16 v[94:97], v[164:167], v[204:207], v[94:97]
	v_mfma_f32_16x16x32_bf16 v[86:89], v[156:159], v[212:215], v[86:89]
	v_mfma_f32_16x16x32_bf16 v[78:81], v[164:167], v[212:215], v[78:81]
	v_mfma_f32_16x16x32_bf16 v[114:117], v[168:171], v[184:187], v[114:117]
	v_mfma_f32_16x16x32_bf16 v[106:109], v[176:179], v[184:187], v[106:109]
	v_mfma_f32_16x16x32_bf16 v[98:101], v[168:171], v[192:195], v[98:101]
	v_mfma_f32_16x16x32_bf16 v[90:93], v[176:179], v[192:195], v[90:93]
	v_mfma_f32_16x16x32_bf16 v[82:85], v[168:171], v[200:203], v[82:85]
	v_mfma_f32_16x16x32_bf16 v[74:77], v[176:179], v[200:203], v[74:77]
	v_mfma_f32_16x16x32_bf16 v[70:73], v[168:171], v[208:211], v[70:73]
	v_mfma_f32_16x16x32_bf16 v[66:69], v[176:179], v[208:211], v[66:69]
	v_mfma_f32_16x16x32_bf16 v[114:117], v[172:175], v[188:191], v[114:117]
	v_mfma_f32_16x16x32_bf16 v[106:109], v[180:183], v[188:191], v[106:109]
	v_mfma_f32_16x16x32_bf16 v[98:101], v[172:175], v[196:199], v[98:101]
	v_mfma_f32_16x16x32_bf16 v[90:93], v[180:183], v[196:199], v[90:93]
	v_mfma_f32_16x16x32_bf16 v[82:85], v[172:175], v[204:207], v[82:85]
	v_mfma_f32_16x16x32_bf16 v[74:77], v[180:183], v[204:207], v[74:77]
	v_mfma_f32_16x16x32_bf16 v[70:73], v[172:175], v[212:215], v[70:73]
	v_mfma_f32_16x16x32_bf16 v[66:69], v[180:183], v[212:215], v[66:69]
	s_setprio 0
	s_barrier
; #define PG8_STAGE(bufoff, gbase, voff) do { _Pragma("unroll") for (int _i = 0; _i < 2; ++_i) \
;         __builtin_amdgcn_global_load_lds((const unsigned*)((const char*)(gbase) + (voff)[_i]), (PG8_LAS unsigned*)(lds + (bufoff) + ldsw + _i * 8192), 16, 0, 0); } while (0)
; #define PG8_LDA(dst, b, h) do { _Pragma("unroll") for (int m = 0; m < 4; ++m) _Pragma("unroll") for (int k = 0; k < 2; ++k) dst[m][k] = *(const PG8_LAS bf16x8*)(lds + PG8_SA(b, h) + aoff + m * 2048 + k * 1024); } while (0)
; #define PG8_MMA(ai, bj, At, Bt) do { __builtin_amdgcn_s_setprio(1); _Pragma("unroll") for (int m = 0; m < 4; ++m) _Pragma("unroll") for (int n = 0; n < 2; ++n) _Pragma("unroll") for (int k = 0; k < 2; ++k) \
;         acc[ai][bj][m][n] = __builtin_amdgcn_mfma_f32_16x16x32_bf16(Bt[n][k], At[m][k], acc[ai][bj][m][n], 0, 0, 0); __builtin_amdgcn_s_setprio(0); } while (0)
; #define PG8_WAIT_V(n) asm volatile("s_waitcnt vmcnt(" #n ")" ::: "memory")
; #define PG8_WAIT_L(n) asm volatile("s_waitcnt lgkmcnt(" #n ")" ::: "memory")
; #define PG8_BAR __builtin_amdgcn_s_barrier()
; #define PG8_SCHED __builtin_amdgcn_sched_barrier(0)
; template <class Epi, class Sched, bool ALIGN_EPI = false, bool SP2 = false>
; __device__ __forceinline__ void gemm_phase(PG8_LAS unsigned char* lds, const Gemm g, const Sched& S, const Epi& E) {
;     ...
;             PG8_LDA(At, 1, 1); PG8_STAGE(PG8_SB(1, 0), b3, voffB); PG8_STAGE(PG8_SB(1, 1), b3 + hstep, voffB); PG8_STAGE(PG8_SA(1, 0), a3, voffA);
;             PG8_WAIT_V(8); PG8_WAIT_L(0); PG8_BAR; PG8_MMA(1, 0, At, B0); PG8_MMA(1, 1, At, B1); PG8_BAR; PG8_SCHED;
	s_add_i32 s34, s52, s2
	v_lshl_add_u64 v[216:217], v[216:217], 0, s[10:11]
	s_mov_b32 m0, s34
	ds_read_b128 v[184:187], v151 offset:49152
	ds_read_b128 v[188:191], v151 offset:50176
	ds_read_b128 v[192:195], v151 offset:51200
	ds_read_b128 v[196:199], v151 offset:52224
	ds_read_b128 v[200:203], v151 offset:53248
	ds_read_b128 v[204:207], v151 offset:54272
	ds_read_b128 v[208:211], v151 offset:55296
	ds_read_b128 v[212:215], v151 offset:56320
	global_load_lds_dwordx4 v[216:217], off
	s_add_i32 m0, s34, 0x2000
	s_add_u32 s30, s30, 0x80080
	v_lshl_add_u64 v[216:217], v[218:219], 0, s[10:11]
	s_addc_u32 s31, s31, 0
	s_add_i32 s34, s53, s2
	global_load_lds_dwordx4 v[216:217], off
	v_lshl_add_u64 v[216:217], s[30:31], 0, v[132:133]
	s_mov_b32 m0, s34
	s_nop 0
	global_load_lds_dwordx4 v[216:217], off
	v_lshl_add_u64 v[216:217], s[30:31], 0, v[136:137]
	s_add_i32 m0, s34, 0x2000
	s_nop 0
	global_load_lds_dwordx4 v[216:217], off
	v_lshl_add_u64 v[216:217], v[220:221], 0, s[10:11]
	s_mov_b32 m0, s38
	s_nop 0
	global_load_lds_dwordx4 v[216:217], off
	v_lshl_add_u64 v[216:217], v[222:223], 0, s[10:11]
	s_mov_b32 m0, s39
	s_nop 0
	global_load_lds_dwordx4 v[216:217], off
	s_waitcnt vmcnt(8)
	s_waitcnt lgkmcnt(0)
	s_barrier
	s_setprio 1
	s_waitcnt lgkmcnt(0)
	v_mfma_f32_16x16x32_bf16 v[62:65], v[152:155], v[184:187], v[62:65]
	v_mfma_f32_16x16x32_bf16 v[58:61], v[160:163], v[184:187], v[58:61]
	v_mfma_f32_16x16x32_bf16 v[54:57], v[152:155], v[192:195], v[54:57]
	v_mfma_f32_16x16x32_bf16 v[46:49], v[160:163], v[192:195], v[46:49]
	v_mfma_f32_16x16x32_bf16 v[38:41], v[152:155], v[200:203], v[38:41]
	v_mfma_f32_16x16x32_bf16 v[34:37], v[160:163], v[200:203], v[34:37]
	v_mfma_f32_16x16x32_bf16 v[22:25], v[152:155], v[208:211], v[22:25]
	v_mfma_f32_16x16x32_bf16 v[18:21], v[160:163], v[208:211], v[18:21]
	v_mfma_f32_16x16x32_bf16 v[62:65], v[156:159], v[188:191], v[62:65]
	v_mfma_f32_16x16x32_bf16 v[58:61], v[164:167], v[188:191], v[58:61]
	v_mfma_f32_16x16x32_bf16 v[54:57], v[156:159], v[196:199], v[54:57]
	v_mfma_f32_16x16x32_bf16 v[46:49], v[164:167], v[196:199], v[46:49]
	v_mfma_f32_16x16x32_bf16 v[38:41], v[156:159], v[204:207], v[38:41]
	v_mfma_f32_16x16x32_bf16 v[34:37], v[164:167], v[204:207], v[34:37]
	v_mfma_f32_16x16x32_bf16 v[22:25], v[156:159], v[212:215], v[22:25]
	v_mfma_f32_16x16x32_bf16 v[18:21], v[164:167], v[212:215], v[18:21]
	v_mfma_f32_16x16x32_bf16 v[50:53], v[168:171], v[184:187], v[50:53]
	v_mfma_f32_16x16x32_bf16 v[42:45], v[176:179], v[184:187], v[42:45]
	v_mfma_f32_16x16x32_bf16 v[30:33], v[168:171], v[192:195], v[30:33]
	v_mfma_f32_16x16x32_bf16 v[26:29], v[176:179], v[192:195], v[26:29]
	v_mfma_f32_16x16x32_bf16 v[14:17], v[168:171], v[200:203], v[14:17]
	v_mfma_f32_16x16x32_bf16 v[10:13], v[176:179], v[200:203], v[10:13]
	v_mfma_f32_16x16x32_bf16 v[6:9], v[168:171], v[208:211], v[6:9]
	v_mfma_f32_16x16x32_bf16 v[2:5], v[176:179], v[208:211], v[2:5]
	v_mfma_f32_16x16x32_bf16 v[50:53], v[172:175], v[188:191], v[50:53]
	v_mfma_f32_16x16x32_bf16 v[42:45], v[180:183], v[188:191], v[42:45]
	v_mfma_f32_16x16x32_bf16 v[30:33], v[172:175], v[196:199], v[30:33]
	v_mfma_f32_16x16x32_bf16 v[26:29], v[180:183], v[196:199], v[26:29]
	v_mfma_f32_16x16x32_bf16 v[14:17], v[172:175], v[204:207], v[14:17]
	v_mfma_f32_16x16x32_bf16 v[10:13], v[180:183], v[204:207], v[10:13]
	v_mfma_f32_16x16x32_bf16 v[6:9], v[172:175], v[212:215], v[6:9]
	v_mfma_f32_16x16x32_bf16 v[2:5], v[180:183], v[212:215], v[2:5]
	s_setprio 0
	s_barrier
	s_add_i32 s51, s51, 2
	s_add_u32 s28, s28, 0x100
	s_addc_u32 s29, s29, 0
	s_add_u32 s47, s47, 0x100
	s_addc_u32 s50, s50, 0
	s_cmp_gt_u32 s51, 29
	s_cbranch_scc0 .LBB0_2642
	s_and_b64 vcc, exec, s[12:13]
	s_cbranch_vccz .LBB0_2645
	s_barrier

; #define PG8_STAGE(bufoff, gbase, voff) do { _Pragma("unroll") for (int _i = 0; _i < 2; ++_i) \
;         __builtin_amdgcn_global_load_lds((const unsigned*)((const char*)(gbase) + (voff)[_i]), (PG8_LAS unsigned*)(lds + (bufoff) + ldsw + _i * 8192), 16, 0, 0); } while (0)
; #define PG8_LDA(dst, b, h) do { _Pragma("unroll") for (int m = 0; m < 4; ++m) _Pragma("unroll") for (int k = 0; k < 2; ++k) dst[m][k] = *(const PG8_LAS bf16x8*)(lds + PG8_SA(b, h) + aoff + m * 2048 + k * 1024); } while (0)
; #define PG8_LDB(dst, b, h) do { _Pragma("unroll") for (int n = 0; n < 2; ++n) _Pragma("unroll") for (int k = 0; k < 2; ++k) dst[n][k] = *(const PG8_LAS bf16x8*)(lds + PG8_SB(b, h) + boff + n * 2048 + k * 1024); } while (0)
; #define PG8_MMA(ai, bj, At, Bt) do { __builtin_amdgcn_s_setprio(1); _Pragma("unroll") for (int m = 0; m < 4; ++m) _Pragma("unroll") for (int n = 0; n < 2; ++n) _Pragma("unroll") for (int k = 0; k < 2; ++k) \
;         acc[ai][bj][m][n] = __builtin_amdgcn_mfma_f32_16x16x32_bf16(Bt[n][k], At[m][k], acc[ai][bj][m][n], 0, 0, 0); __builtin_amdgcn_s_setprio(0); } while (0)
; #define PG8_WAIT_V(n) asm volatile("s_waitcnt vmcnt(" #n ")" ::: "memory")
; #define PG8_WAIT_L(n) asm volatile("s_waitcnt lgkmcnt(" #n ")" ::: "memory")
; #define PG8_BAR __builtin_amdgcn_s_barrier()
; #define PG8_SCHED __builtin_amdgcn_sched_barrier(0)
; template <class Epi, class Sched, bool ALIGN_EPI = false, bool SP2 = false>
; __device__ __forceinline__ void gemm_phase(PG8_LAS unsigned char* lds, const Gemm g, const Sched& S, const Epi& E) {
;     ...
;             PG8_LDB(B0, 0, 0); PG8_LDB(B1, 0, 1); PG8_SCHED; PG8_LDA(At, 0, 0); PG8_STAGE(PG8_SA(1, 1), a1 + hstep, voffA);
;             PG8_WAIT_V(8); PG8_WAIT_L(0); PG8_BAR; PG8_MMA(0, 0, At, B0); PG8_MMA(0, 1, At, B1); PG8_BAR; PG8_SCHED;
;             PG8_LDA(At, 0, 1); PG8_STAGE(PG8_SB(0, 0), b2, voffB); PG8_STAGE(PG8_SB(0, 1), b2 + hstep, voffB); PG8_STAGE(PG8_SA(0, 0), a2, voffA);
.LBB0_2774:
	ds_read_b128 v[146:149], v153
	ds_read_b128 v[156:159], v153 offset:1024
	ds_read_b128 v[160:163], v153 offset:2048
	ds_read_b128 v[164:167], v153 offset:3072
	ds_read_b128 v[168:171], v154
	ds_read_b128 v[172:175], v154 offset:1024
	ds_read_b128 v[176:179], v154 offset:2048
	ds_read_b128 v[180:183], v154 offset:3072
	s_add_u32 s24, s22, 0xfff80080
	s_addc_u32 s25, s23, -1
	s_cmp_eq_u32 s44, 28
	s_cselect_b32 s27, s15, s25
	s_cselect_b32 s26, s40, s24
	s_cselect_b32 s25, s13, s43
	s_cselect_b32 s24, s41, s42
	v_lshl_add_u64 v[216:217], s[22:23], 0, v[138:139]
	s_add_i32 m0, s21, 0xc000
	ds_read_b128 v[184:187], v155
	ds_read_b128 v[188:191], v155 offset:1024
	ds_read_b128 v[192:195], v155 offset:2048
	ds_read_b128 v[196:199], v155 offset:3072
	ds_read_b128 v[200:203], v155 offset:4096
	ds_read_b128 v[204:207], v155 offset:5120
	ds_read_b128 v[208:211], v155 offset:6144
	ds_read_b128 v[212:215], v155 offset:7168
	global_load_lds_dwordx4 v[216:217], off
	v_lshl_add_u64 v[216:217], s[22:23], 0, v[140:141]
	s_add_i32 m0, s21, 0xe000
	s_nop 0
	global_load_lds_dwordx4 v[216:217], off
	s_waitcnt vmcnt(8)
	s_waitcnt lgkmcnt(0)
	s_barrier
	s_setprio 1
	s_waitcnt lgkmcnt(0)
	v_mfma_f32_16x16x32_bf16 v[126:129], v[146:149], v[184:187], v[126:129]
	v_mfma_f32_16x16x32_bf16 v[122:125], v[160:163], v[184:187], v[122:125]
	v_mfma_f32_16x16x32_bf16 v[110:113], v[146:149], v[192:195], v[110:113]
	v_mfma_f32_16x16x32_bf16 v[106:109], v[160:163], v[192:195], v[106:109]
	v_mfma_f32_16x16x32_bf16 v[94:97], v[146:149], v[200:203], v[94:97]
	v_mfma_f32_16x16x32_bf16 v[90:93], v[160:163], v[200:203], v[90:93]
	v_mfma_f32_16x16x32_bf16 v[78:81], v[146:149], v[208:211], v[78:81]
	v_mfma_f32_16x16x32_bf16 v[74:77], v[160:163], v[208:211], v[74:77]
	v_mfma_f32_16x16x32_bf16 v[126:129], v[156:159], v[188:191], v[126:129]
	v_mfma_f32_16x16x32_bf16 v[122:125], v[164:167], v[188:191], v[122:125]
	v_mfma_f32_16x16x32_bf16 v[110:113], v[156:159], v[196:199], v[110:113]
	v_mfma_f32_16x16x32_bf16 v[106:109], v[164:167], v[196:199], v[106:109]
	v_mfma_f32_16x16x32_bf16 v[94:97], v[156:159], v[204:207], v[94:97]
	v_mfma_f32_16x16x32_bf16 v[90:93], v[164:167], v[204:207], v[90:93]
	v_mfma_f32_16x16x32_bf16 v[78:81], v[156:159], v[212:215], v[78:81]
	v_mfma_f32_16x16x32_bf16 v[74:77], v[164:167], v[212:215], v[74:77]
	v_mfma_f32_16x16x32_bf16 v[118:121], v[168:171], v[184:187], v[118:121]
	v_mfma_f32_16x16x32_bf16 v[114:117], v[176:179], v[184:187], v[114:117]
	v_mfma_f32_16x16x32_bf16 v[102:105], v[168:171], v[192:195], v[102:105]
	v_mfma_f32_16x16x32_bf16 v[98:101], v[176:179], v[192:195], v[98:101]
	v_mfma_f32_16x16x32_bf16 v[86:89], v[168:171], v[200:203], v[86:89]
	v_mfma_f32_16x16x32_bf16 v[82:85], v[176:179], v[200:203], v[82:85]
	v_mfma_f32_16x16x32_bf16 v[70:73], v[168:171], v[208:211], v[70:73]
	v_mfma_f32_16x16x32_bf16 v[66:69], v[176:179], v[208:211], v[66:69]
	v_mfma_f32_16x16x32_bf16 v[118:121], v[172:175], v[188:191], v[118:121]
	v_mfma_f32_16x16x32_bf16 v[114:117], v[180:183], v[188:191], v[114:117]
	v_mfma_f32_16x16x32_bf16 v[102:105], v[172:175], v[196:199], v[102:105]
	v_mfma_f32_16x16x32_bf16 v[98:101], v[180:183], v[196:199], v[98:101]
	v_mfma_f32_16x16x32_bf16 v[86:89], v[172:175], v[204:207], v[86:89]
	v_mfma_f32_16x16x32_bf16 v[82:85], v[180:183], v[204:207], v[82:85]
	v_mfma_f32_16x16x32_bf16 v[70:73], v[172:175], v[212:215], v[70:73]
	v_mfma_f32_16x16x32_bf16 v[66:69], v[180:183], v[212:215], v[66:69]
	s_setprio 0
	s_barrier
	s_add_i32 s45, s36, s2
	v_lshl_add_u64 v[216:217], s[24:25], 0, v[134:135]
	s_mov_b32 m0, s45
	ds_read_b128 v[184:187], v155 offset:16384
	ds_read_b128 v[188:191], v155 offset:17408
	ds_read_b128 v[192:195], v155 offset:18432
	ds_read_b128 v[196:199], v155 offset:19456
	ds_read_b128 v[200:203], v155 offset:20480
	ds_read_b128 v[204:207], v155 offset:21504
	ds_read_b128 v[208:211], v155 offset:22528
	ds_read_b128 v[212:215], v155 offset:23552
	global_load_lds_dwordx4 v[216:217], off
	s_add_i32 m0, s45, 0x2000
	s_add_u32 s46, s24, 0x80000
	v_lshl_add_u64 v[218:219], s[24:25], 0, v[130:131]
	s_addc_u32 s47, s25, 0
	s_add_i32 s45, s37, s2
	global_load_lds_dwordx4 v[218:219], off
	v_lshl_add_u64 v[220:221], s[46:47], 0, v[134:135]
	s_mov_b32 m0, s45
	v_lshl_add_u64 v[222:223], s[26:27], 0, v[132:133]
	global_load_lds_dwordx4 v[220:221], off
	v_lshl_add_u64 v[220:221], s[46:47], 0, v[130:131]
	s_add_i32 m0, s45, 0x2000
	s_nop 0
	global_load_lds_dwordx4 v[220:221], off
	v_lshl_add_u64 v[220:221], s[26:27], 0, v[136:137]
	s_mov_b32 m0, s21
	s_nop 0
	global_load_lds_dwordx4 v[220:221], off
	s_mov_b32 m0, s28
	s_nop 0
	global_load_lds_dwordx4 v[222:223], off
	s_waitcnt vmcnt(8)
	s_waitcnt lgkmcnt(0)
	s_barrier
; #define PG8_STAGE(bufoff, gbase, voff) do { _Pragma("unroll") for (int _i = 0; _i < 2; ++_i) \
;         __builtin_amdgcn_global_load_lds((const unsigned*)((const char*)(gbase) + (voff)[_i]), (PG8_LAS unsigned*)(lds + (bufoff) + ldsw + _i * 8192), 16, 0, 0); } while (0)
; #define PG8_LDA(dst, b, h) do { _Pragma("unroll") for (int m = 0; m < 4; ++m) _Pragma("unroll") for (int k = 0; k < 2; ++k) dst[m][k] = *(const PG8_LAS bf16x8*)(lds + PG8_SA(b, h) + aoff + m * 2048 + k * 1024); } while (0)
; #define PG8_LDB(dst, b, h) do { _Pragma("unroll") for (int n = 0; n < 2; ++n) _Pragma("unroll") for (int k = 0; k < 2; ++k) dst[n][k] = *(const PG8_LAS bf16x8*)(lds + PG8_SB(b, h) + boff + n * 2048 + k * 1024); } while (0)
; #define PG8_MMA(ai, bj, At, Bt) do { __builtin_amdgcn_s_setprio(1); _Pragma("unroll") for (int m = 0; m < 4; ++m) _Pragma("unroll") for (int n = 0; n < 2; ++n) _Pragma("unroll") for (int k = 0; k < 2; ++k) \
;         acc[ai][bj][m][n] = __builtin_amdgcn_mfma_f32_16x16x32_bf16(Bt[n][k], At[m][k], acc[ai][bj][m][n], 0, 0, 0); __builtin_amdgcn_s_setprio(0); } while (0)
; #define PG8_WAIT_V(n) asm volatile("s_waitcnt vmcnt(" #n ")" ::: "memory")
; #define PG8_WAIT_L(n) asm volatile("s_waitcnt lgkmcnt(" #n ")" ::: "memory")
; #define PG8_BAR __builtin_amdgcn_s_barrier()
; #define PG8_SCHED __builtin_amdgcn_sched_barrier(0)
; template <class Epi, class Sched, bool ALIGN_EPI = false, bool SP2 = false>
; __device__ __forceinline__ void gemm_phase(PG8_LAS unsigned char* lds, const Gemm g, const Sched& S, const Epi& E) {
;     ...
;             PG8_WAIT_V(8); PG8_WAIT_L(0); PG8_BAR; PG8_MMA(1, 0, At, B0); PG8_MMA(1, 1, At, B1); PG8_BAR; PG8_SCHED;
;             PG8_LDB(B0, 1, 0); PG8_LDB(B1, 1, 1); PG8_SCHED; PG8_LDA(At, 1, 0); PG8_STAGE(PG8_SA(0, 1), a2 + hstep, voffA);
;             PG8_WAIT_V(8); PG8_WAIT_L(0); PG8_BAR; PG8_MMA(0, 0, At, B0); PG8_MMA(0, 1, At, B1); PG8_BAR; PG8_SCHED;
	s_setprio 1
	s_waitcnt lgkmcnt(0)
	v_mfma_f32_16x16x32_bf16 v[62:65], v[146:149], v[184:187], v[62:65]
	v_mfma_f32_16x16x32_bf16 v[58:61], v[160:163], v[184:187], v[58:61]
	v_mfma_f32_16x16x32_bf16 v[46:49], v[146:149], v[192:195], v[46:49]
	v_mfma_f32_16x16x32_bf16 v[42:45], v[160:163], v[192:195], v[42:45]
	v_mfma_f32_16x16x32_bf16 v[30:33], v[146:149], v[200:203], v[30:33]
	v_mfma_f32_16x16x32_bf16 v[26:29], v[160:163], v[200:203], v[26:29]
	v_mfma_f32_16x16x32_bf16 v[14:17], v[146:149], v[208:211], v[14:17]
	v_mfma_f32_16x16x32_bf16 v[10:13], v[160:163], v[208:211], v[10:13]
	v_mfma_f32_16x16x32_bf16 v[62:65], v[156:159], v[188:191], v[62:65]
	v_mfma_f32_16x16x32_bf16 v[58:61], v[164:167], v[188:191], v[58:61]
	v_mfma_f32_16x16x32_bf16 v[46:49], v[156:159], v[196:199], v[46:49]
	v_mfma_f32_16x16x32_bf16 v[42:45], v[164:167], v[196:199], v[42:45]
	v_mfma_f32_16x16x32_bf16 v[30:33], v[156:159], v[204:207], v[30:33]
	v_mfma_f32_16x16x32_bf16 v[26:29], v[164:167], v[204:207], v[26:29]
	v_mfma_f32_16x16x32_bf16 v[14:17], v[156:159], v[212:215], v[14:17]
	v_mfma_f32_16x16x32_bf16 v[10:13], v[164:167], v[212:215], v[10:13]
	v_mfma_f32_16x16x32_bf16 v[54:57], v[168:171], v[184:187], v[54:57]
	v_mfma_f32_16x16x32_bf16 v[50:53], v[176:179], v[184:187], v[50:53]
	v_mfma_f32_16x16x32_bf16 v[38:41], v[168:171], v[192:195], v[38:41]
	v_mfma_f32_16x16x32_bf16 v[34:37], v[176:179], v[192:195], v[34:37]
	v_mfma_f32_16x16x32_bf16 v[22:25], v[168:171], v[200:203], v[22:25]
	v_mfma_f32_16x16x32_bf16 v[18:21], v[176:179], v[200:203], v[18:21]
	v_mfma_f32_16x16x32_bf16 v[6:9], v[168:171], v[208:211], v[6:9]
	v_mfma_f32_16x16x32_bf16 v[2:5], v[176:179], v[208:211], v[2:5]
	v_mfma_f32_16x16x32_bf16 v[54:57], v[172:175], v[188:191], v[54:57]
	v_mfma_f32_16x16x32_bf16 v[50:53], v[180:183], v[188:191], v[50:53]
	v_mfma_f32_16x16x32_bf16 v[38:41], v[172:175], v[196:199], v[38:41]
	v_mfma_f32_16x16x32_bf16 v[34:37], v[180:183], v[196:199], v[34:37]
	v_mfma_f32_16x16x32_bf16 v[22:25], v[172:175], v[204:207], v[22:25]
	v_mfma_f32_16x16x32_bf16 v[18:21], v[180:183], v[204:207], v[18:21]
	v_mfma_f32_16x16x32_bf16 v[6:9], v[172:175], v[212:215], v[6:9]
	v_mfma_f32_16x16x32_bf16 v[2:5], v[180:183], v[212:215], v[2:5]
	s_setprio 0
	s_barrier
	s_add_i32 s45, 0, 0x18000
	s_add_i32 s46, 0, 0x1c000
	v_add_u32_e32 v164, s45, v1
	v_add_u32_e32 v180, s46, v1
	ds_read_b128 v[146:149], v164
	ds_read_b128 v[156:159], v164 offset:1024
	ds_read_b128 v[160:163], v164 offset:2048
	ds_read_b128 v[164:167], v164 offset:3072
	ds_read_b128 v[168:171], v180
	ds_read_b128 v[172:175], v180 offset:1024
	ds_read_b128 v[176:179], v180 offset:2048
	ds_read_b128 v[180:183], v180 offset:3072
	s_add_u32 s26, s26, 0x80000
	s_addc_u32 s27, s27, 0
	s_mov_b32 m0, s29
	v_lshl_add_u64 v[224:225], s[26:27], 0, v[136:137]
	ds_read_b128 v[184:187], v155 offset:32768
	ds_read_b128 v[188:191], v155 offset:33792
	ds_read_b128 v[192:195], v155 offset:34816
	ds_read_b128 v[196:199], v155 offset:35840
	ds_read_b128 v[200:203], v155 offset:36864
	ds_read_b128 v[204:207], v155 offset:37888
	ds_read_b128 v[208:211], v155 offset:38912
	ds_read_b128 v[212:215], v155 offset:39936
	global_load_lds_dwordx4 v[224:225], off
	v_lshl_add_u64 v[224:225], s[26:27], 0, v[132:133]
	s_mov_b32 m0, s30
	s_nop 0
	global_load_lds_dwordx4 v[224:225], off
	s_waitcnt vmcnt(8)
	s_waitcnt lgkmcnt(0)
	s_barrier
	s_setprio 1
	s_waitcnt lgkmcnt(0)
	v_mfma_f32_16x16x32_bf16 v[126:129], v[146:149], v[184:187], v[126:129]
	v_mfma_f32_16x16x32_bf16 v[122:125], v[160:163], v[184:187], v[122:125]
	v_mfma_f32_16x16x32_bf16 v[110:113], v[146:149], v[192:195], v[110:113]
	v_mfma_f32_16x16x32_bf16 v[106:109], v[160:163], v[192:195], v[106:109]
	v_mfma_f32_16x16x32_bf16 v[94:97], v[146:149], v[200:203], v[94:97]
	v_mfma_f32_16x16x32_bf16 v[90:93], v[160:163], v[200:203], v[90:93]
	v_mfma_f32_16x16x32_bf16 v[78:81], v[146:149], v[208:211], v[78:81]
	v_mfma_f32_16x16x32_bf16 v[74:77], v[160:163], v[208:211], v[74:77]
	v_mfma_f32_16x16x32_bf16 v[126:129], v[156:159], v[188:191], v[126:129]
	v_mfma_f32_16x16x32_bf16 v[122:125], v[164:167], v[188:191], v[122:125]
	v_mfma_f32_16x16x32_bf16 v[110:113], v[156:159], v[196:199], v[110:113]
	v_mfma_f32_16x16x32_bf16 v[106:109], v[164:167], v[196:199], v[106:109]
	v_mfma_f32_16x16x32_bf16 v[94:97], v[156:159], v[204:207], v[94:97]
	v_mfma_f32_16x16x32_bf16 v[90:93], v[164:167], v[204:207], v[90:93]
	v_mfma_f32_16x16x32_bf16 v[78:81], v[156:159], v[212:215], v[78:81]
	v_mfma_f32_16x16x32_bf16 v[74:77], v[164:167], v[212:215], v[74:77]
	v_mfma_f32_16x16x32_bf16 v[118:121], v[168:171], v[184:187], v[118:121]
	v_mfma_f32_16x16x32_bf16 v[114:117], v[176:179], v[184:187], v[114:117]
	v_mfma_f32_16x16x32_bf16 v[102:105], v[168:171], v[192:195], v[102:105]
	v_mfma_f32_16x16x32_bf16 v[98:101], v[176:179], v[192:195], v[98:101]
	v_mfma_f32_16x16x32_bf16 v[86:89], v[168:171], v[200:203], v[86:89]
	v_mfma_f32_16x16x32_bf16 v[82:85], v[176:179], v[200:203], v[82:85]
	v_mfma_f32_16x16x32_bf16 v[70:73], v[168:171], v[208:211], v[70:73]
	v_mfma_f32_16x16x32_bf16 v[66:69], v[176:179], v[208:211], v[66:69]
	v_mfma_f32_16x16x32_bf16 v[118:121], v[172:175], v[188:191], v[118:121]
	v_mfma_f32_16x16x32_bf16 v[114:117], v[180:183], v[188:191], v[114:117]
	v_mfma_f32_16x16x32_bf16 v[102:105], v[172:175], v[196:199], v[102:105]
	v_mfma_f32_16x16x32_bf16 v[98:101], v[180:183], v[196:199], v[98:101]
	v_mfma_f32_16x16x32_bf16 v[86:89], v[172:175], v[204:207], v[86:89]
	v_mfma_f32_16x16x32_bf16 v[82:85], v[180:183], v[204:207], v[82:85]
	v_mfma_f32_16x16x32_bf16 v[70:73], v[172:175], v[212:215], v[70:73]
	v_mfma_f32_16x16x32_bf16 v[66:69], v[180:183], v[212:215], v[66:69]
	s_setprio 0
	s_barrier
; #define PG8_STAGE(bufoff, gbase, voff) do { _Pragma("unroll") for (int _i = 0; _i < 2; ++_i) \
;         __builtin_amdgcn_global_load_lds((const unsigned*)((const char*)(gbase) + (voff)[_i]), (PG8_LAS unsigned*)(lds + (bufoff) + ldsw + _i * 8192), 16, 0, 0); } while (0)
; #define PG8_LDA(dst, b, h) do { _Pragma("unroll") for (int m = 0; m < 4; ++m) _Pragma("unroll") for (int k = 0; k < 2; ++k) dst[m][k] = *(const PG8_LAS bf16x8*)(lds + PG8_SA(b, h) + aoff + m * 2048 + k * 1024); } while (0)
; #define PG8_MMA(ai, bj, At, Bt) do { __builtin_amdgcn_s_setprio(1); _Pragma("unroll") for (int m = 0; m < 4; ++m) _Pragma("unroll") for (int n = 0; n < 2; ++n) _Pragma("unroll") for (int k = 0; k < 2; ++k) \
;         acc[ai][bj][m][n] = __builtin_amdgcn_mfma_f32_16x16x32_bf16(Bt[n][k], At[m][k], acc[ai][bj][m][n], 0, 0, 0); __builtin_amdgcn_s_setprio(0); } while (0)
; #define PG8_WAIT_V(n) asm volatile("s_waitcnt vmcnt(" #n ")" ::: "memory")
; #define PG8_WAIT_L(n) asm volatile("s_waitcnt lgkmcnt(" #n ")" ::: "memory")
; #define PG8_BAR __builtin_amdgcn_s_barrier()
; #define PG8_SCHED __builtin_amdgcn_sched_barrier(0)
; template <class Epi, class Sched, bool ALIGN_EPI = false, bool SP2 = false>
; __device__ __forceinline__ void gemm_phase(PG8_LAS unsigned char* lds, const Gemm g, const Sched& S, const Epi& E) {
;     ...
;             PG8_LDA(At, 1, 1); PG8_STAGE(PG8_SB(1, 0), b3, voffB); PG8_STAGE(PG8_SB(1, 1), b3 + hstep, voffB); PG8_STAGE(PG8_SA(1, 0), a3, voffA);
;             PG8_WAIT_V(8); PG8_WAIT_L(0); PG8_BAR; PG8_MMA(1, 0, At, B0); PG8_MMA(1, 1, At, B1); PG8_BAR; PG8_SCHED;
	s_add_i32 s26, s45, s2
	v_lshl_add_u64 v[216:217], v[216:217], 0, s[8:9]
	s_mov_b32 m0, s26
	ds_read_b128 v[184:187], v155 offset:49152
	ds_read_b128 v[188:191], v155 offset:50176
	ds_read_b128 v[192:195], v155 offset:51200
	ds_read_b128 v[196:199], v155 offset:52224
	ds_read_b128 v[200:203], v155 offset:53248
	ds_read_b128 v[204:207], v155 offset:54272
	ds_read_b128 v[208:211], v155 offset:55296
	ds_read_b128 v[212:215], v155 offset:56320
	global_load_lds_dwordx4 v[216:217], off
	s_add_i32 m0, s26, 0x2000
	s_add_u32 s24, s24, 0x80080
	v_lshl_add_u64 v[216:217], v[218:219], 0, s[8:9]
	s_addc_u32 s25, s25, 0
	s_add_i32 s26, s46, s2
	global_load_lds_dwordx4 v[216:217], off
	v_lshl_add_u64 v[216:217], s[24:25], 0, v[134:135]
	s_mov_b32 m0, s26
	s_nop 0
	global_load_lds_dwordx4 v[216:217], off
	v_lshl_add_u64 v[216:217], s[24:25], 0, v[130:131]
	s_add_i32 m0, s26, 0x2000
	s_nop 0
	global_load_lds_dwordx4 v[216:217], off
	v_lshl_add_u64 v[216:217], v[220:221], 0, s[8:9]
	s_mov_b32 m0, s34
	s_nop 0
	global_load_lds_dwordx4 v[216:217], off
	v_lshl_add_u64 v[216:217], v[222:223], 0, s[8:9]
	s_mov_b32 m0, s35
	s_nop 0
	global_load_lds_dwordx4 v[216:217], off
	s_waitcnt vmcnt(8)
	s_waitcnt lgkmcnt(0)
	s_barrier
	s_setprio 1
	s_waitcnt lgkmcnt(0)
	v_mfma_f32_16x16x32_bf16 v[62:65], v[146:149], v[184:187], v[62:65]
	v_mfma_f32_16x16x32_bf16 v[58:61], v[160:163], v[184:187], v[58:61]
	v_mfma_f32_16x16x32_bf16 v[46:49], v[146:149], v[192:195], v[46:49]
	v_mfma_f32_16x16x32_bf16 v[42:45], v[160:163], v[192:195], v[42:45]
	v_mfma_f32_16x16x32_bf16 v[30:33], v[146:149], v[200:203], v[30:33]
	v_mfma_f32_16x16x32_bf16 v[26:29], v[160:163], v[200:203], v[26:29]
	v_mfma_f32_16x16x32_bf16 v[14:17], v[146:149], v[208:211], v[14:17]
	v_mfma_f32_16x16x32_bf16 v[10:13], v[160:163], v[208:211], v[10:13]
	v_mfma_f32_16x16x32_bf16 v[62:65], v[156:159], v[188:191], v[62:65]
	v_mfma_f32_16x16x32_bf16 v[58:61], v[164:167], v[188:191], v[58:61]
	v_mfma_f32_16x16x32_bf16 v[46:49], v[156:159], v[196:199], v[46:49]
	v_mfma_f32_16x16x32_bf16 v[42:45], v[164:167], v[196:199], v[42:45]
	v_mfma_f32_16x16x32_bf16 v[30:33], v[156:159], v[204:207], v[30:33]
	v_mfma_f32_16x16x32_bf16 v[26:29], v[164:167], v[204:207], v[26:29]
	v_mfma_f32_16x16x32_bf16 v[14:17], v[156:159], v[212:215], v[14:17]
	v_mfma_f32_16x16x32_bf16 v[10:13], v[164:167], v[212:215], v[10:13]
	v_mfma_f32_16x16x32_bf16 v[54:57], v[168:171], v[184:187], v[54:57]
	v_mfma_f32_16x16x32_bf16 v[50:53], v[176:179], v[184:187], v[50:53]
	v_mfma_f32_16x16x32_bf16 v[38:41], v[168:171], v[192:195], v[38:41]
	v_mfma_f32_16x16x32_bf16 v[34:37], v[176:179], v[192:195], v[34:37]
	v_mfma_f32_16x16x32_bf16 v[22:25], v[168:171], v[200:203], v[22:25]
	v_mfma_f32_16x16x32_bf16 v[18:21], v[176:179], v[200:203], v[18:21]
	v_mfma_f32_16x16x32_bf16 v[6:9], v[168:171], v[208:211], v[6:9]
	v_mfma_f32_16x16x32_bf16 v[2:5], v[176:179], v[208:211], v[2:5]
	v_mfma_f32_16x16x32_bf16 v[54:57], v[172:175], v[188:191], v[54:57]
	v_mfma_f32_16x16x32_bf16 v[50:53], v[180:183], v[188:191], v[50:53]
	v_mfma_f32_16x16x32_bf16 v[38:41], v[172:175], v[196:199], v[38:41]
	v_mfma_f32_16x16x32_bf16 v[34:37], v[180:183], v[196:199], v[34:37]
	v_mfma_f32_16x16x32_bf16 v[22:25], v[172:175], v[204:207], v[22:25]
	v_mfma_f32_16x16x32_bf16 v[18:21], v[180:183], v[204:207], v[18:21]
	v_mfma_f32_16x16x32_bf16 v[6:9], v[172:175], v[212:215], v[6:9]
	v_mfma_f32_16x16x32_bf16 v[2:5], v[180:183], v[212:215], v[2:5]
	s_setprio 0
	s_barrier
	s_add_i32 s44, s44, 2
	s_add_u32 s22, s22, 0x100
	s_addc_u32 s23, s23, 0
	s_add_u32 s42, s42, 0x100
	s_addc_u32 s43, s43, 0
	s_cmp_gt_u32 s44, 29
	s_cbranch_scc0 .LBB0_2774
	s_and_b64 vcc, exec, s[10:11]
	s_cbranch_vccz .LBB0_2777
	s_barrier

; #define PG8_STAGE(bufoff, gbase, voff) do { _Pragma("unroll") for (int _i = 0; _i < 2; ++_i) \
;         __builtin_amdgcn_global_load_lds((const unsigned*)((const char*)(gbase) + (voff)[_i]), (PG8_LAS unsigned*)(lds + (bufoff) + ldsw + _i * 8192), 16, 0, 0); } while (0)
; #define PG8_LDA(dst, b, h) do { _Pragma("unroll") for (int m = 0; m < 4; ++m) _Pragma("unroll") for (int k = 0; k < 2; ++k) dst[m][k] = *(const PG8_LAS bf16x8*)(lds + PG8_SA(b, h) + aoff + m * 2048 + k * 1024); } while (0)
; #define PG8_LDB(dst, b, h) do { _Pragma("unroll") for (int n = 0; n < 2; ++n) _Pragma("unroll") for (int k = 0; k < 2; ++k) dst[n][k] = *(const PG8_LAS bf16x8*)(lds + PG8_SB(b, h) + boff + n * 2048 + k * 1024); } while (0)
; #define PG8_MMA(ai, bj, At, Bt) do { __builtin_amdgcn_s_setprio(1); _Pragma("unroll") for (int m = 0; m < 4; ++m) _Pragma("unroll") for (int n = 0; n < 2; ++n) _Pragma("unroll") for (int k = 0; k < 2; ++k) \
;         acc[ai][bj][m][n] = __builtin_amdgcn_mfma_f32_16x16x32_bf16(Bt[n][k], At[m][k], acc[ai][bj][m][n], 0, 0, 0); __builtin_amdgcn_s_setprio(0); } while (0)
; #define PG8_WAIT_V(n) asm volatile("s_waitcnt vmcnt(" #n ")" ::: "memory")
; #define PG8_WAIT_L(n) asm volatile("s_waitcnt lgkmcnt(" #n ")" ::: "memory")
; #define PG8_BAR __builtin_amdgcn_s_barrier()
; #define PG8_SCHED __builtin_amdgcn_sched_barrier(0)
; template <class Epi, class Sched, bool ALIGN_EPI = false, bool SP2 = false>
; __device__ __forceinline__ void gemm_phase(PG8_LAS unsigned char* lds, const Gemm g, const Sched& S, const Epi& E) {
;     ...
;             PG8_LDB(B0, 0, 0); PG8_LDB(B1, 0, 1); PG8_SCHED; PG8_LDA(At, 0, 0); PG8_STAGE(PG8_SA(1, 1), a1 + hstep, voffA);
;             PG8_WAIT_V(8); PG8_WAIT_L(0); PG8_BAR; PG8_MMA(0, 0, At, B0); PG8_MMA(0, 1, At, B1); PG8_BAR; PG8_SCHED;
;             PG8_LDA(At, 0, 1); PG8_STAGE(PG8_SB(0, 0), b2, voffB); PG8_STAGE(PG8_SB(0, 1), b2 + hstep, voffB); PG8_STAGE(PG8_SA(0, 0), a2, voffA);
.LBB0_2871:
	ds_read_b128 v[152:155], v149
	ds_read_b128 v[156:159], v149 offset:1024
	ds_read_b128 v[160:163], v149 offset:2048
	ds_read_b128 v[164:167], v149 offset:3072
	ds_read_b128 v[168:171], v150
	ds_read_b128 v[172:175], v150 offset:1024
	ds_read_b128 v[176:179], v150 offset:2048
	ds_read_b128 v[180:183], v150 offset:3072
	s_add_u32 s24, s22, 0x100
	s_addc_u32 s25, s23, 0
	s_cmpk_eq_i32 s51, 0x54
	s_cselect_b32 s29, s7, s25
	s_cselect_b32 s28, s6, s24
	s_cselect_b32 s27, s21, s49
	s_cselect_b32 s26, s20, s48
	v_lshl_add_u64 v[216:217], s[22:23], 0, v[138:139]
	s_add_i32 m0, s3, 0xc000
	ds_read_b128 v[184:187], v151
	ds_read_b128 v[188:191], v151 offset:1024
	ds_read_b128 v[192:195], v151 offset:2048
	ds_read_b128 v[196:199], v151 offset:3072
	ds_read_b128 v[200:203], v151 offset:4096
	ds_read_b128 v[204:207], v151 offset:5120
	ds_read_b128 v[208:211], v151 offset:6144
	ds_read_b128 v[212:215], v151 offset:7168
	global_load_lds_dwordx4 v[216:217], off
	v_lshl_add_u64 v[216:217], s[22:23], 0, v[140:141]
	s_add_i32 m0, s3, 0xe000
	s_nop 0
	global_load_lds_dwordx4 v[216:217], off
	s_waitcnt vmcnt(8)
	s_waitcnt lgkmcnt(0)
	s_barrier
	s_setprio 1
	s_waitcnt lgkmcnt(0)
	v_mfma_f32_16x16x32_bf16 v[126:129], v[152:155], v[184:187], v[126:129]
	v_mfma_f32_16x16x32_bf16 v[122:125], v[160:163], v[184:187], v[122:125]
	v_mfma_f32_16x16x32_bf16 v[118:121], v[152:155], v[192:195], v[118:121]
	v_mfma_f32_16x16x32_bf16 v[110:113], v[160:163], v[192:195], v[110:113]
	v_mfma_f32_16x16x32_bf16 v[102:105], v[152:155], v[200:203], v[102:105]
	v_mfma_f32_16x16x32_bf16 v[94:97], v[160:163], v[200:203], v[94:97]
	v_mfma_f32_16x16x32_bf16 v[86:89], v[152:155], v[208:211], v[86:89]
	v_mfma_f32_16x16x32_bf16 v[78:81], v[160:163], v[208:211], v[78:81]
	v_mfma_f32_16x16x32_bf16 v[126:129], v[156:159], v[188:191], v[126:129]
	v_mfma_f32_16x16x32_bf16 v[122:125], v[164:167], v[188:191], v[122:125]
	v_mfma_f32_16x16x32_bf16 v[118:121], v[156:159], v[196:199], v[118:121]
	v_mfma_f32_16x16x32_bf16 v[110:113], v[164:167], v[196:199], v[110:113]
	v_mfma_f32_16x16x32_bf16 v[102:105], v[156:159], v[204:207], v[102:105]
	v_mfma_f32_16x16x32_bf16 v[94:97], v[164:167], v[204:207], v[94:97]
	v_mfma_f32_16x16x32_bf16 v[86:89], v[156:159], v[212:215], v[86:89]
	v_mfma_f32_16x16x32_bf16 v[78:81], v[164:167], v[212:215], v[78:81]
	v_mfma_f32_16x16x32_bf16 v[114:117], v[168:171], v[184:187], v[114:117]
	v_mfma_f32_16x16x32_bf16 v[106:109], v[176:179], v[184:187], v[106:109]
	v_mfma_f32_16x16x32_bf16 v[98:101], v[168:171], v[192:195], v[98:101]
	v_mfma_f32_16x16x32_bf16 v[90:93], v[176:179], v[192:195], v[90:93]
	v_mfma_f32_16x16x32_bf16 v[82:85], v[168:171], v[200:203], v[82:85]
	v_mfma_f32_16x16x32_bf16 v[74:77], v[176:179], v[200:203], v[74:77]
	v_mfma_f32_16x16x32_bf16 v[70:73], v[168:171], v[208:211], v[70:73]
	v_mfma_f32_16x16x32_bf16 v[66:69], v[176:179], v[208:211], v[66:69]
	v_mfma_f32_16x16x32_bf16 v[114:117], v[172:175], v[188:191], v[114:117]
	v_mfma_f32_16x16x32_bf16 v[106:109], v[180:183], v[188:191], v[106:109]
	v_mfma_f32_16x16x32_bf16 v[98:101], v[172:175], v[196:199], v[98:101]
	v_mfma_f32_16x16x32_bf16 v[90:93], v[180:183], v[196:199], v[90:93]
	v_mfma_f32_16x16x32_bf16 v[82:85], v[172:175], v[204:207], v[82:85]
	v_mfma_f32_16x16x32_bf16 v[74:77], v[180:183], v[204:207], v[74:77]
	v_mfma_f32_16x16x32_bf16 v[70:73], v[172:175], v[212:215], v[70:73]
	v_mfma_f32_16x16x32_bf16 v[66:69], v[180:183], v[212:215], v[66:69]
	s_setprio 0
	s_barrier
	s_add_i32 s22, s38, s2
	v_lshl_add_u64 v[216:217], s[26:27], 0, v[132:133]
	s_mov_b32 m0, s22
	ds_read_b128 v[184:187], v151 offset:16384
	ds_read_b128 v[188:191], v151 offset:17408
	ds_read_b128 v[192:195], v151 offset:18432
	ds_read_b128 v[196:199], v151 offset:19456
	ds_read_b128 v[200:203], v151 offset:20480
	ds_read_b128 v[204:207], v151 offset:21504
	ds_read_b128 v[208:211], v151 offset:22528
	ds_read_b128 v[212:215], v151 offset:23552
	global_load_lds_dwordx4 v[216:217], off
	s_add_i32 m0, s22, 0x2000
	s_add_u32 s22, s26, 0x160000
	v_lshl_add_u64 v[218:219], s[26:27], 0, v[136:137]
	s_addc_u32 s23, s27, 0
	s_add_i32 s52, s39, s2
	global_load_lds_dwordx4 v[218:219], off
	v_lshl_add_u64 v[220:221], s[22:23], 0, v[132:133]
	s_mov_b32 m0, s52
	v_lshl_add_u64 v[222:223], s[28:29], 0, v[134:135]
	global_load_lds_dwordx4 v[220:221], off
	v_lshl_add_u64 v[220:221], s[22:23], 0, v[136:137]
	s_add_i32 m0, s52, 0x2000
	s_nop 0
	global_load_lds_dwordx4 v[220:221], off
	v_lshl_add_u64 v[220:221], s[28:29], 0, v[130:131]
	s_mov_b32 m0, s3
	s_nop 0
	global_load_lds_dwordx4 v[220:221], off
	s_mov_b32 m0, s30
	s_nop 0
	global_load_lds_dwordx4 v[222:223], off
	s_waitcnt vmcnt(8)
	s_waitcnt lgkmcnt(0)
	s_barrier
; #define PG8_STAGE(bufoff, gbase, voff) do { _Pragma("unroll") for (int _i = 0; _i < 2; ++_i) \
;         __builtin_amdgcn_global_load_lds((const unsigned*)((const char*)(gbase) + (voff)[_i]), (PG8_LAS unsigned*)(lds + (bufoff) + ldsw + _i * 8192), 16, 0, 0); } while (0)
; #define PG8_LDA(dst, b, h) do { _Pragma("unroll") for (int m = 0; m < 4; ++m) _Pragma("unroll") for (int k = 0; k < 2; ++k) dst[m][k] = *(const PG8_LAS bf16x8*)(lds + PG8_SA(b, h) + aoff + m * 2048 + k * 1024); } while (0)
; #define PG8_LDB(dst, b, h) do { _Pragma("unroll") for (int n = 0; n < 2; ++n) _Pragma("unroll") for (int k = 0; k < 2; ++k) dst[n][k] = *(const PG8_LAS bf16x8*)(lds + PG8_SB(b, h) + boff + n * 2048 + k * 1024); } while (0)
; #define PG8_MMA(ai, bj, At, Bt) do { __builtin_amdgcn_s_setprio(1); _Pragma("unroll") for (int m = 0; m < 4; ++m) _Pragma("unroll") for (int n = 0; n < 2; ++n) _Pragma("unroll") for (int k = 0; k < 2; ++k) \
;         acc[ai][bj][m][n] = __builtin_amdgcn_mfma_f32_16x16x32_bf16(Bt[n][k], At[m][k], acc[ai][bj][m][n], 0, 0, 0); __builtin_amdgcn_s_setprio(0); } while (0)
; #define PG8_WAIT_V(n) asm volatile("s_waitcnt vmcnt(" #n ")" ::: "memory")
; #define PG8_WAIT_L(n) asm volatile("s_waitcnt lgkmcnt(" #n ")" ::: "memory")
; #define PG8_BAR __builtin_amdgcn_s_barrier()
; #define PG8_SCHED __builtin_amdgcn_sched_barrier(0)
; template <class Epi, class Sched, bool ALIGN_EPI = false, bool SP2 = false>
; __device__ __forceinline__ void gemm_phase(PG8_LAS unsigned char* lds, const Gemm g, const Sched& S, const Epi& E) {
;     ...
;             PG8_WAIT_V(8); PG8_WAIT_L(0); PG8_BAR; PG8_MMA(1, 0, At, B0); PG8_MMA(1, 1, At, B1); PG8_BAR; PG8_SCHED;
;             PG8_LDB(B0, 1, 0); PG8_LDB(B1, 1, 1); PG8_SCHED; PG8_LDA(At, 1, 0); PG8_STAGE(PG8_SA(0, 1), a2 + hstep, voffA);
;             PG8_WAIT_V(8); PG8_WAIT_L(0); PG8_BAR; PG8_MMA(0, 0, At, B0); PG8_MMA(0, 1, At, B1); PG8_BAR; PG8_SCHED;
	s_setprio 1
	s_waitcnt lgkmcnt(0)
	v_mfma_f32_16x16x32_bf16 v[62:65], v[152:155], v[184:187], v[62:65]
	v_mfma_f32_16x16x32_bf16 v[58:61], v[160:163], v[184:187], v[58:61]
	v_mfma_f32_16x16x32_bf16 v[54:57], v[152:155], v[192:195], v[54:57]
	v_mfma_f32_16x16x32_bf16 v[50:53], v[160:163], v[192:195], v[50:53]
	v_mfma_f32_16x16x32_bf16 v[38:41], v[152:155], v[200:203], v[38:41]
	v_mfma_f32_16x16x32_bf16 v[34:37], v[160:163], v[200:203], v[34:37]
	v_mfma_f32_16x16x32_bf16 v[22:25], v[152:155], v[208:211], v[22:25]
	v_mfma_f32_16x16x32_bf16 v[18:21], v[160:163], v[208:211], v[18:21]
	v_mfma_f32_16x16x32_bf16 v[62:65], v[156:159], v[188:191], v[62:65]
	v_mfma_f32_16x16x32_bf16 v[58:61], v[164:167], v[188:191], v[58:61]
	v_mfma_f32_16x16x32_bf16 v[54:57], v[156:159], v[196:199], v[54:57]
	v_mfma_f32_16x16x32_bf16 v[50:53], v[164:167], v[196:199], v[50:53]
	v_mfma_f32_16x16x32_bf16 v[38:41], v[156:159], v[204:207], v[38:41]
	v_mfma_f32_16x16x32_bf16 v[34:37], v[164:167], v[204:207], v[34:37]
	v_mfma_f32_16x16x32_bf16 v[22:25], v[156:159], v[212:215], v[22:25]
	v_mfma_f32_16x16x32_bf16 v[18:21], v[164:167], v[212:215], v[18:21]
	v_mfma_f32_16x16x32_bf16 v[46:49], v[168:171], v[184:187], v[46:49]
	v_mfma_f32_16x16x32_bf16 v[42:45], v[176:179], v[184:187], v[42:45]
	v_mfma_f32_16x16x32_bf16 v[30:33], v[168:171], v[192:195], v[30:33]
	v_mfma_f32_16x16x32_bf16 v[26:29], v[176:179], v[192:195], v[26:29]
	v_mfma_f32_16x16x32_bf16 v[14:17], v[168:171], v[200:203], v[14:17]
	v_mfma_f32_16x16x32_bf16 v[10:13], v[176:179], v[200:203], v[10:13]
	v_mfma_f32_16x16x32_bf16 v[6:9], v[168:171], v[208:211], v[6:9]
	v_mfma_f32_16x16x32_bf16 v[2:5], v[176:179], v[208:211], v[2:5]
	v_mfma_f32_16x16x32_bf16 v[46:49], v[172:175], v[188:191], v[46:49]
	v_mfma_f32_16x16x32_bf16 v[42:45], v[180:183], v[188:191], v[42:45]
	v_mfma_f32_16x16x32_bf16 v[30:33], v[172:175], v[196:199], v[30:33]
	v_mfma_f32_16x16x32_bf16 v[26:29], v[180:183], v[196:199], v[26:29]
	v_mfma_f32_16x16x32_bf16 v[14:17], v[172:175], v[204:207], v[14:17]
	v_mfma_f32_16x16x32_bf16 v[10:13], v[180:183], v[204:207], v[10:13]
	v_mfma_f32_16x16x32_bf16 v[6:9], v[172:175], v[212:215], v[6:9]
	v_mfma_f32_16x16x32_bf16 v[2:5], v[180:183], v[212:215], v[2:5]
	s_setprio 0
	s_barrier
	s_add_i32 s52, 0, 0x18000
	s_add_i32 s53, 0, 0x1c000
	v_add_u32_e32 v164, s52, v1
	v_add_u32_e32 v180, s53, v1
	ds_read_b128 v[152:155], v164
	ds_read_b128 v[156:159], v164 offset:1024
	ds_read_b128 v[160:163], v164 offset:2048
	ds_read_b128 v[164:167], v164 offset:3072
	ds_read_b128 v[168:171], v180
	ds_read_b128 v[172:175], v180 offset:1024
	ds_read_b128 v[176:179], v180 offset:2048
	ds_read_b128 v[180:183], v180 offset:3072
	s_add_u32 s22, s28, 0x160000
	s_addc_u32 s23, s29, 0
	s_mov_b32 m0, s31
	v_lshl_add_u64 v[224:225], s[22:23], 0, v[130:131]
	ds_read_b128 v[184:187], v151 offset:32768
	ds_read_b128 v[188:191], v151 offset:33792
	ds_read_b128 v[192:195], v151 offset:34816
	ds_read_b128 v[196:199], v151 offset:35840
	ds_read_b128 v[200:203], v151 offset:36864
	ds_read_b128 v[204:207], v151 offset:37888
	ds_read_b128 v[208:211], v151 offset:38912
	ds_read_b128 v[212:215], v151 offset:39936
	global_load_lds_dwordx4 v[224:225], off
	v_lshl_add_u64 v[224:225], s[22:23], 0, v[134:135]
	s_mov_b32 m0, s34
	s_nop 0
	global_load_lds_dwordx4 v[224:225], off
	s_waitcnt vmcnt(8)
	s_waitcnt lgkmcnt(0)
	s_barrier
	s_setprio 1
	s_waitcnt lgkmcnt(0)
	v_mfma_f32_16x16x32_bf16 v[126:129], v[152:155], v[184:187], v[126:129]
	v_mfma_f32_16x16x32_bf16 v[122:125], v[160:163], v[184:187], v[122:125]
	v_mfma_f32_16x16x32_bf16 v[118:121], v[152:155], v[192:195], v[118:121]
	v_mfma_f32_16x16x32_bf16 v[110:113], v[160:163], v[192:195], v[110:113]
	v_mfma_f32_16x16x32_bf16 v[102:105], v[152:155], v[200:203], v[102:105]
	v_mfma_f32_16x16x32_bf16 v[94:97], v[160:163], v[200:203], v[94:97]
	v_mfma_f32_16x16x32_bf16 v[86:89], v[152:155], v[208:211], v[86:89]
	v_mfma_f32_16x16x32_bf16 v[78:81], v[160:163], v[208:211], v[78:81]
	v_mfma_f32_16x16x32_bf16 v[126:129], v[156:159], v[188:191], v[126:129]
	v_mfma_f32_16x16x32_bf16 v[122:125], v[164:167], v[188:191], v[122:125]
	v_mfma_f32_16x16x32_bf16 v[118:121], v[156:159], v[196:199], v[118:121]
	v_mfma_f32_16x16x32_bf16 v[110:113], v[164:167], v[196:199], v[110:113]
	v_mfma_f32_16x16x32_bf16 v[102:105], v[156:159], v[204:207], v[102:105]
	v_mfma_f32_16x16x32_bf16 v[94:97], v[164:167], v[204:207], v[94:97]
	v_mfma_f32_16x16x32_bf16 v[86:89], v[156:159], v[212:215], v[86:89]
	v_mfma_f32_16x16x32_bf16 v[78:81], v[164:167], v[212:215], v[78:81]
	v_mfma_f32_16x16x32_bf16 v[114:117], v[168:171], v[184:187], v[114:117]
	v_mfma_f32_16x16x32_bf16 v[106:109], v[176:179], v[184:187], v[106:109]
	v_mfma_f32_16x16x32_bf16 v[98:101], v[168:171], v[192:195], v[98:101]
	v_mfma_f32_16x16x32_bf16 v[90:93], v[176:179], v[192:195], v[90:93]
	v_mfma_f32_16x16x32_bf16 v[82:85], v[168:171], v[200:203], v[82:85]
	v_mfma_f32_16x16x32_bf16 v[74:77], v[176:179], v[200:203], v[74:77]
	v_mfma_f32_16x16x32_bf16 v[70:73], v[168:171], v[208:211], v[70:73]
	v_mfma_f32_16x16x32_bf16 v[66:69], v[176:179], v[208:211], v[66:69]
	v_mfma_f32_16x16x32_bf16 v[114:117], v[172:175], v[188:191], v[114:117]
	v_mfma_f32_16x16x32_bf16 v[106:109], v[180:183], v[188:191], v[106:109]
	v_mfma_f32_16x16x32_bf16 v[98:101], v[172:175], v[196:199], v[98:101]
	v_mfma_f32_16x16x32_bf16 v[90:93], v[180:183], v[196:199], v[90:93]
	v_mfma_f32_16x16x32_bf16 v[82:85], v[172:175], v[204:207], v[82:85]
	v_mfma_f32_16x16x32_bf16 v[74:77], v[180:183], v[204:207], v[74:77]
	v_mfma_f32_16x16x32_bf16 v[70:73], v[172:175], v[212:215], v[70:73]
	v_mfma_f32_16x16x32_bf16 v[66:69], v[180:183], v[212:215], v[66:69]
	s_setprio 0
	s_barrier
; #define PG8_STAGE(bufoff, gbase, voff) do { _Pragma("unroll") for (int _i = 0; _i < 2; ++_i) \
;         __builtin_amdgcn_global_load_lds((const unsigned*)((const char*)(gbase) + (voff)[_i]), (PG8_LAS unsigned*)(lds + (bufoff) + ldsw + _i * 8192), 16, 0, 0); } while (0)
; #define PG8_LDA(dst, b, h) do { _Pragma("unroll") for (int m = 0; m < 4; ++m) _Pragma("unroll") for (int k = 0; k < 2; ++k) dst[m][k] = *(const PG8_LAS bf16x8*)(lds + PG8_SA(b, h) + aoff + m * 2048 + k * 1024); } while (0)
; #define PG8_MMA(ai, bj, At, Bt) do { __builtin_amdgcn_s_setprio(1); _Pragma("unroll") for (int m = 0; m < 4; ++m) _Pragma("unroll") for (int n = 0; n < 2; ++n) _Pragma("unroll") for (int k = 0; k < 2; ++k) \
;         acc[ai][bj][m][n] = __builtin_amdgcn_mfma_f32_16x16x32_bf16(Bt[n][k], At[m][k], acc[ai][bj][m][n], 0, 0, 0); __builtin_amdgcn_s_setprio(0); } while (0)
; #define PG8_WAIT_V(n) asm volatile("s_waitcnt vmcnt(" #n ")" ::: "memory")
; #define PG8_WAIT_L(n) asm volatile("s_waitcnt lgkmcnt(" #n ")" ::: "memory")
; #define PG8_BAR __builtin_amdgcn_s_barrier()
; #define PG8_SCHED __builtin_amdgcn_sched_barrier(0)
; template <class Epi, class Sched, bool ALIGN_EPI = false, bool SP2 = false>
; __device__ __forceinline__ void gemm_phase(PG8_LAS unsigned char* lds, const Gemm g, const Sched& S, const Epi& E) {
;     ...
;             PG8_LDA(At, 1, 1); PG8_STAGE(PG8_SB(1, 0), b3, voffB); PG8_STAGE(PG8_SB(1, 1), b3 + hstep, voffB); PG8_STAGE(PG8_SA(1, 0), a3, voffA);
;             PG8_WAIT_V(8); PG8_WAIT_L(0); PG8_BAR; PG8_MMA(1, 0, At, B0); PG8_MMA(1, 1, At, B1); PG8_BAR; PG8_SCHED;
	s_add_i32 s22, s52, s2
	v_lshl_add_u64 v[216:217], v[216:217], 0, s[8:9]
	s_mov_b32 m0, s22
	ds_read_b128 v[184:187], v151 offset:49152
	ds_read_b128 v[188:191], v151 offset:50176
	ds_read_b128 v[192:195], v151 offset:51200
	ds_read_b128 v[196:199], v151 offset:52224
	ds_read_b128 v[200:203], v151 offset:53248
	ds_read_b128 v[204:207], v151 offset:54272
	ds_read_b128 v[208:211], v151 offset:55296
	ds_read_b128 v[212:215], v151 offset:56320
	global_load_lds_dwordx4 v[216:217], off
	s_add_i32 m0, s22, 0x2000
	s_add_u32 s22, s26, 0x160080
	v_lshl_add_u64 v[216:217], v[218:219], 0, s[8:9]
	s_addc_u32 s23, s27, 0
	s_add_i32 s26, s53, s2
	global_load_lds_dwordx4 v[216:217], off
	v_lshl_add_u64 v[216:217], s[22:23], 0, v[132:133]
	s_mov_b32 m0, s26
	s_nop 0
	global_load_lds_dwordx4 v[216:217], off
	v_lshl_add_u64 v[216:217], s[22:23], 0, v[136:137]
	s_add_i32 m0, s26, 0x2000
	s_nop 0
	global_load_lds_dwordx4 v[216:217], off
	v_lshl_add_u64 v[216:217], v[220:221], 0, s[8:9]
	s_mov_b32 m0, s36
	s_nop 0
	global_load_lds_dwordx4 v[216:217], off
	v_lshl_add_u64 v[216:217], v[222:223], 0, s[8:9]
	s_mov_b32 m0, s37
	s_nop 0
	global_load_lds_dwordx4 v[216:217], off
	s_waitcnt vmcnt(8)
	s_waitcnt lgkmcnt(0)
	s_barrier
	s_setprio 1
	s_waitcnt lgkmcnt(0)
	v_mfma_f32_16x16x32_bf16 v[62:65], v[152:155], v[184:187], v[62:65]
	v_mfma_f32_16x16x32_bf16 v[58:61], v[160:163], v[184:187], v[58:61]
	v_mfma_f32_16x16x32_bf16 v[54:57], v[152:155], v[192:195], v[54:57]
	v_mfma_f32_16x16x32_bf16 v[50:53], v[160:163], v[192:195], v[50:53]
	v_mfma_f32_16x16x32_bf16 v[38:41], v[152:155], v[200:203], v[38:41]
	v_mfma_f32_16x16x32_bf16 v[34:37], v[160:163], v[200:203], v[34:37]
	v_mfma_f32_16x16x32_bf16 v[22:25], v[152:155], v[208:211], v[22:25]
	v_mfma_f32_16x16x32_bf16 v[18:21], v[160:163], v[208:211], v[18:21]
	v_mfma_f32_16x16x32_bf16 v[62:65], v[156:159], v[188:191], v[62:65]
	v_mfma_f32_16x16x32_bf16 v[58:61], v[164:167], v[188:191], v[58:61]
	v_mfma_f32_16x16x32_bf16 v[54:57], v[156:159], v[196:199], v[54:57]
	v_mfma_f32_16x16x32_bf16 v[50:53], v[164:167], v[196:199], v[50:53]
	v_mfma_f32_16x16x32_bf16 v[38:41], v[156:159], v[204:207], v[38:41]
	v_mfma_f32_16x16x32_bf16 v[34:37], v[164:167], v[204:207], v[34:37]
	v_mfma_f32_16x16x32_bf16 v[22:25], v[156:159], v[212:215], v[22:25]
	v_mfma_f32_16x16x32_bf16 v[18:21], v[164:167], v[212:215], v[18:21]
	v_mfma_f32_16x16x32_bf16 v[46:49], v[168:171], v[184:187], v[46:49]
	v_mfma_f32_16x16x32_bf16 v[42:45], v[176:179], v[184:187], v[42:45]
	v_mfma_f32_16x16x32_bf16 v[30:33], v[168:171], v[192:195], v[30:33]
	v_mfma_f32_16x16x32_bf16 v[26:29], v[176:179], v[192:195], v[26:29]
	v_mfma_f32_16x16x32_bf16 v[14:17], v[168:171], v[200:203], v[14:17]
	v_mfma_f32_16x16x32_bf16 v[10:13], v[176:179], v[200:203], v[10:13]
	v_mfma_f32_16x16x32_bf16 v[6:9], v[168:171], v[208:211], v[6:9]
	v_mfma_f32_16x16x32_bf16 v[2:5], v[176:179], v[208:211], v[2:5]
	v_mfma_f32_16x16x32_bf16 v[46:49], v[172:175], v[188:191], v[46:49]
	v_mfma_f32_16x16x32_bf16 v[42:45], v[180:183], v[188:191], v[42:45]
	v_mfma_f32_16x16x32_bf16 v[30:33], v[172:175], v[196:199], v[30:33]
	v_mfma_f32_16x16x32_bf16 v[26:29], v[180:183], v[196:199], v[26:29]
	v_mfma_f32_16x16x32_bf16 v[14:17], v[172:175], v[204:207], v[14:17]
	v_mfma_f32_16x16x32_bf16 v[10:13], v[180:183], v[204:207], v[10:13]
	v_mfma_f32_16x16x32_bf16 v[6:9], v[172:175], v[212:215], v[6:9]
	v_mfma_f32_16x16x32_bf16 v[2:5], v[180:183], v[212:215], v[2:5]
	s_setprio 0
	s_barrier
	s_add_i32 s51, s51, 2
	s_add_u32 s48, s48, 0x100
	s_addc_u32 s49, s49, 0
	s_cmpk_gt_u32 s51, 0x55
	s_mov_b64 s[22:23], s[24:25]
	s_cbranch_scc0 .LBB0_2871
	s_and_b64 vcc, exec, s[10:11]
	s_cbranch_vccz .LBB0_2874
	s_barrier
